# v37 + K-loop LDS-DMA loads use the saddr form (SGPR base + 32-bit lane offset): 16 v_lshl_add_u64 per iteration removed from the load segments; bit-identical
# speedup vs baseline: 1.0095x; 1.0095x over previous
; #define PG8_WAIT_V(n) asm volatile("s_waitcnt vmcnt(" #n ")" ::: "memory")
; #define PG8_WAIT_L(n) asm volatile("s_waitcnt lgkmcnt(" #n ")" ::: "memory")
; #define PG8_BAR __builtin_amdgcn_s_barrier()
; #define PG8_SCHED __builtin_amdgcn_sched_barrier(0)
; template <class Epi, class AddrA, class AddrB>
; __device__ __forceinline__ void gemm_phase(const Sched S, const int lda, const int ldb, const int K, const AddrA addrA,
;                                            const AddrB addrB, const Epi E) {
;     ...
;     const bool has_next = S.next(ui + 1, nxt);
;     const char* nA = has_next ? addrA(nxt) : cA;
;     const char* nB = has_next ? addrB(nxt) : cB;
;     for (int t = 0; t < nt; t += 2) {
;       const bool last = (t == nt - 2);
;       const char* a1 = cA + (size_t)(t + 1) * kstep;
;       const char* a2 = last ? nA : cA + (size_t)(t + 2) * kstep;
;       const char* b2 = last ? nB : cB + (size_t)(t + 2) * kstep;
;       const char* a3 = a2 + kstep;
;       const char* b3 = b2 + kstep;
;       PG8_LDB(B0, 0, 0); PG8_SCHED; PG8_LDA(At, 0, 0); PG8_STAGE(PG8_SA(1, 1), a1 + hstepA, voffA);
;       PG8_WAIT_L(8); PG8_BAR; PG8_WAIT_L(0); PG8_MMA(0, 0, At, B0); PG8_BAR; PG8_SCHED;
;       PG8_LDB(B1, 0, 1); PG8_STAGE(PG8_SB(0, 0), b2, voffB);
;       PG8_BAR; PG8_WAIT_L(0); PG8_MMA(0, 1, At, B1); PG8_BAR;
;       PG8_LDA(At, 0, 1); PG8_STAGE(PG8_SA(0, 0), a2, voffA);
;       PG8_BAR; PG8_WAIT_L(0); PG8_MMA(1, 0, At, B0); PG8_BAR; PG8_SCHED;
;       PG8_STAGE(PG8_SB(0, 1), b2 + hstepB, voffB);
;       PG8_WAIT_V(6); PG8_BAR; PG8_MMA(1, 1, At, B1); PG8_BAR;
;       PG8_LDB(B0, 1, 0); PG8_SCHED; PG8_LDA(At, 1, 0); PG8_STAGE(PG8_SA(0, 1), a2 + hstepA, voffA);
;       PG8_WAIT_L(8); PG8_BAR; PG8_WAIT_L(0); PG8_MMA(0, 0, At, B0); PG8_BAR; PG8_SCHED;
;       PG8_LDB(B1, 1, 1); PG8_STAGE(PG8_SB(1, 0), b3, voffB);
;       PG8_BAR; PG8_WAIT_L(0); PG8_MMA(0, 1, At, B1); PG8_BAR;
;       PG8_LDA(At, 1, 1); PG8_STAGE(PG8_SA(1, 0), a3, voffA);
;       PG8_BAR; PG8_WAIT_L(0); PG8_MMA(1, 0, At, B0); PG8_BAR; PG8_SCHED;
;       PG8_STAGE(PG8_SB(1, 1), b3 + hstepB, voffB);
;       PG8_WAIT_V(6); PG8_BAR; PG8_MMA(1, 1, At, B1); PG8_BAR;
.LBB0_108:
	s_ashr_i32 s1, s0, 31
	s_lshl_b64 s[6:7], s[0:1], 20
	s_add_u32 s6, s20, s6
	s_addc_u32 s7, s21, s7
	s_and_b64 s[8:9], s[16:17], exec
	s_cselect_b32 s1, s7, s15
	s_cselect_b32 s11, s6, s14
	s_ashr_i32 s3, s2, 31
	s_lshl_b64 s[8:9], s[2:3], 20
	s_add_u32 s8, s22, s8
	s_addc_u32 s9, s23, s9
	s_and_b64 s[16:17], s[16:17], exec
	s_cselect_b32 s3, s9, s13
	s_cselect_b32 s36, s8, s12
	s_add_u32 s37, s12, 0x100
	s_addc_u32 s38, s13, 0
	s_add_u32 s12, s14, 0x80080
	s_addc_u32 s13, s15, 0
	s_mov_b32 s39, -2
	s_add_i32 s40, 0, 0x10000
	v_add_u32_e32 v142, s40, v145
	ds_read_b128 v[148:151], v142
	ds_read_b128 v[152:155], v142 offset:1024
	ds_read_b128 v[156:159], v142 offset:2048
	ds_read_b128 v[160:163], v142 offset:3072
	s_add_i32 m0, s24, 0xc000
	ds_read_b128 v[168:171], v146
	ds_read_b128 v[172:175], v146 offset:1024
	ds_read_b128 v[176:179], v146 offset:2048
	ds_read_b128 v[180:183], v146 offset:3072
	ds_read_b128 v[184:187], v146 offset:4096
	ds_read_b128 v[188:191], v146 offset:5120
	ds_read_b128 v[192:195], v146 offset:6144
	ds_read_b128 v[212:215], v146 offset:7168
	global_load_lds_dwordx4 v140, s[12:13]
	s_add_i32 m0, s24, 0xe000
	s_nop 0
	global_load_lds_dwordx4 v138, s[12:13]
	s_waitcnt lgkmcnt(6)
	s_setprio 1
	s_barrier
	v_mfma_f32_16x16x32_bf16 v[128:131], v[148:151], v[168:171], 0
	v_mfma_f32_16x16x32_bf16 v[128:131], v[152:155], v[172:175], v[128:131]
	s_waitcnt lgkmcnt(0)
	v_mfma_f32_16x16x32_bf16 v[120:123], v[148:151], v[176:179], 0
	v_mfma_f32_16x16x32_bf16 v[120:123], v[152:155], v[180:183], v[120:123]
	v_mfma_f32_16x16x32_bf16 v[104:107], v[148:151], v[184:187], 0
	v_mfma_f32_16x16x32_bf16 v[104:107], v[152:155], v[188:191], v[104:107]
	v_mfma_f32_16x16x32_bf16 v[88:91], v[148:151], v[192:195], 0
	v_mfma_f32_16x16x32_bf16 v[88:91], v[152:155], v[212:215], v[88:91]
	v_mfma_f32_16x16x32_bf16 v[124:127], v[156:159], v[168:171], 0
	v_mfma_f32_16x16x32_bf16 v[124:127], v[160:163], v[172:175], v[124:127]
	v_mfma_f32_16x16x32_bf16 v[112:115], v[156:159], v[176:179], 0
	v_mfma_f32_16x16x32_bf16 v[112:115], v[160:163], v[180:183], v[112:115]
	v_mfma_f32_16x16x32_bf16 v[96:99], v[156:159], v[184:187], 0
	v_mfma_f32_16x16x32_bf16 v[96:99], v[160:163], v[188:191], v[96:99]
	v_mfma_f32_16x16x32_bf16 v[80:83], v[156:159], v[192:195], 0
	v_mfma_f32_16x16x32_bf16 v[80:83], v[160:163], v[212:215], v[80:83]
	s_barrier
	s_setprio 0
	s_add_u32 s14, s12, 0xfff80080
	s_addc_u32 s15, s13, -1
	s_cmp_eq_u32 s39, 28
	s_cselect_b32 s17, s1, s15
	s_cselect_b32 s16, s11, s14
	s_cselect_b32 s15, s3, s38
	s_cselect_b32 s14, s36, s37
	s_add_i32 s42, 0, 0x14000
	v_add_u32_e32 v142, s42, v145
	s_add_i32 s40, s40, s19
	ds_read_b128 v[216:219], v142
	ds_read_b128 v[220:223], v142 offset:1024
	ds_read_b128 v[224:227], v142 offset:2048
	ds_read_b128 v[228:231], v142 offset:3072
	s_add_u32 s98, s14, 0x80
	s_addc_u32 s99, s15, 0
	s_mov_b32 m0, s40
	s_nop 0
	global_load_lds_dwordx4 v134, s[14:15]
	s_add_i32 m0, s40, 0x2000
	s_nop 0
	global_load_lds_dwordx4 v0, s[14:15]
	s_mov_b32 m0, s24
	s_add_u32 s100, s16, 0x80
	s_addc_u32 s101, s17, 0
	s_waitcnt lgkmcnt(2)
	s_setprio 1
	s_barrier
	v_mfma_f32_16x16x32_bf16 v[116:119], v[216:219], v[168:171], 0
	v_mfma_f32_16x16x32_bf16 v[116:119], v[220:223], v[172:175], v[116:119]
	s_waitcnt lgkmcnt(0)
	v_mfma_f32_16x16x32_bf16 v[100:103], v[216:219], v[176:179], 0
	v_mfma_f32_16x16x32_bf16 v[100:103], v[220:223], v[180:183], v[100:103]
	v_mfma_f32_16x16x32_bf16 v[84:87], v[216:219], v[184:187], 0
	v_mfma_f32_16x16x32_bf16 v[84:87], v[220:223], v[188:191], v[84:87]
	v_mfma_f32_16x16x32_bf16 v[72:75], v[216:219], v[192:195], 0
	v_mfma_f32_16x16x32_bf16 v[72:75], v[220:223], v[212:215], v[72:75]
	v_mfma_f32_16x16x32_bf16 v[108:111], v[224:227], v[168:171], 0
	v_mfma_f32_16x16x32_bf16 v[108:111], v[228:231], v[172:175], v[108:111]
	v_mfma_f32_16x16x32_bf16 v[92:95], v[224:227], v[176:179], 0
	v_mfma_f32_16x16x32_bf16 v[92:95], v[228:231], v[180:183], v[92:95]
	v_mfma_f32_16x16x32_bf16 v[76:79], v[224:227], v[184:187], 0
	v_mfma_f32_16x16x32_bf16 v[76:79], v[228:231], v[188:191], v[76:79]
	v_mfma_f32_16x16x32_bf16 v[68:71], v[224:227], v[192:195], 0
	v_mfma_f32_16x16x32_bf16 v[68:71], v[228:231], v[212:215], v[68:71]
	s_barrier
	s_setprio 0
	ds_read_b128 v[168:171], v146 offset:16384
	ds_read_b128 v[172:175], v146 offset:17408
	ds_read_b128 v[176:179], v146 offset:18432
	ds_read_b128 v[180:183], v146 offset:19456
	ds_read_b128 v[184:187], v146 offset:20480
	ds_read_b128 v[188:191], v146 offset:21504
	ds_read_b128 v[192:195], v146 offset:22528
	ds_read_b128 v[212:215], v146 offset:23552
	global_load_lds_dwordx4 v136, s[16:17]
	s_mov_b32 m0, s25
	s_nop 0
	global_load_lds_dwordx4 v132, s[16:17]
	s_waitcnt lgkmcnt(6)
	s_setprio 1
	s_barrier
	v_mfma_f32_16x16x32_bf16 v[64:67], v[148:151], v[168:171], 0
	v_mfma_f32_16x16x32_bf16 v[64:67], v[152:155], v[172:175], v[64:67]
	s_waitcnt lgkmcnt(0)
	v_mfma_f32_16x16x32_bf16 v[56:59], v[148:151], v[176:179], 0
	v_mfma_f32_16x16x32_bf16 v[56:59], v[152:155], v[180:183], v[56:59]
	v_mfma_f32_16x16x32_bf16 v[40:43], v[148:151], v[184:187], 0
	v_mfma_f32_16x16x32_bf16 v[40:43], v[152:155], v[188:191], v[40:43]
	v_mfma_f32_16x16x32_bf16 v[24:27], v[148:151], v[192:195], 0
	v_mfma_f32_16x16x32_bf16 v[24:27], v[152:155], v[212:215], v[24:27]
	v_mfma_f32_16x16x32_bf16 v[60:63], v[156:159], v[168:171], 0
	v_mfma_f32_16x16x32_bf16 v[60:63], v[160:163], v[172:175], v[60:63]
	v_mfma_f32_16x16x32_bf16 v[48:51], v[156:159], v[176:179], 0
	v_mfma_f32_16x16x32_bf16 v[48:51], v[160:163], v[180:183], v[48:51]
	v_mfma_f32_16x16x32_bf16 v[32:35], v[156:159], v[184:187], 0
	v_mfma_f32_16x16x32_bf16 v[32:35], v[160:163], v[188:191], v[32:35]
	v_mfma_f32_16x16x32_bf16 v[16:19], v[156:159], v[192:195], 0
	v_mfma_f32_16x16x32_bf16 v[16:19], v[160:163], v[212:215], v[16:19]
	s_barrier
; #define PG8_WAIT_V(n) asm volatile("s_waitcnt vmcnt(" #n ")" ::: "memory")
; #define PG8_WAIT_L(n) asm volatile("s_waitcnt lgkmcnt(" #n ")" ::: "memory")
; #define PG8_BAR __builtin_amdgcn_s_barrier()
; #define PG8_SCHED __builtin_amdgcn_sched_barrier(0)
; template <class Epi, class AddrA, class AddrB>
; __device__ __forceinline__ void gemm_phase(const Sched S, const int lda, const int ldb, const int K, const AddrA addrA,
;                                            const AddrB addrB, const Epi E) {
;     ...
;       PG8_LDB(B0, 0, 0); PG8_SCHED; PG8_LDA(At, 0, 0); PG8_STAGE(PG8_SA(1, 1), a1 + hstepA, voffA);
;       PG8_WAIT_L(8); PG8_BAR; PG8_WAIT_L(0); PG8_MMA(0, 0, At, B0); PG8_BAR; PG8_SCHED;
;       PG8_LDB(B1, 0, 1); PG8_STAGE(PG8_SB(0, 0), b2, voffB);
;       PG8_BAR; PG8_WAIT_L(0); PG8_MMA(0, 1, At, B1); PG8_BAR;
;       PG8_LDA(At, 0, 1); PG8_STAGE(PG8_SA(0, 0), a2, voffA);
;       PG8_BAR; PG8_WAIT_L(0); PG8_MMA(1, 0, At, B0); PG8_BAR; PG8_SCHED;
;       PG8_STAGE(PG8_SB(0, 1), b2 + hstepB, voffB);
;       PG8_WAIT_V(6); PG8_BAR; PG8_MMA(1, 1, At, B1); PG8_BAR;
;       PG8_LDB(B0, 1, 0); PG8_SCHED; PG8_LDA(At, 1, 0); PG8_STAGE(PG8_SA(0, 1), a2 + hstepA, voffA);
;       PG8_WAIT_L(8); PG8_BAR; PG8_WAIT_L(0); PG8_MMA(0, 0, At, B0); PG8_BAR; PG8_SCHED;
;       PG8_LDB(B1, 1, 1); PG8_STAGE(PG8_SB(1, 0), b3, voffB);
;       PG8_BAR; PG8_WAIT_L(0); PG8_MMA(0, 1, At, B1); PG8_BAR;
;       PG8_LDA(At, 1, 1); PG8_STAGE(PG8_SA(1, 0), a3, voffA);
;       PG8_BAR; PG8_WAIT_L(0); PG8_MMA(1, 0, At, B0); PG8_BAR; PG8_SCHED;
;       PG8_STAGE(PG8_SB(1, 1), b3 + hstepB, voffB);
;       PG8_WAIT_V(6); PG8_BAR; PG8_MMA(1, 1, At, B1); PG8_BAR;
	s_setprio 0
	s_add_u32 s40, s14, 0x80000
	s_addc_u32 s41, s15, 0
	s_add_i32 s42, s42, s19
	s_mov_b32 m0, s42
	s_nop 0
	global_load_lds_dwordx4 v134, s[40:41]
	s_add_i32 m0, s42, 0x2000
	s_nop 0
	global_load_lds_dwordx4 v0, s[40:41]
	s_add_i32 s40, 0, 0x18000
	v_add_u32_e32 v147, s40, v145
	s_waitcnt vmcnt(6)
	s_setprio 1
	s_barrier
	v_mfma_f32_16x16x32_bf16 v[52:55], v[216:219], v[168:171], 0
	v_mfma_f32_16x16x32_bf16 v[52:55], v[220:223], v[172:175], v[52:55]
	v_mfma_f32_16x16x32_bf16 v[36:39], v[216:219], v[176:179], 0
	v_mfma_f32_16x16x32_bf16 v[36:39], v[220:223], v[180:183], v[36:39]
	v_mfma_f32_16x16x32_bf16 v[20:23], v[216:219], v[184:187], 0
	v_mfma_f32_16x16x32_bf16 v[20:23], v[220:223], v[188:191], v[20:23]
	v_mfma_f32_16x16x32_bf16 v[8:11], v[216:219], v[192:195], 0
	v_mfma_f32_16x16x32_bf16 v[8:11], v[220:223], v[212:215], v[8:11]
	v_mfma_f32_16x16x32_bf16 v[44:47], v[224:227], v[168:171], 0
	v_mfma_f32_16x16x32_bf16 v[44:47], v[228:231], v[172:175], v[44:47]
	v_mfma_f32_16x16x32_bf16 v[28:31], v[224:227], v[176:179], 0
	v_mfma_f32_16x16x32_bf16 v[28:31], v[228:231], v[180:183], v[28:31]
	v_mfma_f32_16x16x32_bf16 v[12:15], v[224:227], v[184:187], 0
	v_mfma_f32_16x16x32_bf16 v[12:15], v[228:231], v[188:191], v[12:15]
	v_mfma_f32_16x16x32_bf16 v[4:7], v[224:227], v[192:195], 0
	v_mfma_f32_16x16x32_bf16 v[4:7], v[228:231], v[212:215], v[4:7]
	s_barrier
	s_setprio 0
	ds_read_b128 v[148:151], v147
	ds_read_b128 v[152:155], v147 offset:1024
	ds_read_b128 v[156:159], v147 offset:2048
	ds_read_b128 v[160:163], v147 offset:3072
	s_add_u32 s16, s16, 0x80000
	s_addc_u32 s17, s17, 0
	s_mov_b32 m0, s26
	ds_read_b128 v[168:171], v146 offset:32768
	ds_read_b128 v[172:175], v146 offset:33792
	ds_read_b128 v[176:179], v146 offset:34816
	ds_read_b128 v[180:183], v146 offset:35840
	ds_read_b128 v[184:187], v146 offset:36864
	ds_read_b128 v[188:191], v146 offset:37888
	ds_read_b128 v[192:195], v146 offset:38912
	ds_read_b128 v[212:215], v146 offset:39936
	global_load_lds_dwordx4 v136, s[16:17]
	s_mov_b32 m0, s27
	s_nop 0
	global_load_lds_dwordx4 v132, s[16:17]
	s_waitcnt lgkmcnt(6)
	s_setprio 1
	s_barrier
	v_mfma_f32_16x16x32_bf16 v[128:131], v[148:151], v[168:171], v[128:131]
	v_mfma_f32_16x16x32_bf16 v[128:131], v[152:155], v[172:175], v[128:131]
	s_waitcnt lgkmcnt(0)
	v_mfma_f32_16x16x32_bf16 v[120:123], v[148:151], v[176:179], v[120:123]
	v_mfma_f32_16x16x32_bf16 v[120:123], v[152:155], v[180:183], v[120:123]
	v_mfma_f32_16x16x32_bf16 v[104:107], v[148:151], v[184:187], v[104:107]
	v_mfma_f32_16x16x32_bf16 v[104:107], v[152:155], v[188:191], v[104:107]
	v_mfma_f32_16x16x32_bf16 v[88:91], v[148:151], v[192:195], v[88:91]
	v_mfma_f32_16x16x32_bf16 v[88:91], v[152:155], v[212:215], v[88:91]
	v_mfma_f32_16x16x32_bf16 v[124:127], v[156:159], v[168:171], v[124:127]
	v_mfma_f32_16x16x32_bf16 v[124:127], v[160:163], v[172:175], v[124:127]
	v_mfma_f32_16x16x32_bf16 v[112:115], v[156:159], v[176:179], v[112:115]
	v_mfma_f32_16x16x32_bf16 v[112:115], v[160:163], v[180:183], v[112:115]
	v_mfma_f32_16x16x32_bf16 v[96:99], v[156:159], v[184:187], v[96:99]
	v_mfma_f32_16x16x32_bf16 v[96:99], v[160:163], v[188:191], v[96:99]
	v_mfma_f32_16x16x32_bf16 v[80:83], v[156:159], v[192:195], v[80:83]
	v_mfma_f32_16x16x32_bf16 v[80:83], v[160:163], v[212:215], v[80:83]
	s_barrier
	s_setprio 0
	s_add_i32 s16, 0, 0x1c000
	s_add_i32 s17, s40, s19
	v_add_u32_e32 v147, s16, v145
	s_mov_b32 m0, s17
	ds_read_b128 v[216:219], v147
	ds_read_b128 v[220:223], v147 offset:1024
	ds_read_b128 v[224:227], v147 offset:2048
	ds_read_b128 v[228:231], v147 offset:3072
	global_load_lds_dwordx4 v134, s[98:99]
	s_add_i32 m0, s17, 0x2000
	s_nop 0
	global_load_lds_dwordx4 v0, s[98:99]
	s_mov_b32 m0, s30
	s_waitcnt lgkmcnt(2)
	s_setprio 1
	s_barrier
	v_mfma_f32_16x16x32_bf16 v[116:119], v[216:219], v[168:171], v[116:119]
	v_mfma_f32_16x16x32_bf16 v[116:119], v[220:223], v[172:175], v[116:119]
	s_waitcnt lgkmcnt(0)
	v_mfma_f32_16x16x32_bf16 v[100:103], v[216:219], v[176:179], v[100:103]
	v_mfma_f32_16x16x32_bf16 v[100:103], v[220:223], v[180:183], v[100:103]
	v_mfma_f32_16x16x32_bf16 v[84:87], v[216:219], v[184:187], v[84:87]
	v_mfma_f32_16x16x32_bf16 v[84:87], v[220:223], v[188:191], v[84:87]
	v_mfma_f32_16x16x32_bf16 v[72:75], v[216:219], v[192:195], v[72:75]
	v_mfma_f32_16x16x32_bf16 v[72:75], v[220:223], v[212:215], v[72:75]
	v_mfma_f32_16x16x32_bf16 v[108:111], v[224:227], v[168:171], v[108:111]
	v_mfma_f32_16x16x32_bf16 v[108:111], v[228:231], v[172:175], v[108:111]
	v_mfma_f32_16x16x32_bf16 v[92:95], v[224:227], v[176:179], v[92:95]
	v_mfma_f32_16x16x32_bf16 v[92:95], v[228:231], v[180:183], v[92:95]
	v_mfma_f32_16x16x32_bf16 v[76:79], v[224:227], v[184:187], v[76:79]
	v_mfma_f32_16x16x32_bf16 v[76:79], v[228:231], v[188:191], v[76:79]
	v_mfma_f32_16x16x32_bf16 v[68:71], v[224:227], v[192:195], v[68:71]
	v_mfma_f32_16x16x32_bf16 v[68:71], v[228:231], v[212:215], v[68:71]
	s_barrier
	s_setprio 0
	ds_read_b128 v[168:171], v146 offset:49152
	ds_read_b128 v[172:175], v146 offset:50176
	ds_read_b128 v[176:179], v146 offset:51200
	ds_read_b128 v[180:183], v146 offset:52224
	ds_read_b128 v[184:187], v146 offset:53248
	ds_read_b128 v[188:191], v146 offset:54272
	ds_read_b128 v[192:195], v146 offset:55296
	ds_read_b128 v[212:215], v146 offset:56320
	global_load_lds_dwordx4 v136, s[100:101]
	s_mov_b32 m0, s31
	s_nop 0
	global_load_lds_dwordx4 v132, s[100:101]
	s_waitcnt lgkmcnt(6)
	s_setprio 1
	s_barrier
; #define PG8_WAIT_V(n) asm volatile("s_waitcnt vmcnt(" #n ")" ::: "memory")
; #define PG8_WAIT_L(n) asm volatile("s_waitcnt lgkmcnt(" #n ")" ::: "memory")
; #define PG8_BAR __builtin_amdgcn_s_barrier()
; #define PG8_SCHED __builtin_amdgcn_sched_barrier(0)
; template <class Epi, class AddrA, class AddrB>
; __device__ __forceinline__ void gemm_phase(const Sched S, const int lda, const int ldb, const int K, const AddrA addrA,
;                                            const AddrB addrB, const Epi E) {
;     ...
;     for (int t = 0; t < nt; t += 2) {
;       const bool last = (t == nt - 2);
;       const char* a1 = cA + (size_t)(t + 1) * kstep;
;       const char* a2 = last ? nA : cA + (size_t)(t + 2) * kstep;
;       const char* b2 = last ? nB : cB + (size_t)(t + 2) * kstep;
;       const char* a3 = a2 + kstep;
;       const char* b3 = b2 + kstep;
;       PG8_LDB(B0, 0, 0); PG8_SCHED; PG8_LDA(At, 0, 0); PG8_STAGE(PG8_SA(1, 1), a1 + hstepA, voffA);
;       PG8_WAIT_L(8); PG8_BAR; PG8_WAIT_L(0); PG8_MMA(0, 0, At, B0); PG8_BAR; PG8_SCHED;
;       PG8_LDB(B1, 0, 1); PG8_STAGE(PG8_SB(0, 0), b2, voffB);
;       PG8_BAR; PG8_WAIT_L(0); PG8_MMA(0, 1, At, B1); PG8_BAR;
;       PG8_LDA(At, 0, 1); PG8_STAGE(PG8_SA(0, 0), a2, voffA);
;       PG8_BAR; PG8_WAIT_L(0); PG8_MMA(1, 0, At, B0); PG8_BAR; PG8_SCHED;
;       PG8_STAGE(PG8_SB(0, 1), b2 + hstepB, voffB);
;       PG8_WAIT_V(6); PG8_BAR; PG8_MMA(1, 1, At, B1); PG8_BAR;
;       PG8_LDB(B0, 1, 0); PG8_SCHED; PG8_LDA(At, 1, 0); PG8_STAGE(PG8_SA(0, 1), a2 + hstepA, voffA);
;       PG8_WAIT_L(8); PG8_BAR; PG8_WAIT_L(0); PG8_MMA(0, 0, At, B0); PG8_BAR; PG8_SCHED;
;       PG8_LDB(B1, 1, 1); PG8_STAGE(PG8_SB(1, 0), b3, voffB);
;       PG8_BAR; PG8_WAIT_L(0); PG8_MMA(0, 1, At, B1); PG8_BAR;
;       PG8_LDA(At, 1, 1); PG8_STAGE(PG8_SA(1, 0), a3, voffA);
;       PG8_BAR; PG8_WAIT_L(0); PG8_MMA(1, 0, At, B0); PG8_BAR; PG8_SCHED;
;       PG8_STAGE(PG8_SB(1, 1), b3 + hstepB, voffB);
;       PG8_WAIT_V(6); PG8_BAR; PG8_MMA(1, 1, At, B1); PG8_BAR;
	v_mfma_f32_16x16x32_bf16 v[64:67], v[148:151], v[168:171], v[64:67]
	v_mfma_f32_16x16x32_bf16 v[64:67], v[152:155], v[172:175], v[64:67]
	s_waitcnt lgkmcnt(0)
	v_mfma_f32_16x16x32_bf16 v[56:59], v[148:151], v[176:179], v[56:59]
	v_mfma_f32_16x16x32_bf16 v[56:59], v[152:155], v[180:183], v[56:59]
	v_mfma_f32_16x16x32_bf16 v[40:43], v[148:151], v[184:187], v[40:43]
	v_mfma_f32_16x16x32_bf16 v[40:43], v[152:155], v[188:191], v[40:43]
	v_mfma_f32_16x16x32_bf16 v[24:27], v[148:151], v[192:195], v[24:27]
	v_mfma_f32_16x16x32_bf16 v[24:27], v[152:155], v[212:215], v[24:27]
	v_mfma_f32_16x16x32_bf16 v[60:63], v[156:159], v[168:171], v[60:63]
	v_mfma_f32_16x16x32_bf16 v[60:63], v[160:163], v[172:175], v[60:63]
	v_mfma_f32_16x16x32_bf16 v[48:51], v[156:159], v[176:179], v[48:51]
	v_mfma_f32_16x16x32_bf16 v[48:51], v[160:163], v[180:183], v[48:51]
	v_mfma_f32_16x16x32_bf16 v[32:35], v[156:159], v[184:187], v[32:35]
	v_mfma_f32_16x16x32_bf16 v[32:35], v[160:163], v[188:191], v[32:35]
	v_mfma_f32_16x16x32_bf16 v[16:19], v[156:159], v[192:195], v[16:19]
	v_mfma_f32_16x16x32_bf16 v[16:19], v[160:163], v[212:215], v[16:19]
	s_barrier
	s_setprio 0
	s_add_u32 s14, s14, 0x80080
	s_addc_u32 s15, s15, 0
	s_add_i32 s16, s16, s19
	s_mov_b32 m0, s16
	s_nop 0
	global_load_lds_dwordx4 v134, s[14:15]
	s_add_i32 m0, s16, 0x2000
	s_nop 0
	global_load_lds_dwordx4 v0, s[14:15]
	s_add_i32 s39, s39, 2
	s_add_u32 s37, s37, 0x100
	s_addc_u32 s38, s38, 0
	s_add_u32 s12, s12, 0x100
	s_addc_u32 s13, s13, 0
	s_waitcnt vmcnt(6)
	s_setprio 1
	s_barrier
	v_mfma_f32_16x16x32_bf16 v[52:55], v[216:219], v[168:171], v[52:55]
	v_mfma_f32_16x16x32_bf16 v[52:55], v[220:223], v[172:175], v[52:55]
	v_mfma_f32_16x16x32_bf16 v[36:39], v[216:219], v[176:179], v[36:39]
	v_mfma_f32_16x16x32_bf16 v[36:39], v[220:223], v[180:183], v[36:39]
	v_mfma_f32_16x16x32_bf16 v[20:23], v[216:219], v[184:187], v[20:23]
	v_mfma_f32_16x16x32_bf16 v[20:23], v[220:223], v[188:191], v[20:23]
	v_mfma_f32_16x16x32_bf16 v[8:11], v[216:219], v[192:195], v[8:11]
	v_mfma_f32_16x16x32_bf16 v[8:11], v[220:223], v[212:215], v[8:11]
	v_mfma_f32_16x16x32_bf16 v[44:47], v[224:227], v[168:171], v[44:47]
	v_mfma_f32_16x16x32_bf16 v[44:47], v[228:231], v[172:175], v[44:47]
	v_mfma_f32_16x16x32_bf16 v[28:31], v[224:227], v[176:179], v[28:31]
	v_mfma_f32_16x16x32_bf16 v[28:31], v[228:231], v[180:183], v[28:31]
	v_mfma_f32_16x16x32_bf16 v[12:15], v[224:227], v[184:187], v[12:15]
	v_mfma_f32_16x16x32_bf16 v[12:15], v[228:231], v[188:191], v[12:15]
	v_mfma_f32_16x16x32_bf16 v[4:7], v[224:227], v[192:195], v[4:7]
	v_mfma_f32_16x16x32_bf16 v[4:7], v[228:231], v[212:215], v[4:7]
	s_barrier
	s_setprio 0
	s_cmp_gt_u32 s39, 29
.LBB0_109:
	s_add_i32 s40, 0, 0x10000
	v_add_u32_e32 v142, s40, v145
	ds_read_b128 v[148:151], v142
	ds_read_b128 v[152:155], v142 offset:1024
	ds_read_b128 v[156:159], v142 offset:2048
	ds_read_b128 v[160:163], v142 offset:3072
	s_add_i32 m0, s24, 0xc000
	ds_read_b128 v[168:171], v146
	ds_read_b128 v[172:175], v146 offset:1024
	ds_read_b128 v[176:179], v146 offset:2048
	ds_read_b128 v[180:183], v146 offset:3072
	ds_read_b128 v[184:187], v146 offset:4096
	ds_read_b128 v[188:191], v146 offset:5120
	ds_read_b128 v[192:195], v146 offset:6144
	ds_read_b128 v[212:215], v146 offset:7168
	global_load_lds_dwordx4 v140, s[12:13]
	s_add_i32 m0, s24, 0xe000
	s_nop 0
	global_load_lds_dwordx4 v138, s[12:13]
	s_waitcnt lgkmcnt(6)
	s_setprio 1
	s_barrier
	v_mfma_f32_16x16x32_bf16 v[128:131], v[148:151], v[168:171], v[128:131]
	v_mfma_f32_16x16x32_bf16 v[128:131], v[152:155], v[172:175], v[128:131]
	s_waitcnt lgkmcnt(0)
	v_mfma_f32_16x16x32_bf16 v[120:123], v[148:151], v[176:179], v[120:123]
	v_mfma_f32_16x16x32_bf16 v[120:123], v[152:155], v[180:183], v[120:123]
	v_mfma_f32_16x16x32_bf16 v[104:107], v[148:151], v[184:187], v[104:107]
	v_mfma_f32_16x16x32_bf16 v[104:107], v[152:155], v[188:191], v[104:107]
	v_mfma_f32_16x16x32_bf16 v[88:91], v[148:151], v[192:195], v[88:91]
	v_mfma_f32_16x16x32_bf16 v[88:91], v[152:155], v[212:215], v[88:91]
	v_mfma_f32_16x16x32_bf16 v[124:127], v[156:159], v[168:171], v[124:127]
	v_mfma_f32_16x16x32_bf16 v[124:127], v[160:163], v[172:175], v[124:127]
	v_mfma_f32_16x16x32_bf16 v[112:115], v[156:159], v[176:179], v[112:115]
	v_mfma_f32_16x16x32_bf16 v[112:115], v[160:163], v[180:183], v[112:115]
	v_mfma_f32_16x16x32_bf16 v[96:99], v[156:159], v[184:187], v[96:99]
	v_mfma_f32_16x16x32_bf16 v[96:99], v[160:163], v[188:191], v[96:99]
	v_mfma_f32_16x16x32_bf16 v[80:83], v[156:159], v[192:195], v[80:83]
	v_mfma_f32_16x16x32_bf16 v[80:83], v[160:163], v[212:215], v[80:83]
	s_barrier
	s_setprio 0
	s_add_u32 s14, s12, 0xfff80080
	s_addc_u32 s15, s13, -1
	s_cmp_eq_u32 s39, 28
	s_cselect_b32 s17, s1, s15
	s_cselect_b32 s16, s11, s14
	s_cselect_b32 s15, s3, s38
	s_cselect_b32 s14, s36, s37
	s_add_i32 s42, 0, 0x14000
	v_add_u32_e32 v142, s42, v145
	s_add_i32 s40, s40, s19
	ds_read_b128 v[216:219], v142
	ds_read_b128 v[220:223], v142 offset:1024
	ds_read_b128 v[224:227], v142 offset:2048
	ds_read_b128 v[228:231], v142 offset:3072
	s_add_u32 s98, s14, 0x80
	s_addc_u32 s99, s15, 0
	s_mov_b32 m0, s40
	s_nop 0
	global_load_lds_dwordx4 v134, s[14:15]
	s_add_i32 m0, s40, 0x2000
	s_nop 0
	global_load_lds_dwordx4 v0, s[14:15]
	s_mov_b32 m0, s24
	s_add_u32 s100, s16, 0x80
	s_addc_u32 s101, s17, 0
	s_waitcnt lgkmcnt(2)
	s_setprio 1
	s_barrier
; #define PG8_WAIT_V(n) asm volatile("s_waitcnt vmcnt(" #n ")" ::: "memory")
; #define PG8_WAIT_L(n) asm volatile("s_waitcnt lgkmcnt(" #n ")" ::: "memory")
; #define PG8_BAR __builtin_amdgcn_s_barrier()
; #define PG8_SCHED __builtin_amdgcn_sched_barrier(0)
; template <class Epi, class AddrA, class AddrB>
; __device__ __forceinline__ void gemm_phase(const Sched S, const int lda, const int ldb, const int K, const AddrA addrA,
;                                            const AddrB addrB, const Epi E) {
;     ...
;       PG8_LDB(B0, 0, 0); PG8_SCHED; PG8_LDA(At, 0, 0); PG8_STAGE(PG8_SA(1, 1), a1 + hstepA, voffA);
;       PG8_WAIT_L(8); PG8_BAR; PG8_WAIT_L(0); PG8_MMA(0, 0, At, B0); PG8_BAR; PG8_SCHED;
;       PG8_LDB(B1, 0, 1); PG8_STAGE(PG8_SB(0, 0), b2, voffB);
;       PG8_BAR; PG8_WAIT_L(0); PG8_MMA(0, 1, At, B1); PG8_BAR;
;       PG8_LDA(At, 0, 1); PG8_STAGE(PG8_SA(0, 0), a2, voffA);
;       PG8_BAR; PG8_WAIT_L(0); PG8_MMA(1, 0, At, B0); PG8_BAR; PG8_SCHED;
;       PG8_STAGE(PG8_SB(0, 1), b2 + hstepB, voffB);
;       PG8_WAIT_V(6); PG8_BAR; PG8_MMA(1, 1, At, B1); PG8_BAR;
;       PG8_LDB(B0, 1, 0); PG8_SCHED; PG8_LDA(At, 1, 0); PG8_STAGE(PG8_SA(0, 1), a2 + hstepA, voffA);
;       PG8_WAIT_L(8); PG8_BAR; PG8_WAIT_L(0); PG8_MMA(0, 0, At, B0); PG8_BAR; PG8_SCHED;
;       PG8_LDB(B1, 1, 1); PG8_STAGE(PG8_SB(1, 0), b3, voffB);
;       PG8_BAR; PG8_WAIT_L(0); PG8_MMA(0, 1, At, B1); PG8_BAR;
;       PG8_LDA(At, 1, 1); PG8_STAGE(PG8_SA(1, 0), a3, voffA);
;       PG8_BAR; PG8_WAIT_L(0); PG8_MMA(1, 0, At, B0); PG8_BAR; PG8_SCHED;
;       PG8_STAGE(PG8_SB(1, 1), b3 + hstepB, voffB);
;       PG8_WAIT_V(6); PG8_BAR; PG8_MMA(1, 1, At, B1); PG8_BAR;
	v_mfma_f32_16x16x32_bf16 v[116:119], v[216:219], v[168:171], v[116:119]
	v_mfma_f32_16x16x32_bf16 v[116:119], v[220:223], v[172:175], v[116:119]
	s_waitcnt lgkmcnt(0)
	v_mfma_f32_16x16x32_bf16 v[100:103], v[216:219], v[176:179], v[100:103]
	v_mfma_f32_16x16x32_bf16 v[100:103], v[220:223], v[180:183], v[100:103]
	v_mfma_f32_16x16x32_bf16 v[84:87], v[216:219], v[184:187], v[84:87]
	v_mfma_f32_16x16x32_bf16 v[84:87], v[220:223], v[188:191], v[84:87]
	v_mfma_f32_16x16x32_bf16 v[72:75], v[216:219], v[192:195], v[72:75]
	v_mfma_f32_16x16x32_bf16 v[72:75], v[220:223], v[212:215], v[72:75]
	v_mfma_f32_16x16x32_bf16 v[108:111], v[224:227], v[168:171], v[108:111]
	v_mfma_f32_16x16x32_bf16 v[108:111], v[228:231], v[172:175], v[108:111]
	v_mfma_f32_16x16x32_bf16 v[92:95], v[224:227], v[176:179], v[92:95]
	v_mfma_f32_16x16x32_bf16 v[92:95], v[228:231], v[180:183], v[92:95]
	v_mfma_f32_16x16x32_bf16 v[76:79], v[224:227], v[184:187], v[76:79]
	v_mfma_f32_16x16x32_bf16 v[76:79], v[228:231], v[188:191], v[76:79]
	v_mfma_f32_16x16x32_bf16 v[68:71], v[224:227], v[192:195], v[68:71]
	v_mfma_f32_16x16x32_bf16 v[68:71], v[228:231], v[212:215], v[68:71]
	s_barrier
	s_setprio 0
	ds_read_b128 v[168:171], v146 offset:16384
	ds_read_b128 v[172:175], v146 offset:17408
	ds_read_b128 v[176:179], v146 offset:18432
	ds_read_b128 v[180:183], v146 offset:19456
	ds_read_b128 v[184:187], v146 offset:20480
	ds_read_b128 v[188:191], v146 offset:21504
	ds_read_b128 v[192:195], v146 offset:22528
	ds_read_b128 v[212:215], v146 offset:23552
	global_load_lds_dwordx4 v136, s[16:17]
	s_mov_b32 m0, s25
	s_nop 0
	global_load_lds_dwordx4 v132, s[16:17]
	s_waitcnt lgkmcnt(6)
	s_setprio 1
	s_barrier
	v_mfma_f32_16x16x32_bf16 v[64:67], v[148:151], v[168:171], v[64:67]
	v_mfma_f32_16x16x32_bf16 v[64:67], v[152:155], v[172:175], v[64:67]
	s_waitcnt lgkmcnt(0)
	v_mfma_f32_16x16x32_bf16 v[56:59], v[148:151], v[176:179], v[56:59]
	v_mfma_f32_16x16x32_bf16 v[56:59], v[152:155], v[180:183], v[56:59]
	v_mfma_f32_16x16x32_bf16 v[40:43], v[148:151], v[184:187], v[40:43]
	v_mfma_f32_16x16x32_bf16 v[40:43], v[152:155], v[188:191], v[40:43]
	v_mfma_f32_16x16x32_bf16 v[24:27], v[148:151], v[192:195], v[24:27]
	v_mfma_f32_16x16x32_bf16 v[24:27], v[152:155], v[212:215], v[24:27]
	v_mfma_f32_16x16x32_bf16 v[60:63], v[156:159], v[168:171], v[60:63]
	v_mfma_f32_16x16x32_bf16 v[60:63], v[160:163], v[172:175], v[60:63]
	v_mfma_f32_16x16x32_bf16 v[48:51], v[156:159], v[176:179], v[48:51]
	v_mfma_f32_16x16x32_bf16 v[48:51], v[160:163], v[180:183], v[48:51]
	v_mfma_f32_16x16x32_bf16 v[32:35], v[156:159], v[184:187], v[32:35]
	v_mfma_f32_16x16x32_bf16 v[32:35], v[160:163], v[188:191], v[32:35]
	v_mfma_f32_16x16x32_bf16 v[16:19], v[156:159], v[192:195], v[16:19]
	v_mfma_f32_16x16x32_bf16 v[16:19], v[160:163], v[212:215], v[16:19]
	s_barrier
	s_setprio 0
	s_add_u32 s40, s14, 0x80000
	s_addc_u32 s41, s15, 0
	s_add_i32 s42, s42, s19
	s_mov_b32 m0, s42
	s_nop 0
	global_load_lds_dwordx4 v134, s[40:41]
	s_add_i32 m0, s42, 0x2000
	s_nop 0
	global_load_lds_dwordx4 v0, s[40:41]
	s_add_i32 s40, 0, 0x18000
	v_add_u32_e32 v147, s40, v145
	s_waitcnt vmcnt(6)
	s_setprio 1
	s_barrier
	v_mfma_f32_16x16x32_bf16 v[52:55], v[216:219], v[168:171], v[52:55]
	v_mfma_f32_16x16x32_bf16 v[52:55], v[220:223], v[172:175], v[52:55]
	v_mfma_f32_16x16x32_bf16 v[36:39], v[216:219], v[176:179], v[36:39]
	v_mfma_f32_16x16x32_bf16 v[36:39], v[220:223], v[180:183], v[36:39]
	v_mfma_f32_16x16x32_bf16 v[20:23], v[216:219], v[184:187], v[20:23]
	v_mfma_f32_16x16x32_bf16 v[20:23], v[220:223], v[188:191], v[20:23]
	v_mfma_f32_16x16x32_bf16 v[8:11], v[216:219], v[192:195], v[8:11]
	v_mfma_f32_16x16x32_bf16 v[8:11], v[220:223], v[212:215], v[8:11]
	v_mfma_f32_16x16x32_bf16 v[44:47], v[224:227], v[168:171], v[44:47]
	v_mfma_f32_16x16x32_bf16 v[44:47], v[228:231], v[172:175], v[44:47]
	v_mfma_f32_16x16x32_bf16 v[28:31], v[224:227], v[176:179], v[28:31]
	v_mfma_f32_16x16x32_bf16 v[28:31], v[228:231], v[180:183], v[28:31]
	v_mfma_f32_16x16x32_bf16 v[12:15], v[224:227], v[184:187], v[12:15]
	v_mfma_f32_16x16x32_bf16 v[12:15], v[228:231], v[188:191], v[12:15]
	v_mfma_f32_16x16x32_bf16 v[4:7], v[224:227], v[192:195], v[4:7]
	v_mfma_f32_16x16x32_bf16 v[4:7], v[228:231], v[212:215], v[4:7]
	s_barrier
	s_setprio 0
	ds_read_b128 v[148:151], v147
	ds_read_b128 v[152:155], v147 offset:1024
	ds_read_b128 v[156:159], v147 offset:2048
	ds_read_b128 v[160:163], v147 offset:3072
	s_add_u32 s16, s16, 0x80000
	s_addc_u32 s17, s17, 0
	s_mov_b32 m0, s26
	ds_read_b128 v[168:171], v146 offset:32768
	ds_read_b128 v[172:175], v146 offset:33792
	ds_read_b128 v[176:179], v146 offset:34816
	ds_read_b128 v[180:183], v146 offset:35840
	ds_read_b128 v[184:187], v146 offset:36864
	ds_read_b128 v[188:191], v146 offset:37888
	ds_read_b128 v[192:195], v146 offset:38912
	ds_read_b128 v[212:215], v146 offset:39936
	global_load_lds_dwordx4 v136, s[16:17]
	s_mov_b32 m0, s27
	s_nop 0
	global_load_lds_dwordx4 v132, s[16:17]
	s_waitcnt lgkmcnt(6)
	s_setprio 1
	s_barrier
	v_mfma_f32_16x16x32_bf16 v[128:131], v[148:151], v[168:171], v[128:131]
	v_mfma_f32_16x16x32_bf16 v[128:131], v[152:155], v[172:175], v[128:131]
	s_waitcnt lgkmcnt(0)
	v_mfma_f32_16x16x32_bf16 v[120:123], v[148:151], v[176:179], v[120:123]
	v_mfma_f32_16x16x32_bf16 v[120:123], v[152:155], v[180:183], v[120:123]
	v_mfma_f32_16x16x32_bf16 v[104:107], v[148:151], v[184:187], v[104:107]
	v_mfma_f32_16x16x32_bf16 v[104:107], v[152:155], v[188:191], v[104:107]
	v_mfma_f32_16x16x32_bf16 v[88:91], v[148:151], v[192:195], v[88:91]
	v_mfma_f32_16x16x32_bf16 v[88:91], v[152:155], v[212:215], v[88:91]
	v_mfma_f32_16x16x32_bf16 v[124:127], v[156:159], v[168:171], v[124:127]
	v_mfma_f32_16x16x32_bf16 v[124:127], v[160:163], v[172:175], v[124:127]
	v_mfma_f32_16x16x32_bf16 v[112:115], v[156:159], v[176:179], v[112:115]
	v_mfma_f32_16x16x32_bf16 v[112:115], v[160:163], v[180:183], v[112:115]
	v_mfma_f32_16x16x32_bf16 v[96:99], v[156:159], v[184:187], v[96:99]
	v_mfma_f32_16x16x32_bf16 v[96:99], v[160:163], v[188:191], v[96:99]
	v_mfma_f32_16x16x32_bf16 v[80:83], v[156:159], v[192:195], v[80:83]
	v_mfma_f32_16x16x32_bf16 v[80:83], v[160:163], v[212:215], v[80:83]
	s_barrier
; #define PG8_WAIT_V(n) asm volatile("s_waitcnt vmcnt(" #n ")" ::: "memory")
; #define PG8_WAIT_L(n) asm volatile("s_waitcnt lgkmcnt(" #n ")" ::: "memory")
; #define PG8_BAR __builtin_amdgcn_s_barrier()
; #define PG8_SCHED __builtin_amdgcn_sched_barrier(0)
; template <class Epi, class AddrA, class AddrB>
; __device__ __forceinline__ void gemm_phase(const Sched S, const int lda, const int ldb, const int K, const AddrA addrA,
;                                            const AddrB addrB, const Epi E) {
;     ...
;       PG8_LDB(B0, 0, 0); PG8_SCHED; PG8_LDA(At, 0, 0); PG8_STAGE(PG8_SA(1, 1), a1 + hstepA, voffA);
;       PG8_WAIT_L(8); PG8_BAR; PG8_WAIT_L(0); PG8_MMA(0, 0, At, B0); PG8_BAR; PG8_SCHED;
;       PG8_LDB(B1, 0, 1); PG8_STAGE(PG8_SB(0, 0), b2, voffB);
;       PG8_BAR; PG8_WAIT_L(0); PG8_MMA(0, 1, At, B1); PG8_BAR;
;       PG8_LDA(At, 0, 1); PG8_STAGE(PG8_SA(0, 0), a2, voffA);
;       PG8_BAR; PG8_WAIT_L(0); PG8_MMA(1, 0, At, B0); PG8_BAR; PG8_SCHED;
;       PG8_STAGE(PG8_SB(0, 1), b2 + hstepB, voffB);
;       PG8_WAIT_V(6); PG8_BAR; PG8_MMA(1, 1, At, B1); PG8_BAR;
;       PG8_LDB(B0, 1, 0); PG8_SCHED; PG8_LDA(At, 1, 0); PG8_STAGE(PG8_SA(0, 1), a2 + hstepA, voffA);
;       PG8_WAIT_L(8); PG8_BAR; PG8_WAIT_L(0); PG8_MMA(0, 0, At, B0); PG8_BAR; PG8_SCHED;
;       PG8_LDB(B1, 1, 1); PG8_STAGE(PG8_SB(1, 0), b3, voffB);
;       PG8_BAR; PG8_WAIT_L(0); PG8_MMA(0, 1, At, B1); PG8_BAR;
;       PG8_LDA(At, 1, 1); PG8_STAGE(PG8_SA(1, 0), a3, voffA);
;       PG8_BAR; PG8_WAIT_L(0); PG8_MMA(1, 0, At, B0); PG8_BAR; PG8_SCHED;
;       PG8_STAGE(PG8_SB(1, 1), b3 + hstepB, voffB);
;       PG8_WAIT_V(6); PG8_BAR; PG8_MMA(1, 1, At, B1); PG8_BAR;
	s_setprio 0
	s_add_i32 s16, 0, 0x1c000
	s_add_i32 s17, s40, s19
	v_add_u32_e32 v147, s16, v145
	s_mov_b32 m0, s17
	ds_read_b128 v[216:219], v147
	ds_read_b128 v[220:223], v147 offset:1024
	ds_read_b128 v[224:227], v147 offset:2048
	ds_read_b128 v[228:231], v147 offset:3072
	global_load_lds_dwordx4 v134, s[98:99]
	s_add_i32 m0, s17, 0x2000
	s_nop 0
	global_load_lds_dwordx4 v0, s[98:99]
	s_mov_b32 m0, s30
	s_waitcnt lgkmcnt(2)
	s_setprio 1
	s_barrier
	v_mfma_f32_16x16x32_bf16 v[116:119], v[216:219], v[168:171], v[116:119]
	v_mfma_f32_16x16x32_bf16 v[116:119], v[220:223], v[172:175], v[116:119]
	s_waitcnt lgkmcnt(0)
	v_mfma_f32_16x16x32_bf16 v[100:103], v[216:219], v[176:179], v[100:103]
	v_mfma_f32_16x16x32_bf16 v[100:103], v[220:223], v[180:183], v[100:103]
	v_mfma_f32_16x16x32_bf16 v[84:87], v[216:219], v[184:187], v[84:87]
	v_mfma_f32_16x16x32_bf16 v[84:87], v[220:223], v[188:191], v[84:87]
	v_mfma_f32_16x16x32_bf16 v[72:75], v[216:219], v[192:195], v[72:75]
	v_mfma_f32_16x16x32_bf16 v[72:75], v[220:223], v[212:215], v[72:75]
	v_mfma_f32_16x16x32_bf16 v[108:111], v[224:227], v[168:171], v[108:111]
	v_mfma_f32_16x16x32_bf16 v[108:111], v[228:231], v[172:175], v[108:111]
	v_mfma_f32_16x16x32_bf16 v[92:95], v[224:227], v[176:179], v[92:95]
	v_mfma_f32_16x16x32_bf16 v[92:95], v[228:231], v[180:183], v[92:95]
	v_mfma_f32_16x16x32_bf16 v[76:79], v[224:227], v[184:187], v[76:79]
	v_mfma_f32_16x16x32_bf16 v[76:79], v[228:231], v[188:191], v[76:79]
	v_mfma_f32_16x16x32_bf16 v[68:71], v[224:227], v[192:195], v[68:71]
	v_mfma_f32_16x16x32_bf16 v[68:71], v[228:231], v[212:215], v[68:71]
	s_barrier
	s_setprio 0
	ds_read_b128 v[168:171], v146 offset:49152
	ds_read_b128 v[172:175], v146 offset:50176
	ds_read_b128 v[176:179], v146 offset:51200
	ds_read_b128 v[180:183], v146 offset:52224
	ds_read_b128 v[184:187], v146 offset:53248
	ds_read_b128 v[188:191], v146 offset:54272
	ds_read_b128 v[192:195], v146 offset:55296
	ds_read_b128 v[212:215], v146 offset:56320
	global_load_lds_dwordx4 v136, s[100:101]
	s_mov_b32 m0, s31
	s_nop 0
	global_load_lds_dwordx4 v132, s[100:101]
	s_waitcnt lgkmcnt(6)
	s_setprio 1
	s_barrier
	v_mfma_f32_16x16x32_bf16 v[64:67], v[148:151], v[168:171], v[64:67]
	v_mfma_f32_16x16x32_bf16 v[64:67], v[152:155], v[172:175], v[64:67]
	s_waitcnt lgkmcnt(0)
	v_mfma_f32_16x16x32_bf16 v[56:59], v[148:151], v[176:179], v[56:59]
	v_mfma_f32_16x16x32_bf16 v[56:59], v[152:155], v[180:183], v[56:59]
	v_mfma_f32_16x16x32_bf16 v[40:43], v[148:151], v[184:187], v[40:43]
	v_mfma_f32_16x16x32_bf16 v[40:43], v[152:155], v[188:191], v[40:43]
	v_mfma_f32_16x16x32_bf16 v[24:27], v[148:151], v[192:195], v[24:27]
	v_mfma_f32_16x16x32_bf16 v[24:27], v[152:155], v[212:215], v[24:27]
	v_mfma_f32_16x16x32_bf16 v[60:63], v[156:159], v[168:171], v[60:63]
	v_mfma_f32_16x16x32_bf16 v[60:63], v[160:163], v[172:175], v[60:63]
	v_mfma_f32_16x16x32_bf16 v[48:51], v[156:159], v[176:179], v[48:51]
	v_mfma_f32_16x16x32_bf16 v[48:51], v[160:163], v[180:183], v[48:51]
	v_mfma_f32_16x16x32_bf16 v[32:35], v[156:159], v[184:187], v[32:35]
	v_mfma_f32_16x16x32_bf16 v[32:35], v[160:163], v[188:191], v[32:35]
	v_mfma_f32_16x16x32_bf16 v[16:19], v[156:159], v[192:195], v[16:19]
	v_mfma_f32_16x16x32_bf16 v[16:19], v[160:163], v[212:215], v[16:19]
	s_barrier
	s_setprio 0
	s_add_u32 s14, s14, 0x80080
	s_addc_u32 s15, s15, 0
	s_add_i32 s16, s16, s19
	s_mov_b32 m0, s16
	s_nop 0
	global_load_lds_dwordx4 v134, s[14:15]
	s_add_i32 m0, s16, 0x2000
	s_nop 0
	global_load_lds_dwordx4 v0, s[14:15]
	s_add_i32 s39, s39, 2
	s_add_u32 s37, s37, 0x100
	s_addc_u32 s38, s38, 0
	s_add_u32 s12, s12, 0x100
	s_addc_u32 s13, s13, 0
	s_waitcnt vmcnt(6)
	s_setprio 1
	s_barrier
	v_mfma_f32_16x16x32_bf16 v[52:55], v[216:219], v[168:171], v[52:55]
	v_mfma_f32_16x16x32_bf16 v[52:55], v[220:223], v[172:175], v[52:55]
	v_mfma_f32_16x16x32_bf16 v[36:39], v[216:219], v[176:179], v[36:39]
	v_mfma_f32_16x16x32_bf16 v[36:39], v[220:223], v[180:183], v[36:39]
	v_mfma_f32_16x16x32_bf16 v[20:23], v[216:219], v[184:187], v[20:23]
	v_mfma_f32_16x16x32_bf16 v[20:23], v[220:223], v[188:191], v[20:23]
	v_mfma_f32_16x16x32_bf16 v[8:11], v[216:219], v[192:195], v[8:11]
	v_mfma_f32_16x16x32_bf16 v[8:11], v[220:223], v[212:215], v[8:11]
	v_mfma_f32_16x16x32_bf16 v[44:47], v[224:227], v[168:171], v[44:47]
	v_mfma_f32_16x16x32_bf16 v[44:47], v[228:231], v[172:175], v[44:47]
	v_mfma_f32_16x16x32_bf16 v[28:31], v[224:227], v[176:179], v[28:31]
	v_mfma_f32_16x16x32_bf16 v[28:31], v[228:231], v[180:183], v[28:31]
	v_mfma_f32_16x16x32_bf16 v[12:15], v[224:227], v[184:187], v[12:15]
	v_mfma_f32_16x16x32_bf16 v[12:15], v[228:231], v[188:191], v[12:15]
	v_mfma_f32_16x16x32_bf16 v[4:7], v[224:227], v[192:195], v[4:7]
	v_mfma_f32_16x16x32_bf16 v[4:7], v[228:231], v[212:215], v[4:7]
	s_barrier
;   __device__ __forceinline__ void operator()(EPI_ARGS) const {
;     bf16_t* base = proj + ((size_t)u.pn * MTOK + (size_t)(u.pm * 256 + wr * 64 + fr)) * PLD + wc * 32 + 8 * fq;
; #pragma unroll
;     for (int ai = 0; ai < 2; ++ai)
; #pragma unroll
;       for (int m = 0; m < 4; ++m) {
;         bf16_t* rowp = base + (size_t)(ai * HALF + m * 16) * PLD;
; #pragma unroll
;         for (int bj = 0; bj < 2; ++bj) {
;           const f32x4 v0 = acc[ai][bj][m][0], v1 = acc[ai][bj][m][1];
;           u32x4 o;
;           o.x = pack2(v0[0], v0[1]); o.y = pack2(v0[2], v0[3]); o.z = pack2(v1[0], v1[1]); o.w = pack2(v1[2], v1[3]);
;           *(u32x4*)(rowp + bj * HALF) = o;
;         }
;       }
	s_setprio 0
	s_cmp_gt_u32 s39, 29
	s_cbranch_scc0 .LBB0_109
	s_ashr_i32 s11, s10, 31
	v_lshl_add_u32 v142, s35, 8, v144
	s_lshl_b64 s[10:11], s[10:11], 23
	v_ashrrev_i32_e32 v143, 31, v142
	s_add_u32 s10, s28, s10
	s_addc_u32 s11, s29, s11
	v_lshlrev_b64 v[142:143], 9, v[142:143]
	v_lshl_add_u64 v[142:143], s[10:11], 0, v[142:143]
	v_lshl_add_u64 v[142:143], v[142:143], 0, s[72:73]
	v_lshl_add_u64 v[142:143], v[142:143], 0, v[2:3]
	v_cvt_pk_bf16_f32 v116, v116, v117
	v_cvt_pk_bf16_f32 v117, v118, v119
	v_cvt_pk_bf16_f32 v119, v110, v111
	v_cvt_pk_bf16_f32 v110, v112, v113
	v_add_co_u32_e32 v112, vcc, s96, v142
	s_movk_i32 s1, 0x4000
	s_nop 0
	v_addc_co_u32_e32 v113, vcc, 0, v143, vcc
	v_cvt_pk_bf16_f32 v100, v100, v101
	v_cvt_pk_bf16_f32 v101, v102, v103
	v_cvt_pk_bf16_f32 v103, v94, v95
	v_cvt_pk_bf16_f32 v94, v96, v97
	v_add_co_u32_e32 v96, vcc, s1, v142
	s_movk_i32 s1, 0x6000
	s_nop 0
	v_addc_co_u32_e32 v97, vcc, 0, v143, vcc
	v_cvt_pk_bf16_f32 v84, v84, v85
	v_cvt_pk_bf16_f32 v85, v86, v87
	v_cvt_pk_bf16_f32 v87, v78, v79
	v_cvt_pk_bf16_f32 v78, v80, v81
	v_add_co_u32_e32 v80, vcc, s1, v142
	v_cvt_pk_bf16_f32 v64, v64, v65
	v_cvt_pk_bf16_f32 v65, v66, v67
	v_cvt_pk_bf16_f32 v66, v60, v61
	s_mov_b32 s1, 0x12000
	s_nop 0
	v_addc_co_u32_e32 v81, vcc, 0, v143, vcc
	v_add_co_u32_e32 v60, vcc, s67, v142
	v_cvt_pk_bf16_f32 v52, v52, v53
	v_cvt_pk_bf16_f32 v53, v54, v55
	v_cvt_pk_bf16_f32 v55, v46, v47
	v_cvt_pk_bf16_f32 v46, v48, v49
	s_nop 1
	v_addc_co_u32_e32 v61, vcc, 0, v143, vcc
	v_add_co_u32_e32 v48, vcc, s1, v142
	s_mov_b32 s1, 0x14000
	s_nop 0
	v_addc_co_u32_e32 v49, vcc, 0, v143, vcc
	v_cvt_pk_bf16_f32 v36, v36, v37
	v_cvt_pk_bf16_f32 v37, v38, v39
	v_cvt_pk_bf16_f32 v39, v30, v31
	v_cvt_pk_bf16_f32 v30, v32, v33
	v_add_co_u32_e32 v32, vcc, s1, v142
	s_mov_b32 s1, 0x16000
	s_nop 0
	v_addc_co_u32_e32 v33, vcc, 0, v143, vcc
	v_cvt_pk_bf16_f32 v20, v20, v21
	v_cvt_pk_bf16_f32 v21, v22, v23
	v_cvt_pk_bf16_f32 v23, v14, v15
	v_cvt_pk_bf16_f32 v14, v16, v17
	v_add_co_u32_e32 v16, vcc, s1, v142
	s_mov_b32 s10, s2
	s_nop 0
	v_addc_co_u32_e32 v17, vcc, 0, v143, vcc
	s_and_b64 vcc, exec, s[4:5]
	s_mov_b32 s35, s0
	s_mov_b64 s[12:13], s[8:9]
	s_mov_b64 s[14:15], s[6:7]
	v_cvt_pk_bf16_f32 v128, v128, v129
	v_cvt_pk_bf16_f32 v129, v130, v131
	v_cvt_pk_bf16_f32 v130, v124, v125
	v_cvt_pk_bf16_f32 v131, v126, v127
	flat_store_dwordx4 v[142:143], v[128:131]
	v_cvt_pk_bf16_f32 v118, v108, v109
	flat_store_dwordx4 v[142:143], v[116:119] offset:256
	v_cvt_pk_bf16_f32 v108, v120, v121
	v_cvt_pk_bf16_f32 v109, v122, v123
	v_cvt_pk_bf16_f32 v111, v114, v115
	flat_store_dwordx4 v[112:113], v[108:111]
	v_cvt_pk_bf16_f32 v102, v92, v93
	flat_store_dwordx4 v[112:113], v[100:103] offset:256
	v_cvt_pk_bf16_f32 v92, v104, v105
	v_cvt_pk_bf16_f32 v93, v106, v107
	v_cvt_pk_bf16_f32 v95, v98, v99
	flat_store_dwordx4 v[96:97], v[92:95]
	v_cvt_pk_bf16_f32 v86, v76, v77
	flat_store_dwordx4 v[96:97], v[84:87] offset:256
	v_cvt_pk_bf16_f32 v76, v88, v89
	v_cvt_pk_bf16_f32 v77, v90, v91
	v_cvt_pk_bf16_f32 v79, v82, v83
	flat_store_dwordx4 v[80:81], v[76:79]
	v_cvt_pk_bf16_f32 v72, v72, v73
	v_cvt_pk_bf16_f32 v73, v74, v75
	v_cvt_pk_bf16_f32 v74, v68, v69
	v_cvt_pk_bf16_f32 v75, v70, v71
	flat_store_dwordx4 v[80:81], v[72:75] offset:256
	v_cvt_pk_bf16_f32 v67, v62, v63
	flat_store_dwordx4 v[60:61], v[64:67]
	v_cvt_pk_bf16_f32 v54, v44, v45
	flat_store_dwordx4 v[60:61], v[52:55] offset:256
	v_cvt_pk_bf16_f32 v44, v56, v57
	v_cvt_pk_bf16_f32 v45, v58, v59
	v_cvt_pk_bf16_f32 v47, v50, v51
	flat_store_dwordx4 v[48:49], v[44:47]
	v_cvt_pk_bf16_f32 v38, v28, v29
	flat_store_dwordx4 v[48:49], v[36:39] offset:256
	v_cvt_pk_bf16_f32 v28, v40, v41
	v_cvt_pk_bf16_f32 v29, v42, v43
	v_cvt_pk_bf16_f32 v31, v34, v35
	flat_store_dwordx4 v[32:33], v[28:31]
	v_cvt_pk_bf16_f32 v22, v12, v13
	flat_store_dwordx4 v[32:33], v[20:23] offset:256
	v_cvt_pk_bf16_f32 v12, v24, v25
	v_cvt_pk_bf16_f32 v13, v26, v27
	v_cvt_pk_bf16_f32 v15, v18, v19
	flat_store_dwordx4 v[16:17], v[12:15]
	v_cvt_pk_bf16_f32 v8, v8, v9
	v_cvt_pk_bf16_f32 v9, v10, v11
	v_cvt_pk_bf16_f32 v10, v4, v5
	v_cvt_pk_bf16_f32 v11, v6, v7
	flat_store_dwordx4 v[16:17], v[8:11] offset:256
	s_cbranch_vccz .LBB0_106
	s_waitcnt vmcnt(0)
	s_cmpk_gt_u32 s18, 0xff
	s_cbranch_scc1 .LBB0_113
	s_barrier

; #define PG8_WAIT_V(n) asm volatile("s_waitcnt vmcnt(" #n ")" ::: "memory")
; #define PG8_WAIT_L(n) asm volatile("s_waitcnt lgkmcnt(" #n ")" ::: "memory")
; template <class Epi, class AddrA, class AddrB>
; __device__ __forceinline__ void gemm_phase(const Sched S, const int lda, const int ldb, const int K, const AddrA addrA,
;                                            const AddrB addrB, const Epi E) {
;     ...
;     const bool has_next = S.next(ui + 1, nxt);
;     const char* nA = has_next ? addrA(nxt) : cA;
;     const char* nB = has_next ? addrB(nxt) : cB;
;     for (int t = 0; t < nt; t += 2) {
;       const bool last = (t == nt - 2);
;       const char* a1 = cA + (size_t)(t + 1) * kstep;
;       const char* a2 = last ? nA : cA + (size_t)(t + 2) * kstep;
;       const char* b2 = last ? nB : cB + (size_t)(t + 2) * kstep;
;       const char* a3 = a2 + kstep;
;       const char* b3 = b2 + kstep;
;       PG8_LDB(B0, 0, 0); PG8_SCHED; PG8_LDA(At, 0, 0); PG8_STAGE(PG8_SA(1, 1), a1 + hstepA, voffA);
;       PG8_WAIT_L(8); PG8_BAR; PG8_WAIT_L(0); PG8_MMA(0, 0, At, B0); PG8_BAR; PG8_SCHED;
;       PG8_LDB(B1, 0, 1); PG8_STAGE(PG8_SB(0, 0), b2, voffB);
;       PG8_BAR; PG8_WAIT_L(0); PG8_MMA(0, 1, At, B1); PG8_BAR;
;       PG8_LDA(At, 0, 1); PG8_STAGE(PG8_SA(0, 0), a2, voffA);
;       PG8_BAR; PG8_WAIT_L(0); PG8_MMA(1, 0, At, B0); PG8_BAR; PG8_SCHED;
;       PG8_STAGE(PG8_SB(0, 1), b2 + hstepB, voffB);
;       PG8_WAIT_V(6); PG8_BAR; PG8_MMA(1, 1, At, B1); PG8_BAR;
;       PG8_LDB(B0, 1, 0); PG8_SCHED; PG8_LDA(At, 1, 0); PG8_STAGE(PG8_SA(0, 1), a2 + hstepA, voffA);
;       PG8_WAIT_L(8); PG8_BAR; PG8_WAIT_L(0); PG8_MMA(0, 0, At, B0); PG8_BAR; PG8_SCHED;
;       PG8_LDB(B1, 1, 1); PG8_STAGE(PG8_SB(1, 0), b3, voffB);
;       PG8_BAR; PG8_WAIT_L(0); PG8_MMA(0, 1, At, B1); PG8_BAR;
;       PG8_LDA(At, 1, 1); PG8_STAGE(PG8_SA(1, 0), a3, voffA);
;       PG8_BAR; PG8_WAIT_L(0); PG8_MMA(1, 0, At, B0); PG8_BAR; PG8_SCHED;
;       PG8_STAGE(PG8_SB(1, 1), b3 + hstepB, voffB);
;       PG8_WAIT_V(6); PG8_BAR; PG8_MMA(1, 1, At, B1); PG8_BAR;
; __device__ void phase_post(const Params& p, int layer) {
;     ...
;     gemm_phase(S, DM, 512, 512,
;                [=](const Unit& u) { return (const char*)(pooled + (size_t)u.pm * 256 * DM + (u.pn >> 1) * 512); },
;                [=](const Unit& u) { return (const char*)(wpt + (size_t)u.pn * 256 * 512); }, EpiPool{proj, psc, y0});
.LBB0_484:
	s_ashr_i32 s15, s14, 31
	s_lshl_b64 s[20:21], s[14:15], 20
	s_add_u32 s3, s25, s20
	s_addc_u32 s15, s26, s21
	s_lshl_b32 s17, s16, 8
	s_and_b32 s20, s17, 0xfffffe00
	s_ashr_i32 s21, s20, 31
	s_lshl_b64 s[20:21], s[20:21], 1
	s_add_u32 s20, s3, s20
	s_addc_u32 s21, s15, s21
	s_and_b64 s[22:23], s[10:11], exec
	s_cselect_b32 s3, s21, s7
	s_cselect_b32 s15, s20, s6
	s_ashr_i32 s17, s16, 31
	s_lshl_b64 s[22:23], s[16:17], 18
	s_add_u32 s22, s27, s22
	s_addc_u32 s23, s28, s23
	s_and_b64 s[10:11], s[10:11], exec
	s_cselect_b32 s17, s23, s5
	s_cselect_b32 s40, s22, s4
	s_add_u32 s41, s4, 0x100
	s_addc_u32 s42, s5, 0
	s_add_u32 s4, s6, 0x80080
	s_addc_u32 s5, s7, 0
	s_mov_b32 s43, -2
	s_add_i32 s44, 0, 0x10000
	v_add_u32_e32 v2, s44, v167
	ds_read_b128 v[92:95], v2
	ds_read_b128 v[100:103], v2 offset:1024
	ds_read_b128 v[132:135], v2 offset:2048
	ds_read_b128 v[144:147], v2 offset:3072
	s_add_i32 m0, s30, 0xc000
	ds_read_b128 v[148:151], v169
	ds_read_b128 v[152:155], v169 offset:1024
	ds_read_b128 v[176:179], v169 offset:2048
	ds_read_b128 v[180:183], v169 offset:3072
	ds_read_b128 v[184:187], v169 offset:4096
	ds_read_b128 v[188:191], v169 offset:5120
	ds_read_b128 v[192:195], v169 offset:6144
	ds_read_b128 v[212:215], v169 offset:7168
	global_load_lds_dwordx4 v172, s[4:5]
	s_add_i32 m0, s30, 0xe000
	s_nop 0
	global_load_lds_dwordx4 v170, s[4:5]
	s_waitcnt lgkmcnt(6)
	s_setprio 1
	s_barrier
	v_mfma_f32_16x16x32_bf16 v[140:143], v[92:95], v[148:151], 0
	v_mfma_f32_16x16x32_bf16 v[140:143], v[100:103], v[152:155], v[140:143]
	s_waitcnt lgkmcnt(0)
	v_mfma_f32_16x16x32_bf16 v[128:131], v[92:95], v[176:179], 0
	v_mfma_f32_16x16x32_bf16 v[128:131], v[100:103], v[180:183], v[128:131]
	v_mfma_f32_16x16x32_bf16 v[120:123], v[92:95], v[184:187], 0
	v_mfma_f32_16x16x32_bf16 v[120:123], v[100:103], v[188:191], v[120:123]
	v_mfma_f32_16x16x32_bf16 v[112:115], v[92:95], v[192:195], 0
	v_mfma_f32_16x16x32_bf16 v[112:115], v[100:103], v[212:215], v[112:115]
	v_mfma_f32_16x16x32_bf16 v[136:139], v[132:135], v[148:151], 0
	v_mfma_f32_16x16x32_bf16 v[136:139], v[144:147], v[152:155], v[136:139]
	v_mfma_f32_16x16x32_bf16 v[124:127], v[132:135], v[176:179], 0
	v_mfma_f32_16x16x32_bf16 v[124:127], v[144:147], v[180:183], v[124:127]
	v_mfma_f32_16x16x32_bf16 v[116:119], v[132:135], v[184:187], 0
	v_mfma_f32_16x16x32_bf16 v[116:119], v[144:147], v[188:191], v[116:119]
	v_mfma_f32_16x16x32_bf16 v[108:111], v[132:135], v[192:195], 0
	v_mfma_f32_16x16x32_bf16 v[108:111], v[144:147], v[212:215], v[108:111]
	s_barrier
	s_setprio 0
	s_add_u32 s6, s4, 0xfff80080
	s_addc_u32 s7, s5, -1
	s_cmp_eq_u32 s43, 4
	s_cselect_b32 s11, s3, s7
	s_cselect_b32 s10, s15, s6
	s_cselect_b32 s7, s17, s42
	s_cselect_b32 s6, s40, s41
	s_add_i32 s46, 0, 0x14000
	s_add_i32 s44, s44, s29
	v_add_u32_e32 v2, s46, v167
	s_add_u32 s98, s6, 0x80
	s_addc_u32 s99, s7, 0
	s_mov_b32 m0, s44
	ds_read_b128 v[216:219], v2
	ds_read_b128 v[220:223], v2 offset:1024
	ds_read_b128 v[224:227], v2 offset:2048
	ds_read_b128 v[228:231], v2 offset:3072
	global_load_lds_dwordx4 v158, s[6:7]
	s_add_i32 m0, s44, 0x2000
	s_nop 0
	global_load_lds_dwordx4 v0, s[6:7]
	s_mov_b32 m0, s30
	s_add_u32 s100, s10, 0x80
	s_addc_u32 s101, s11, 0
	s_waitcnt lgkmcnt(2)
	s_setprio 1
	s_barrier
	v_mfma_f32_16x16x32_bf16 v[64:67], v[216:219], v[148:151], 0
	v_mfma_f32_16x16x32_bf16 v[64:67], v[220:223], v[152:155], v[64:67]
	s_waitcnt lgkmcnt(0)
	v_mfma_f32_16x16x32_bf16 v[56:59], v[216:219], v[176:179], 0
	v_mfma_f32_16x16x32_bf16 v[56:59], v[220:223], v[180:183], v[56:59]
	v_mfma_f32_16x16x32_bf16 v[48:51], v[216:219], v[184:187], 0
	v_mfma_f32_16x16x32_bf16 v[48:51], v[220:223], v[188:191], v[48:51]
	v_mfma_f32_16x16x32_bf16 v[40:43], v[216:219], v[192:195], 0
	v_mfma_f32_16x16x32_bf16 v[40:43], v[220:223], v[212:215], v[40:43]
	v_mfma_f32_16x16x32_bf16 v[60:63], v[224:227], v[148:151], 0
	v_mfma_f32_16x16x32_bf16 v[60:63], v[228:231], v[152:155], v[60:63]
	v_mfma_f32_16x16x32_bf16 v[52:55], v[224:227], v[176:179], 0
	v_mfma_f32_16x16x32_bf16 v[52:55], v[228:231], v[180:183], v[52:55]
	v_mfma_f32_16x16x32_bf16 v[44:47], v[224:227], v[184:187], 0
	v_mfma_f32_16x16x32_bf16 v[44:47], v[228:231], v[188:191], v[44:47]
	v_mfma_f32_16x16x32_bf16 v[36:39], v[224:227], v[192:195], 0
	v_mfma_f32_16x16x32_bf16 v[36:39], v[228:231], v[212:215], v[36:39]
	s_barrier
	s_setprio 0
	ds_read_b128 v[148:151], v169 offset:16384
	ds_read_b128 v[152:155], v169 offset:17408
	ds_read_b128 v[176:179], v169 offset:18432
	ds_read_b128 v[180:183], v169 offset:19456
	ds_read_b128 v[184:187], v169 offset:20480
	ds_read_b128 v[188:191], v169 offset:21504
	ds_read_b128 v[192:195], v169 offset:22528
	ds_read_b128 v[212:215], v169 offset:23552
	global_load_lds_dwordx4 v160, s[10:11]
	s_mov_b32 m0, s31
	s_nop 0
	global_load_lds_dwordx4 v156, s[10:11]
	s_waitcnt lgkmcnt(6)
	s_setprio 1
	s_barrier
	v_mfma_f32_16x16x32_bf16 v[104:107], v[92:95], v[148:151], 0
	v_mfma_f32_16x16x32_bf16 v[104:107], v[100:103], v[152:155], v[104:107]
	s_waitcnt lgkmcnt(0)
	v_mfma_f32_16x16x32_bf16 v[88:91], v[92:95], v[176:179], 0
	v_mfma_f32_16x16x32_bf16 v[88:91], v[100:103], v[180:183], v[88:91]
	v_mfma_f32_16x16x32_bf16 v[80:83], v[92:95], v[184:187], 0
	v_mfma_f32_16x16x32_bf16 v[80:83], v[100:103], v[188:191], v[80:83]
	v_mfma_f32_16x16x32_bf16 v[72:75], v[92:95], v[192:195], 0
	v_mfma_f32_16x16x32_bf16 v[72:75], v[100:103], v[212:215], v[72:75]
	v_mfma_f32_16x16x32_bf16 v[96:99], v[132:135], v[148:151], 0
	v_mfma_f32_16x16x32_bf16 v[96:99], v[144:147], v[152:155], v[96:99]
	v_mfma_f32_16x16x32_bf16 v[84:87], v[132:135], v[176:179], 0
	v_mfma_f32_16x16x32_bf16 v[84:87], v[144:147], v[180:183], v[84:87]
	v_mfma_f32_16x16x32_bf16 v[76:79], v[132:135], v[184:187], 0
	v_mfma_f32_16x16x32_bf16 v[76:79], v[144:147], v[188:191], v[76:79]
	v_mfma_f32_16x16x32_bf16 v[68:71], v[132:135], v[192:195], 0
	v_mfma_f32_16x16x32_bf16 v[68:71], v[144:147], v[212:215], v[68:71]
	s_barrier
; #define PG8_WAIT_V(n) asm volatile("s_waitcnt vmcnt(" #n ")" ::: "memory")
; #define PG8_WAIT_L(n) asm volatile("s_waitcnt lgkmcnt(" #n ")" ::: "memory")
; #define PG8_BAR __builtin_amdgcn_s_barrier()
; #define PG8_SCHED __builtin_amdgcn_sched_barrier(0)
; template <class Epi, class AddrA, class AddrB>
; __device__ __forceinline__ void gemm_phase(const Sched S, const int lda, const int ldb, const int K, const AddrA addrA,
;                                            const AddrB addrB, const Epi E) {
;     ...
;       PG8_LDB(B0, 0, 0); PG8_SCHED; PG8_LDA(At, 0, 0); PG8_STAGE(PG8_SA(1, 1), a1 + hstepA, voffA);
;       PG8_WAIT_L(8); PG8_BAR; PG8_WAIT_L(0); PG8_MMA(0, 0, At, B0); PG8_BAR; PG8_SCHED;
;       PG8_LDB(B1, 0, 1); PG8_STAGE(PG8_SB(0, 0), b2, voffB);
;       PG8_BAR; PG8_WAIT_L(0); PG8_MMA(0, 1, At, B1); PG8_BAR;
;       PG8_LDA(At, 0, 1); PG8_STAGE(PG8_SA(0, 0), a2, voffA);
;       PG8_BAR; PG8_WAIT_L(0); PG8_MMA(1, 0, At, B0); PG8_BAR; PG8_SCHED;
;       PG8_STAGE(PG8_SB(0, 1), b2 + hstepB, voffB);
;       PG8_WAIT_V(6); PG8_BAR; PG8_MMA(1, 1, At, B1); PG8_BAR;
;       PG8_LDB(B0, 1, 0); PG8_SCHED; PG8_LDA(At, 1, 0); PG8_STAGE(PG8_SA(0, 1), a2 + hstepA, voffA);
;       PG8_WAIT_L(8); PG8_BAR; PG8_WAIT_L(0); PG8_MMA(0, 0, At, B0); PG8_BAR; PG8_SCHED;
;       PG8_LDB(B1, 1, 1); PG8_STAGE(PG8_SB(1, 0), b3, voffB);
;       PG8_BAR; PG8_WAIT_L(0); PG8_MMA(0, 1, At, B1); PG8_BAR;
;       PG8_LDA(At, 1, 1); PG8_STAGE(PG8_SA(1, 0), a3, voffA);
;       PG8_BAR; PG8_WAIT_L(0); PG8_MMA(1, 0, At, B0); PG8_BAR; PG8_SCHED;
;       PG8_STAGE(PG8_SB(1, 1), b3 + hstepB, voffB);
;       PG8_WAIT_V(6); PG8_BAR; PG8_MMA(1, 1, At, B1); PG8_BAR;
	s_setprio 0
	s_add_u32 s44, s6, 0x20000
	s_addc_u32 s45, s7, 0
	s_add_i32 s46, s46, s29
	s_mov_b32 m0, s46
	s_nop 0
	global_load_lds_dwordx4 v158, s[44:45]
	s_add_i32 m0, s46, 0x2000
	s_nop 0
	global_load_lds_dwordx4 v0, s[44:45]
	s_add_i32 s44, 0, 0x18000
	v_add_u32_e32 v2, s44, v167
	s_waitcnt vmcnt(6)
	s_setprio 1
	s_barrier
	v_mfma_f32_16x16x32_bf16 v[32:35], v[216:219], v[148:151], 0
	v_mfma_f32_16x16x32_bf16 v[32:35], v[220:223], v[152:155], v[32:35]
	v_mfma_f32_16x16x32_bf16 v[24:27], v[216:219], v[176:179], 0
	v_mfma_f32_16x16x32_bf16 v[24:27], v[220:223], v[180:183], v[24:27]
	v_mfma_f32_16x16x32_bf16 v[16:19], v[216:219], v[184:187], 0
	v_mfma_f32_16x16x32_bf16 v[16:19], v[220:223], v[188:191], v[16:19]
	v_mfma_f32_16x16x32_bf16 v[8:11], v[216:219], v[192:195], 0
	v_mfma_f32_16x16x32_bf16 v[8:11], v[220:223], v[212:215], v[8:11]
	v_mfma_f32_16x16x32_bf16 v[28:31], v[224:227], v[148:151], 0
	v_mfma_f32_16x16x32_bf16 v[28:31], v[228:231], v[152:155], v[28:31]
	v_mfma_f32_16x16x32_bf16 v[20:23], v[224:227], v[176:179], 0
	v_mfma_f32_16x16x32_bf16 v[20:23], v[228:231], v[180:183], v[20:23]
	v_mfma_f32_16x16x32_bf16 v[12:15], v[224:227], v[184:187], 0
	v_mfma_f32_16x16x32_bf16 v[12:15], v[228:231], v[188:191], v[12:15]
	v_mfma_f32_16x16x32_bf16 v[4:7], v[224:227], v[192:195], 0
	v_mfma_f32_16x16x32_bf16 v[4:7], v[228:231], v[212:215], v[4:7]
	s_barrier
	s_setprio 0
	ds_read_b128 v[92:95], v2
	ds_read_b128 v[100:103], v2 offset:1024
	ds_read_b128 v[132:135], v2 offset:2048
	ds_read_b128 v[144:147], v2 offset:3072
	s_add_u32 s10, s10, 0x80000
	s_addc_u32 s11, s11, 0
	s_mov_b32 m0, s34
	ds_read_b128 v[148:151], v169 offset:32768
	ds_read_b128 v[152:155], v169 offset:33792
	ds_read_b128 v[176:179], v169 offset:34816
	ds_read_b128 v[180:183], v169 offset:35840
	ds_read_b128 v[184:187], v169 offset:36864
	ds_read_b128 v[188:191], v169 offset:37888
	ds_read_b128 v[192:195], v169 offset:38912
	ds_read_b128 v[212:215], v169 offset:39936
	global_load_lds_dwordx4 v160, s[10:11]
	s_mov_b32 m0, s35
	s_nop 0
	global_load_lds_dwordx4 v156, s[10:11]
	s_waitcnt lgkmcnt(6)
	s_setprio 1
	s_barrier
	v_mfma_f32_16x16x32_bf16 v[140:143], v[92:95], v[148:151], v[140:143]
	v_mfma_f32_16x16x32_bf16 v[140:143], v[100:103], v[152:155], v[140:143]
	s_waitcnt lgkmcnt(0)
	v_mfma_f32_16x16x32_bf16 v[128:131], v[92:95], v[176:179], v[128:131]
	v_mfma_f32_16x16x32_bf16 v[128:131], v[100:103], v[180:183], v[128:131]
	v_mfma_f32_16x16x32_bf16 v[120:123], v[92:95], v[184:187], v[120:123]
	v_mfma_f32_16x16x32_bf16 v[120:123], v[100:103], v[188:191], v[120:123]
	v_mfma_f32_16x16x32_bf16 v[112:115], v[92:95], v[192:195], v[112:115]
	v_mfma_f32_16x16x32_bf16 v[112:115], v[100:103], v[212:215], v[112:115]
	v_mfma_f32_16x16x32_bf16 v[136:139], v[132:135], v[148:151], v[136:139]
	v_mfma_f32_16x16x32_bf16 v[136:139], v[144:147], v[152:155], v[136:139]
	v_mfma_f32_16x16x32_bf16 v[124:127], v[132:135], v[176:179], v[124:127]
	v_mfma_f32_16x16x32_bf16 v[124:127], v[144:147], v[180:183], v[124:127]
	v_mfma_f32_16x16x32_bf16 v[116:119], v[132:135], v[184:187], v[116:119]
	v_mfma_f32_16x16x32_bf16 v[116:119], v[144:147], v[188:191], v[116:119]
	v_mfma_f32_16x16x32_bf16 v[108:111], v[132:135], v[192:195], v[108:111]
	v_mfma_f32_16x16x32_bf16 v[108:111], v[144:147], v[212:215], v[108:111]
	s_barrier
	s_setprio 0
	s_add_i32 s10, 0, 0x1c000
	s_add_i32 s11, s44, s29
	v_add_u32_e32 v2, s10, v167
	s_mov_b32 m0, s11
	ds_read_b128 v[216:219], v2
	ds_read_b128 v[220:223], v2 offset:1024
	ds_read_b128 v[224:227], v2 offset:2048
	ds_read_b128 v[228:231], v2 offset:3072
	global_load_lds_dwordx4 v158, s[98:99]
	s_add_i32 m0, s11, 0x2000
	s_nop 0
	global_load_lds_dwordx4 v0, s[98:99]
	s_mov_b32 m0, s37
	s_waitcnt lgkmcnt(2)
	s_setprio 1
	s_barrier
	v_mfma_f32_16x16x32_bf16 v[64:67], v[216:219], v[148:151], v[64:67]
	v_mfma_f32_16x16x32_bf16 v[64:67], v[220:223], v[152:155], v[64:67]
	s_waitcnt lgkmcnt(0)
	v_mfma_f32_16x16x32_bf16 v[56:59], v[216:219], v[176:179], v[56:59]
	v_mfma_f32_16x16x32_bf16 v[56:59], v[220:223], v[180:183], v[56:59]
	v_mfma_f32_16x16x32_bf16 v[48:51], v[216:219], v[184:187], v[48:51]
	v_mfma_f32_16x16x32_bf16 v[48:51], v[220:223], v[188:191], v[48:51]
	v_mfma_f32_16x16x32_bf16 v[40:43], v[216:219], v[192:195], v[40:43]
	v_mfma_f32_16x16x32_bf16 v[40:43], v[220:223], v[212:215], v[40:43]
	v_mfma_f32_16x16x32_bf16 v[60:63], v[224:227], v[148:151], v[60:63]
	v_mfma_f32_16x16x32_bf16 v[60:63], v[228:231], v[152:155], v[60:63]
	v_mfma_f32_16x16x32_bf16 v[52:55], v[224:227], v[176:179], v[52:55]
	v_mfma_f32_16x16x32_bf16 v[52:55], v[228:231], v[180:183], v[52:55]
	v_mfma_f32_16x16x32_bf16 v[44:47], v[224:227], v[184:187], v[44:47]
	v_mfma_f32_16x16x32_bf16 v[44:47], v[228:231], v[188:191], v[44:47]
	v_mfma_f32_16x16x32_bf16 v[36:39], v[224:227], v[192:195], v[36:39]
	v_mfma_f32_16x16x32_bf16 v[36:39], v[228:231], v[212:215], v[36:39]
	s_barrier
	s_setprio 0
	ds_read_b128 v[148:151], v169 offset:49152
	ds_read_b128 v[152:155], v169 offset:50176
	ds_read_b128 v[176:179], v169 offset:51200
	ds_read_b128 v[180:183], v169 offset:52224
	ds_read_b128 v[184:187], v169 offset:53248
	ds_read_b128 v[188:191], v169 offset:54272
	ds_read_b128 v[192:195], v169 offset:55296
	ds_read_b128 v[212:215], v169 offset:56320
	global_load_lds_dwordx4 v160, s[100:101]
	s_mov_b32 m0, s38
	s_nop 0
	global_load_lds_dwordx4 v156, s[100:101]
	s_waitcnt lgkmcnt(6)
	s_setprio 1
	s_barrier
; #define PG8_WAIT_V(n) asm volatile("s_waitcnt vmcnt(" #n ")" ::: "memory")
; #define PG8_WAIT_L(n) asm volatile("s_waitcnt lgkmcnt(" #n ")" ::: "memory")
; #define PG8_BAR __builtin_amdgcn_s_barrier()
; #define PG8_SCHED __builtin_amdgcn_sched_barrier(0)
; template <class Epi, class AddrA, class AddrB>
; __device__ __forceinline__ void gemm_phase(const Sched S, const int lda, const int ldb, const int K, const AddrA addrA,
;                                            const AddrB addrB, const Epi E) {
;     ...
;     for (int t = 0; t < nt; t += 2) {
;       const bool last = (t == nt - 2);
;       const char* a1 = cA + (size_t)(t + 1) * kstep;
;       const char* a2 = last ? nA : cA + (size_t)(t + 2) * kstep;
;       const char* b2 = last ? nB : cB + (size_t)(t + 2) * kstep;
;       const char* a3 = a2 + kstep;
;       const char* b3 = b2 + kstep;
;       PG8_LDB(B0, 0, 0); PG8_SCHED; PG8_LDA(At, 0, 0); PG8_STAGE(PG8_SA(1, 1), a1 + hstepA, voffA);
;       PG8_WAIT_L(8); PG8_BAR; PG8_WAIT_L(0); PG8_MMA(0, 0, At, B0); PG8_BAR; PG8_SCHED;
;       PG8_LDB(B1, 0, 1); PG8_STAGE(PG8_SB(0, 0), b2, voffB);
;       PG8_BAR; PG8_WAIT_L(0); PG8_MMA(0, 1, At, B1); PG8_BAR;
;       PG8_LDA(At, 0, 1); PG8_STAGE(PG8_SA(0, 0), a2, voffA);
;       PG8_BAR; PG8_WAIT_L(0); PG8_MMA(1, 0, At, B0); PG8_BAR; PG8_SCHED;
;       PG8_STAGE(PG8_SB(0, 1), b2 + hstepB, voffB);
;       PG8_WAIT_V(6); PG8_BAR; PG8_MMA(1, 1, At, B1); PG8_BAR;
;       PG8_LDB(B0, 1, 0); PG8_SCHED; PG8_LDA(At, 1, 0); PG8_STAGE(PG8_SA(0, 1), a2 + hstepA, voffA);
;       PG8_WAIT_L(8); PG8_BAR; PG8_WAIT_L(0); PG8_MMA(0, 0, At, B0); PG8_BAR; PG8_SCHED;
;       PG8_LDB(B1, 1, 1); PG8_STAGE(PG8_SB(1, 0), b3, voffB);
;       PG8_BAR; PG8_WAIT_L(0); PG8_MMA(0, 1, At, B1); PG8_BAR;
;       PG8_LDA(At, 1, 1); PG8_STAGE(PG8_SA(1, 0), a3, voffA);
;       PG8_BAR; PG8_WAIT_L(0); PG8_MMA(1, 0, At, B0); PG8_BAR; PG8_SCHED;
;       PG8_STAGE(PG8_SB(1, 1), b3 + hstepB, voffB);
;       PG8_WAIT_V(6); PG8_BAR; PG8_MMA(1, 1, At, B1); PG8_BAR;
	v_mfma_f32_16x16x32_bf16 v[104:107], v[92:95], v[148:151], v[104:107]
	v_mfma_f32_16x16x32_bf16 v[104:107], v[100:103], v[152:155], v[104:107]
	s_waitcnt lgkmcnt(0)
	v_mfma_f32_16x16x32_bf16 v[88:91], v[92:95], v[176:179], v[88:91]
	v_mfma_f32_16x16x32_bf16 v[88:91], v[100:103], v[180:183], v[88:91]
	v_mfma_f32_16x16x32_bf16 v[80:83], v[92:95], v[184:187], v[80:83]
	v_mfma_f32_16x16x32_bf16 v[80:83], v[100:103], v[188:191], v[80:83]
	v_mfma_f32_16x16x32_bf16 v[72:75], v[92:95], v[192:195], v[72:75]
	v_mfma_f32_16x16x32_bf16 v[72:75], v[100:103], v[212:215], v[72:75]
	v_mfma_f32_16x16x32_bf16 v[96:99], v[132:135], v[148:151], v[96:99]
	v_mfma_f32_16x16x32_bf16 v[96:99], v[144:147], v[152:155], v[96:99]
	v_mfma_f32_16x16x32_bf16 v[84:87], v[132:135], v[176:179], v[84:87]
	v_mfma_f32_16x16x32_bf16 v[84:87], v[144:147], v[180:183], v[84:87]
	v_mfma_f32_16x16x32_bf16 v[76:79], v[132:135], v[184:187], v[76:79]
	v_mfma_f32_16x16x32_bf16 v[76:79], v[144:147], v[188:191], v[76:79]
	v_mfma_f32_16x16x32_bf16 v[68:71], v[132:135], v[192:195], v[68:71]
	v_mfma_f32_16x16x32_bf16 v[68:71], v[144:147], v[212:215], v[68:71]
	s_barrier
	s_setprio 0
	s_add_u32 s6, s6, 0x20080
	s_addc_u32 s7, s7, 0
	s_add_i32 s10, s10, s29
	s_mov_b32 m0, s10
	s_nop 0
	global_load_lds_dwordx4 v158, s[6:7]
	s_add_i32 m0, s10, 0x2000
	s_nop 0
	global_load_lds_dwordx4 v0, s[6:7]
	s_add_i32 s43, s43, 2
	s_add_u32 s41, s41, 0x100
	s_addc_u32 s42, s42, 0
	s_add_u32 s4, s4, 0x100
	s_addc_u32 s5, s5, 0
	s_waitcnt vmcnt(6)
	s_setprio 1
	s_barrier
	v_mfma_f32_16x16x32_bf16 v[32:35], v[216:219], v[148:151], v[32:35]
	v_mfma_f32_16x16x32_bf16 v[32:35], v[220:223], v[152:155], v[32:35]
	v_mfma_f32_16x16x32_bf16 v[24:27], v[216:219], v[176:179], v[24:27]
	v_mfma_f32_16x16x32_bf16 v[24:27], v[220:223], v[180:183], v[24:27]
	v_mfma_f32_16x16x32_bf16 v[16:19], v[216:219], v[184:187], v[16:19]
	v_mfma_f32_16x16x32_bf16 v[16:19], v[220:223], v[188:191], v[16:19]
	v_mfma_f32_16x16x32_bf16 v[8:11], v[216:219], v[192:195], v[8:11]
	v_mfma_f32_16x16x32_bf16 v[8:11], v[220:223], v[212:215], v[8:11]
	v_mfma_f32_16x16x32_bf16 v[28:31], v[224:227], v[148:151], v[28:31]
	v_mfma_f32_16x16x32_bf16 v[28:31], v[228:231], v[152:155], v[28:31]
	v_mfma_f32_16x16x32_bf16 v[20:23], v[224:227], v[176:179], v[20:23]
	v_mfma_f32_16x16x32_bf16 v[20:23], v[228:231], v[180:183], v[20:23]
	v_mfma_f32_16x16x32_bf16 v[12:15], v[224:227], v[184:187], v[12:15]
	v_mfma_f32_16x16x32_bf16 v[12:15], v[228:231], v[188:191], v[12:15]
	v_mfma_f32_16x16x32_bf16 v[4:7], v[224:227], v[192:195], v[4:7]
	v_mfma_f32_16x16x32_bf16 v[4:7], v[228:231], v[212:215], v[4:7]
	s_barrier
	s_setprio 0
	s_cmp_gt_u32 s43, 5
.LBB0_485:
	s_add_i32 s44, 0, 0x10000
	v_add_u32_e32 v2, s44, v167
	ds_read_b128 v[92:95], v2
	ds_read_b128 v[100:103], v2 offset:1024
	ds_read_b128 v[132:135], v2 offset:2048
	ds_read_b128 v[144:147], v2 offset:3072
	s_add_i32 m0, s30, 0xc000
	ds_read_b128 v[148:151], v169
	ds_read_b128 v[152:155], v169 offset:1024
	ds_read_b128 v[176:179], v169 offset:2048
	ds_read_b128 v[180:183], v169 offset:3072
	ds_read_b128 v[184:187], v169 offset:4096
	ds_read_b128 v[188:191], v169 offset:5120
	ds_read_b128 v[192:195], v169 offset:6144
	ds_read_b128 v[212:215], v169 offset:7168
	global_load_lds_dwordx4 v172, s[4:5]
	s_add_i32 m0, s30, 0xe000
	s_nop 0
	global_load_lds_dwordx4 v170, s[4:5]
	s_waitcnt lgkmcnt(6)
	s_setprio 1
	s_barrier
	v_mfma_f32_16x16x32_bf16 v[140:143], v[92:95], v[148:151], v[140:143]
	v_mfma_f32_16x16x32_bf16 v[140:143], v[100:103], v[152:155], v[140:143]
	s_waitcnt lgkmcnt(0)
	v_mfma_f32_16x16x32_bf16 v[128:131], v[92:95], v[176:179], v[128:131]
	v_mfma_f32_16x16x32_bf16 v[128:131], v[100:103], v[180:183], v[128:131]
	v_mfma_f32_16x16x32_bf16 v[120:123], v[92:95], v[184:187], v[120:123]
	v_mfma_f32_16x16x32_bf16 v[120:123], v[100:103], v[188:191], v[120:123]
	v_mfma_f32_16x16x32_bf16 v[112:115], v[92:95], v[192:195], v[112:115]
	v_mfma_f32_16x16x32_bf16 v[112:115], v[100:103], v[212:215], v[112:115]
	v_mfma_f32_16x16x32_bf16 v[136:139], v[132:135], v[148:151], v[136:139]
	v_mfma_f32_16x16x32_bf16 v[136:139], v[144:147], v[152:155], v[136:139]
	v_mfma_f32_16x16x32_bf16 v[124:127], v[132:135], v[176:179], v[124:127]
	v_mfma_f32_16x16x32_bf16 v[124:127], v[144:147], v[180:183], v[124:127]
	v_mfma_f32_16x16x32_bf16 v[116:119], v[132:135], v[184:187], v[116:119]
	v_mfma_f32_16x16x32_bf16 v[116:119], v[144:147], v[188:191], v[116:119]
	v_mfma_f32_16x16x32_bf16 v[108:111], v[132:135], v[192:195], v[108:111]
	v_mfma_f32_16x16x32_bf16 v[108:111], v[144:147], v[212:215], v[108:111]
	s_barrier
	s_setprio 0
	s_add_u32 s6, s4, 0xfff80080
	s_addc_u32 s7, s5, -1
	s_cmp_eq_u32 s43, 4
	s_cselect_b32 s11, s3, s7
	s_cselect_b32 s10, s15, s6
	s_cselect_b32 s7, s17, s42
	s_cselect_b32 s6, s40, s41
	s_add_i32 s46, 0, 0x14000
	s_add_i32 s44, s44, s29
	v_add_u32_e32 v2, s46, v167
	s_add_u32 s98, s6, 0x80
	s_addc_u32 s99, s7, 0
	s_mov_b32 m0, s44
	ds_read_b128 v[216:219], v2
	ds_read_b128 v[220:223], v2 offset:1024
	ds_read_b128 v[224:227], v2 offset:2048
	ds_read_b128 v[228:231], v2 offset:3072
	global_load_lds_dwordx4 v158, s[6:7]
	s_add_i32 m0, s44, 0x2000
	s_nop 0
	global_load_lds_dwordx4 v0, s[6:7]
	s_mov_b32 m0, s30
	s_add_u32 s100, s10, 0x80
	s_addc_u32 s101, s11, 0
	s_waitcnt lgkmcnt(2)
	s_setprio 1
	s_barrier
; #define PG8_WAIT_V(n) asm volatile("s_waitcnt vmcnt(" #n ")" ::: "memory")
; #define PG8_WAIT_L(n) asm volatile("s_waitcnt lgkmcnt(" #n ")" ::: "memory")
; #define PG8_BAR __builtin_amdgcn_s_barrier()
; #define PG8_SCHED __builtin_amdgcn_sched_barrier(0)
; template <class Epi, class AddrA, class AddrB>
; __device__ __forceinline__ void gemm_phase(const Sched S, const int lda, const int ldb, const int K, const AddrA addrA,
;                                            const AddrB addrB, const Epi E) {
;     ...
;       PG8_LDB(B0, 0, 0); PG8_SCHED; PG8_LDA(At, 0, 0); PG8_STAGE(PG8_SA(1, 1), a1 + hstepA, voffA);
;       PG8_WAIT_L(8); PG8_BAR; PG8_WAIT_L(0); PG8_MMA(0, 0, At, B0); PG8_BAR; PG8_SCHED;
;       PG8_LDB(B1, 0, 1); PG8_STAGE(PG8_SB(0, 0), b2, voffB);
;       PG8_BAR; PG8_WAIT_L(0); PG8_MMA(0, 1, At, B1); PG8_BAR;
;       PG8_LDA(At, 0, 1); PG8_STAGE(PG8_SA(0, 0), a2, voffA);
;       PG8_BAR; PG8_WAIT_L(0); PG8_MMA(1, 0, At, B0); PG8_BAR; PG8_SCHED;
;       PG8_STAGE(PG8_SB(0, 1), b2 + hstepB, voffB);
;       PG8_WAIT_V(6); PG8_BAR; PG8_MMA(1, 1, At, B1); PG8_BAR;
;       PG8_LDB(B0, 1, 0); PG8_SCHED; PG8_LDA(At, 1, 0); PG8_STAGE(PG8_SA(0, 1), a2 + hstepA, voffA);
;       PG8_WAIT_L(8); PG8_BAR; PG8_WAIT_L(0); PG8_MMA(0, 0, At, B0); PG8_BAR; PG8_SCHED;
;       PG8_LDB(B1, 1, 1); PG8_STAGE(PG8_SB(1, 0), b3, voffB);
;       PG8_BAR; PG8_WAIT_L(0); PG8_MMA(0, 1, At, B1); PG8_BAR;
;       PG8_LDA(At, 1, 1); PG8_STAGE(PG8_SA(1, 0), a3, voffA);
;       PG8_BAR; PG8_WAIT_L(0); PG8_MMA(1, 0, At, B0); PG8_BAR; PG8_SCHED;
;       PG8_STAGE(PG8_SB(1, 1), b3 + hstepB, voffB);
;       PG8_WAIT_V(6); PG8_BAR; PG8_MMA(1, 1, At, B1); PG8_BAR;
	v_mfma_f32_16x16x32_bf16 v[64:67], v[216:219], v[148:151], v[64:67]
	v_mfma_f32_16x16x32_bf16 v[64:67], v[220:223], v[152:155], v[64:67]
	s_waitcnt lgkmcnt(0)
	v_mfma_f32_16x16x32_bf16 v[56:59], v[216:219], v[176:179], v[56:59]
	v_mfma_f32_16x16x32_bf16 v[56:59], v[220:223], v[180:183], v[56:59]
	v_mfma_f32_16x16x32_bf16 v[48:51], v[216:219], v[184:187], v[48:51]
	v_mfma_f32_16x16x32_bf16 v[48:51], v[220:223], v[188:191], v[48:51]
	v_mfma_f32_16x16x32_bf16 v[40:43], v[216:219], v[192:195], v[40:43]
	v_mfma_f32_16x16x32_bf16 v[40:43], v[220:223], v[212:215], v[40:43]
	v_mfma_f32_16x16x32_bf16 v[60:63], v[224:227], v[148:151], v[60:63]
	v_mfma_f32_16x16x32_bf16 v[60:63], v[228:231], v[152:155], v[60:63]
	v_mfma_f32_16x16x32_bf16 v[52:55], v[224:227], v[176:179], v[52:55]
	v_mfma_f32_16x16x32_bf16 v[52:55], v[228:231], v[180:183], v[52:55]
	v_mfma_f32_16x16x32_bf16 v[44:47], v[224:227], v[184:187], v[44:47]
	v_mfma_f32_16x16x32_bf16 v[44:47], v[228:231], v[188:191], v[44:47]
	v_mfma_f32_16x16x32_bf16 v[36:39], v[224:227], v[192:195], v[36:39]
	v_mfma_f32_16x16x32_bf16 v[36:39], v[228:231], v[212:215], v[36:39]
	s_barrier
	s_setprio 0
	ds_read_b128 v[148:151], v169 offset:16384
	ds_read_b128 v[152:155], v169 offset:17408
	ds_read_b128 v[176:179], v169 offset:18432
	ds_read_b128 v[180:183], v169 offset:19456
	ds_read_b128 v[184:187], v169 offset:20480
	ds_read_b128 v[188:191], v169 offset:21504
	ds_read_b128 v[192:195], v169 offset:22528
	ds_read_b128 v[212:215], v169 offset:23552
	global_load_lds_dwordx4 v160, s[10:11]
	s_mov_b32 m0, s31
	s_nop 0
	global_load_lds_dwordx4 v156, s[10:11]
	s_waitcnt lgkmcnt(6)
	s_setprio 1
	s_barrier
	v_mfma_f32_16x16x32_bf16 v[104:107], v[92:95], v[148:151], v[104:107]
	v_mfma_f32_16x16x32_bf16 v[104:107], v[100:103], v[152:155], v[104:107]
	s_waitcnt lgkmcnt(0)
	v_mfma_f32_16x16x32_bf16 v[88:91], v[92:95], v[176:179], v[88:91]
	v_mfma_f32_16x16x32_bf16 v[88:91], v[100:103], v[180:183], v[88:91]
	v_mfma_f32_16x16x32_bf16 v[80:83], v[92:95], v[184:187], v[80:83]
	v_mfma_f32_16x16x32_bf16 v[80:83], v[100:103], v[188:191], v[80:83]
	v_mfma_f32_16x16x32_bf16 v[72:75], v[92:95], v[192:195], v[72:75]
	v_mfma_f32_16x16x32_bf16 v[72:75], v[100:103], v[212:215], v[72:75]
	v_mfma_f32_16x16x32_bf16 v[96:99], v[132:135], v[148:151], v[96:99]
	v_mfma_f32_16x16x32_bf16 v[96:99], v[144:147], v[152:155], v[96:99]
	v_mfma_f32_16x16x32_bf16 v[84:87], v[132:135], v[176:179], v[84:87]
	v_mfma_f32_16x16x32_bf16 v[84:87], v[144:147], v[180:183], v[84:87]
	v_mfma_f32_16x16x32_bf16 v[76:79], v[132:135], v[184:187], v[76:79]
	v_mfma_f32_16x16x32_bf16 v[76:79], v[144:147], v[188:191], v[76:79]
	v_mfma_f32_16x16x32_bf16 v[68:71], v[132:135], v[192:195], v[68:71]
	v_mfma_f32_16x16x32_bf16 v[68:71], v[144:147], v[212:215], v[68:71]
	s_barrier
	s_setprio 0
	s_add_u32 s44, s6, 0x20000
	s_addc_u32 s45, s7, 0
	s_add_i32 s46, s46, s29
	s_mov_b32 m0, s46
	s_nop 0
	global_load_lds_dwordx4 v158, s[44:45]
	s_add_i32 m0, s46, 0x2000
	s_nop 0
	global_load_lds_dwordx4 v0, s[44:45]
	s_add_i32 s44, 0, 0x18000
	v_add_u32_e32 v2, s44, v167
	s_waitcnt vmcnt(6)
	s_setprio 1
	s_barrier
	v_mfma_f32_16x16x32_bf16 v[32:35], v[216:219], v[148:151], v[32:35]
	v_mfma_f32_16x16x32_bf16 v[32:35], v[220:223], v[152:155], v[32:35]
	v_mfma_f32_16x16x32_bf16 v[24:27], v[216:219], v[176:179], v[24:27]
	v_mfma_f32_16x16x32_bf16 v[24:27], v[220:223], v[180:183], v[24:27]
	v_mfma_f32_16x16x32_bf16 v[16:19], v[216:219], v[184:187], v[16:19]
	v_mfma_f32_16x16x32_bf16 v[16:19], v[220:223], v[188:191], v[16:19]
	v_mfma_f32_16x16x32_bf16 v[8:11], v[216:219], v[192:195], v[8:11]
	v_mfma_f32_16x16x32_bf16 v[8:11], v[220:223], v[212:215], v[8:11]
	v_mfma_f32_16x16x32_bf16 v[28:31], v[224:227], v[148:151], v[28:31]
	v_mfma_f32_16x16x32_bf16 v[28:31], v[228:231], v[152:155], v[28:31]
	v_mfma_f32_16x16x32_bf16 v[20:23], v[224:227], v[176:179], v[20:23]
	v_mfma_f32_16x16x32_bf16 v[20:23], v[228:231], v[180:183], v[20:23]
	v_mfma_f32_16x16x32_bf16 v[12:15], v[224:227], v[184:187], v[12:15]
	v_mfma_f32_16x16x32_bf16 v[12:15], v[228:231], v[188:191], v[12:15]
	v_mfma_f32_16x16x32_bf16 v[4:7], v[224:227], v[192:195], v[4:7]
	v_mfma_f32_16x16x32_bf16 v[4:7], v[228:231], v[212:215], v[4:7]
	s_barrier
	s_setprio 0
	ds_read_b128 v[92:95], v2
	ds_read_b128 v[100:103], v2 offset:1024
	ds_read_b128 v[132:135], v2 offset:2048
	ds_read_b128 v[144:147], v2 offset:3072
	s_add_u32 s10, s10, 0x80000
	s_addc_u32 s11, s11, 0
	s_mov_b32 m0, s34
	ds_read_b128 v[148:151], v169 offset:32768
	ds_read_b128 v[152:155], v169 offset:33792
	ds_read_b128 v[176:179], v169 offset:34816
	ds_read_b128 v[180:183], v169 offset:35840
	ds_read_b128 v[184:187], v169 offset:36864
	ds_read_b128 v[188:191], v169 offset:37888
	ds_read_b128 v[192:195], v169 offset:38912
	ds_read_b128 v[212:215], v169 offset:39936
	global_load_lds_dwordx4 v160, s[10:11]
	s_mov_b32 m0, s35
	s_nop 0
	global_load_lds_dwordx4 v156, s[10:11]
	s_waitcnt lgkmcnt(6)
	s_setprio 1
	s_barrier
	v_mfma_f32_16x16x32_bf16 v[140:143], v[92:95], v[148:151], v[140:143]
	v_mfma_f32_16x16x32_bf16 v[140:143], v[100:103], v[152:155], v[140:143]
	s_waitcnt lgkmcnt(0)
	v_mfma_f32_16x16x32_bf16 v[128:131], v[92:95], v[176:179], v[128:131]
	v_mfma_f32_16x16x32_bf16 v[128:131], v[100:103], v[180:183], v[128:131]
	v_mfma_f32_16x16x32_bf16 v[120:123], v[92:95], v[184:187], v[120:123]
	v_mfma_f32_16x16x32_bf16 v[120:123], v[100:103], v[188:191], v[120:123]
	v_mfma_f32_16x16x32_bf16 v[112:115], v[92:95], v[192:195], v[112:115]
	v_mfma_f32_16x16x32_bf16 v[112:115], v[100:103], v[212:215], v[112:115]
	v_mfma_f32_16x16x32_bf16 v[136:139], v[132:135], v[148:151], v[136:139]
	v_mfma_f32_16x16x32_bf16 v[136:139], v[144:147], v[152:155], v[136:139]
	v_mfma_f32_16x16x32_bf16 v[124:127], v[132:135], v[176:179], v[124:127]
	v_mfma_f32_16x16x32_bf16 v[124:127], v[144:147], v[180:183], v[124:127]
	v_mfma_f32_16x16x32_bf16 v[116:119], v[132:135], v[184:187], v[116:119]
	v_mfma_f32_16x16x32_bf16 v[116:119], v[144:147], v[188:191], v[116:119]
	v_mfma_f32_16x16x32_bf16 v[108:111], v[132:135], v[192:195], v[108:111]
	v_mfma_f32_16x16x32_bf16 v[108:111], v[144:147], v[212:215], v[108:111]
	s_barrier
; #define PG8_WAIT_V(n) asm volatile("s_waitcnt vmcnt(" #n ")" ::: "memory")
; #define PG8_WAIT_L(n) asm volatile("s_waitcnt lgkmcnt(" #n ")" ::: "memory")
; #define PG8_BAR __builtin_amdgcn_s_barrier()
; #define PG8_SCHED __builtin_amdgcn_sched_barrier(0)
; template <class Epi, class AddrA, class AddrB>
; __device__ __forceinline__ void gemm_phase(const Sched S, const int lda, const int ldb, const int K, const AddrA addrA,
;                                            const AddrB addrB, const Epi E) {
;     ...
;       PG8_LDB(B0, 0, 0); PG8_SCHED; PG8_LDA(At, 0, 0); PG8_STAGE(PG8_SA(1, 1), a1 + hstepA, voffA);
;       PG8_WAIT_L(8); PG8_BAR; PG8_WAIT_L(0); PG8_MMA(0, 0, At, B0); PG8_BAR; PG8_SCHED;
;       PG8_LDB(B1, 0, 1); PG8_STAGE(PG8_SB(0, 0), b2, voffB);
;       PG8_BAR; PG8_WAIT_L(0); PG8_MMA(0, 1, At, B1); PG8_BAR;
;       PG8_LDA(At, 0, 1); PG8_STAGE(PG8_SA(0, 0), a2, voffA);
;       PG8_BAR; PG8_WAIT_L(0); PG8_MMA(1, 0, At, B0); PG8_BAR; PG8_SCHED;
;       PG8_STAGE(PG8_SB(0, 1), b2 + hstepB, voffB);
;       PG8_WAIT_V(6); PG8_BAR; PG8_MMA(1, 1, At, B1); PG8_BAR;
;       PG8_LDB(B0, 1, 0); PG8_SCHED; PG8_LDA(At, 1, 0); PG8_STAGE(PG8_SA(0, 1), a2 + hstepA, voffA);
;       PG8_WAIT_L(8); PG8_BAR; PG8_WAIT_L(0); PG8_MMA(0, 0, At, B0); PG8_BAR; PG8_SCHED;
;       PG8_LDB(B1, 1, 1); PG8_STAGE(PG8_SB(1, 0), b3, voffB);
;       PG8_BAR; PG8_WAIT_L(0); PG8_MMA(0, 1, At, B1); PG8_BAR;
;       PG8_LDA(At, 1, 1); PG8_STAGE(PG8_SA(1, 0), a3, voffA);
;       PG8_BAR; PG8_WAIT_L(0); PG8_MMA(1, 0, At, B0); PG8_BAR; PG8_SCHED;
;       PG8_STAGE(PG8_SB(1, 1), b3 + hstepB, voffB);
;       PG8_WAIT_V(6); PG8_BAR; PG8_MMA(1, 1, At, B1); PG8_BAR;
	s_setprio 0
	s_add_i32 s10, 0, 0x1c000
	s_add_i32 s11, s44, s29
	v_add_u32_e32 v2, s10, v167
	s_mov_b32 m0, s11
	ds_read_b128 v[216:219], v2
	ds_read_b128 v[220:223], v2 offset:1024
	ds_read_b128 v[224:227], v2 offset:2048
	ds_read_b128 v[228:231], v2 offset:3072
	global_load_lds_dwordx4 v158, s[98:99]
	s_add_i32 m0, s11, 0x2000
	s_nop 0
	global_load_lds_dwordx4 v0, s[98:99]
	s_mov_b32 m0, s37
	s_waitcnt lgkmcnt(2)
	s_setprio 1
	s_barrier
	v_mfma_f32_16x16x32_bf16 v[64:67], v[216:219], v[148:151], v[64:67]
	v_mfma_f32_16x16x32_bf16 v[64:67], v[220:223], v[152:155], v[64:67]
	s_waitcnt lgkmcnt(0)
	v_mfma_f32_16x16x32_bf16 v[56:59], v[216:219], v[176:179], v[56:59]
	v_mfma_f32_16x16x32_bf16 v[56:59], v[220:223], v[180:183], v[56:59]
	v_mfma_f32_16x16x32_bf16 v[48:51], v[216:219], v[184:187], v[48:51]
	v_mfma_f32_16x16x32_bf16 v[48:51], v[220:223], v[188:191], v[48:51]
	v_mfma_f32_16x16x32_bf16 v[40:43], v[216:219], v[192:195], v[40:43]
	v_mfma_f32_16x16x32_bf16 v[40:43], v[220:223], v[212:215], v[40:43]
	v_mfma_f32_16x16x32_bf16 v[60:63], v[224:227], v[148:151], v[60:63]
	v_mfma_f32_16x16x32_bf16 v[60:63], v[228:231], v[152:155], v[60:63]
	v_mfma_f32_16x16x32_bf16 v[52:55], v[224:227], v[176:179], v[52:55]
	v_mfma_f32_16x16x32_bf16 v[52:55], v[228:231], v[180:183], v[52:55]
	v_mfma_f32_16x16x32_bf16 v[44:47], v[224:227], v[184:187], v[44:47]
	v_mfma_f32_16x16x32_bf16 v[44:47], v[228:231], v[188:191], v[44:47]
	v_mfma_f32_16x16x32_bf16 v[36:39], v[224:227], v[192:195], v[36:39]
	v_mfma_f32_16x16x32_bf16 v[36:39], v[228:231], v[212:215], v[36:39]
	s_barrier
	s_setprio 0
	ds_read_b128 v[148:151], v169 offset:49152
	ds_read_b128 v[152:155], v169 offset:50176
	ds_read_b128 v[176:179], v169 offset:51200
	ds_read_b128 v[180:183], v169 offset:52224
	ds_read_b128 v[184:187], v169 offset:53248
	ds_read_b128 v[188:191], v169 offset:54272
	ds_read_b128 v[192:195], v169 offset:55296
	ds_read_b128 v[212:215], v169 offset:56320
	global_load_lds_dwordx4 v160, s[100:101]
	s_mov_b32 m0, s38
	s_nop 0
	global_load_lds_dwordx4 v156, s[100:101]
	s_waitcnt lgkmcnt(6)
	s_setprio 1
	s_barrier
	v_mfma_f32_16x16x32_bf16 v[104:107], v[92:95], v[148:151], v[104:107]
	v_mfma_f32_16x16x32_bf16 v[104:107], v[100:103], v[152:155], v[104:107]
	s_waitcnt lgkmcnt(0)
	v_mfma_f32_16x16x32_bf16 v[88:91], v[92:95], v[176:179], v[88:91]
	v_mfma_f32_16x16x32_bf16 v[88:91], v[100:103], v[180:183], v[88:91]
	v_mfma_f32_16x16x32_bf16 v[80:83], v[92:95], v[184:187], v[80:83]
	v_mfma_f32_16x16x32_bf16 v[80:83], v[100:103], v[188:191], v[80:83]
	v_mfma_f32_16x16x32_bf16 v[72:75], v[92:95], v[192:195], v[72:75]
	v_mfma_f32_16x16x32_bf16 v[72:75], v[100:103], v[212:215], v[72:75]
	v_mfma_f32_16x16x32_bf16 v[96:99], v[132:135], v[148:151], v[96:99]
	v_mfma_f32_16x16x32_bf16 v[96:99], v[144:147], v[152:155], v[96:99]
	v_mfma_f32_16x16x32_bf16 v[84:87], v[132:135], v[176:179], v[84:87]
	v_mfma_f32_16x16x32_bf16 v[84:87], v[144:147], v[180:183], v[84:87]
	v_mfma_f32_16x16x32_bf16 v[76:79], v[132:135], v[184:187], v[76:79]
	v_mfma_f32_16x16x32_bf16 v[76:79], v[144:147], v[188:191], v[76:79]
	v_mfma_f32_16x16x32_bf16 v[68:71], v[132:135], v[192:195], v[68:71]
	v_mfma_f32_16x16x32_bf16 v[68:71], v[144:147], v[212:215], v[68:71]
	s_barrier
	s_setprio 0
	s_add_u32 s6, s6, 0x20080
	s_addc_u32 s7, s7, 0
	s_add_i32 s10, s10, s29
	s_mov_b32 m0, s10
	s_nop 0
	global_load_lds_dwordx4 v158, s[6:7]
	s_add_i32 m0, s10, 0x2000
	s_nop 0
	global_load_lds_dwordx4 v0, s[6:7]
	s_add_i32 s43, s43, 2
	s_add_u32 s41, s41, 0x100
	s_addc_u32 s42, s42, 0
	s_add_u32 s4, s4, 0x100
	s_addc_u32 s5, s5, 0
	s_waitcnt vmcnt(6)
	s_setprio 1
	s_barrier
	v_mfma_f32_16x16x32_bf16 v[32:35], v[216:219], v[148:151], v[32:35]
	v_mfma_f32_16x16x32_bf16 v[32:35], v[220:223], v[152:155], v[32:35]
	v_mfma_f32_16x16x32_bf16 v[24:27], v[216:219], v[176:179], v[24:27]
	v_mfma_f32_16x16x32_bf16 v[24:27], v[220:223], v[180:183], v[24:27]
	v_mfma_f32_16x16x32_bf16 v[16:19], v[216:219], v[184:187], v[16:19]
	v_mfma_f32_16x16x32_bf16 v[16:19], v[220:223], v[188:191], v[16:19]
	v_mfma_f32_16x16x32_bf16 v[8:11], v[216:219], v[192:195], v[8:11]
	v_mfma_f32_16x16x32_bf16 v[8:11], v[220:223], v[212:215], v[8:11]
	v_mfma_f32_16x16x32_bf16 v[28:31], v[224:227], v[148:151], v[28:31]
	v_mfma_f32_16x16x32_bf16 v[28:31], v[228:231], v[152:155], v[28:31]
	v_mfma_f32_16x16x32_bf16 v[20:23], v[224:227], v[176:179], v[20:23]
	v_mfma_f32_16x16x32_bf16 v[20:23], v[228:231], v[180:183], v[20:23]
	v_mfma_f32_16x16x32_bf16 v[12:15], v[224:227], v[184:187], v[12:15]
	v_mfma_f32_16x16x32_bf16 v[12:15], v[228:231], v[188:191], v[12:15]
	v_mfma_f32_16x16x32_bf16 v[4:7], v[224:227], v[192:195], v[4:7]
	v_mfma_f32_16x16x32_bf16 v[4:7], v[228:231], v[212:215], v[4:7]
	s_barrier
	s_setprio 0
	s_cmp_gt_u32 s43, 5
	s_cbranch_scc0 .LBB0_485
; __device__ __forceinline__ size_t pidx(size_t row, int col) { return ((size_t)(col >> 8) * MTOK + row) * PLD + (col & 255); }
; __device__ __forceinline__ float bflo(unsigned v) { return __uint_as_float(v << 16); }
; __device__ __forceinline__ float bfhi(unsigned v) { return __uint_as_float(v & 0xffff0000u); }
; __device__ __forceinline__ float siluf_(float x) { return x * __builtin_amdgcn_rcpf(1.0f + __expf(-x)); }
;   __device__ __forceinline__ void operator()(EPI_ARGS) const {
;     const size_t row0 = (size_t)u.pm * 256 + wr * 64 + fr;
;     const int col0 = u.pn * 256 + wc * 32 + 8 * fq;
; #pragma unroll
;     for (int bj = 0; bj < 2; ++bj) {
;       const int c = col0 + bj * HALF;
;       const f32x4 s0 = *(const f32x4*)(psc + c), s1 = *(const f32x4*)(psc + c + 4);
; #pragma unroll
;       for (int ai = 0; ai < 2; ++ai) {
;         u32x4 z[4];
; #pragma unroll
;         for (int m = 0; m < 4; ++m) z[m] = *(const u32x4*)(proj + pidx(row0 + ai * HALF + m * 16, PZ + c));
;         __builtin_amdgcn_sched_barrier(0);
; #pragma unroll
;         for (int m = 0; m < 4; ++m) {
;           const size_t row = row0 + ai * HALF + m * 16;
;           const f32x4 v0 = acc[ai][bj][m][0], v1 = acc[ai][bj][m][1];
;           u32x4 o;
;           o.x = pack2(v0[0] * s0[0] * siluf_(bflo(z[m].x)), v0[1] * s0[1] * siluf_(bfhi(z[m].x)));
;           o.y = pack2(v0[2] * s0[2] * siluf_(bflo(z[m].y)), v0[3] * s0[3] * siluf_(bfhi(z[m].y)));
;           o.z = pack2(v1[0] * s1[0] * siluf_(bflo(z[m].z)), v1[1] * s1[1] * siluf_(bfhi(z[m].z)));
;           o.w = pack2(v1[2] * s1[2] * siluf_(bflo(z[m].w)), v1[3] * s1[3] * siluf_(bfhi(z[m].w)));
;           *(u32x4*)(y0 + row * DM + c) = o;
	s_ashr_i32 s3, s2, 31
	s_lshl_b64 s[2:3], s[2:3], 8
	v_lshl_add_u64 v[186:187], s[2:3], 0, v[162:163]
	s_lshl_b32 s2, s33, 8
	v_or_b32_e32 v196, s2, v168
	s_addk_i32 s2, 0x800
	s_ashr_i32 s2, s2, 8
	s_ashr_i32 s3, s2, 31
	s_lshl_b64 s[2:3], s[2:3], 23
	s_add_u32 s2, s0, s2
	s_addc_u32 s3, s1, s3
	v_lshlrev_b32_e32 v2, 1, v168
	v_or_b32_e32 v194, 16, v186
	v_mov_b32_e32 v195, v187
	v_ashrrev_i32_e32 v197, 31, v196
	v_lshl_add_u64 v[188:189], s[2:3], 0, v[2:3]
	v_lshlrev_b64 v[178:179], 9, v[186:187]
	v_lshlrev_b64 v[180:181], 9, v[194:195]
	v_or_b32_e32 v192, 32, v186
	v_mov_b32_e32 v193, v187
	v_or_b32_e32 v190, 48, v186
	v_mov_b32_e32 v191, v187
	v_lshl_add_u64 v[176:177], v[196:197], 2, s[12:13]
	v_lshl_add_u64 v[132:133], v[188:189], 0, v[178:179]
	v_lshl_add_u64 v[134:135], v[188:189], 0, v[180:181]
	v_lshlrev_b64 v[182:183], 9, v[192:193]
	v_lshlrev_b64 v[184:185], 9, v[190:191]
	global_load_dwordx4 v[92:95], v[176:177], off offset:16
	global_load_dwordx4 v[100:103], v[176:177], off
	flat_load_dwordx4 v[152:155], v[132:133]
	flat_load_dwordx4 v[148:151], v[134:135]
	v_lshl_add_u64 v[132:133], v[188:189], 0, v[182:183]
	v_lshl_add_u64 v[134:135], v[188:189], 0, v[184:185]
	flat_load_dwordx4 v[144:147], v[132:133]
	s_nop 0
	flat_load_dwordx4 v[132:135], v[134:135]
	s_waitcnt vmcnt(0) lgkmcnt(0)
	v_lshlrev_b32_e32 v213, 16, v152
	v_mul_f32_e32 v2, 0xbfb8aa3b, v213
	v_exp_f32_e32 v2, v2
	v_mov_b32_e32 v214, v140
	v_mov_b32_e32 v212, v100
	s_mov_b64 s[4:5], 0x90
	v_add_f32_e32 v2, 1.0, v2
	v_rcp_f32_e32 v215, v2
	s_nop 0
	v_pk_mul_f32 v[212:213], v[214:215], v[212:213]
	s_nop 0
	v_mul_f32_e32 v2, v212, v213
	v_and_b32_e32 v213, 0xffff0000, v152
	v_mul_f32_e32 v140, 0xbfb8aa3b, v213
	v_exp_f32_e32 v140, v140
	v_mov_b32_e32 v214, v141
	v_mov_b32_e32 v212, v101
	v_add_f32_e32 v140, 1.0, v140
	v_rcp_f32_e32 v215, v140
	s_nop 0
	v_pk_mul_f32 v[140:141], v[214:215], v[212:213]
	s_nop 0
	v_mul_f32_e32 v140, v140, v141
	v_lshlrev_b32_e32 v141, 16, v153
	v_cvt_pk_bf16_f32 v152, v2, v140
	v_mul_f32_e32 v2, 0xbfb8aa3b, v141
	v_exp_f32_e32 v2, v2
	v_mov_b32_e32 v212, v142
	v_mov_b32_e32 v140, v102
	v_mov_b32_e32 v142, v136
	v_add_f32_e32 v2, 1.0, v2
	v_rcp_f32_e32 v213, v2
	s_nop 0
	v_pk_mul_f32 v[140:141], v[212:213], v[140:141]
	s_nop 0
	v_mul_f32_e32 v2, v140, v141
	v_and_b32_e32 v141, 0xffff0000, v153
	v_mul_f32_e32 v140, 0xbfb8aa3b, v141
	v_exp_f32_e32 v140, v140
	v_mov_b32_e32 v212, v143
	v_add_f32_e32 v140, 1.0, v140
	v_rcp_f32_e32 v213, v140
	v_mov_b32_e32 v140, v103
	v_pk_mul_f32 v[140:141], v[212:213], v[140:141]
	s_nop 0
	v_mul_f32_e32 v140, v140, v141
	v_lshlrev_b32_e32 v141, 16, v154
	v_cvt_pk_bf16_f32 v153, v2, v140
	v_mul_f32_e32 v2, 0xbfb8aa3b, v141
	v_exp_f32_e32 v2, v2
	v_mov_b32_e32 v140, v92
	v_add_f32_e32 v2, 1.0, v2
	v_rcp_f32_e32 v143, v2
	s_nop 0
	v_pk_mul_f32 v[140:141], v[142:143], v[140:141]
	s_nop 0
	v_mul_f32_e32 v2, v140, v141
	v_and_b32_e32 v141, 0xffff0000, v154
	v_mul_f32_e32 v136, 0xbfb8aa3b, v141
	v_exp_f32_e32 v136, v136
	v_mov_b32_e32 v142, v137
	v_mov_b32_e32 v140, v93
	v_add_f32_e32 v136, 1.0, v136
	v_rcp_f32_e32 v143, v136
	s_nop 0
	v_pk_mul_f32 v[136:137], v[142:143], v[140:141]
	s_nop 0
	v_mul_f32_e32 v136, v136, v137
	v_lshlrev_b32_e32 v137, 16, v155
	v_cvt_pk_bf16_f32 v154, v2, v136
	v_mul_f32_e32 v2, 0xbfb8aa3b, v137
	v_exp_f32_e32 v2, v2
	v_mov_b32_e32 v140, v138
	v_mov_b32_e32 v136, v94
	v_mov_b32_e32 v142, v128
	v_add_f32_e32 v2, 1.0, v2
	v_rcp_f32_e32 v141, v2
	v_mov_b32_e32 v138, v100
	v_pk_mul_f32 v[136:137], v[140:141], v[136:137]
	s_nop 0
	v_mul_f32_e32 v2, v136, v137
	v_and_b32_e32 v137, 0xffff0000, v155
	v_mul_f32_e32 v136, 0xbfb8aa3b, v137
	v_exp_f32_e32 v136, v136
	v_mov_b32_e32 v140, v139
	v_lshlrev_b32_e32 v139, 16, v148
	v_add_f32_e32 v136, 1.0, v136
	v_rcp_f32_e32 v141, v136
	v_mov_b32_e32 v136, v95
	v_pk_mul_f32 v[136:137], v[140:141], v[136:137]
	s_nop 0
	v_mul_f32_e32 v136, v136, v137
	v_cvt_pk_bf16_f32 v155, v2, v136
	v_mul_f32_e32 v2, 0xbfb8aa3b, v139
	v_exp_f32_e32 v2, v2
	v_lshlrev_b64 v[140:141], 1, v[196:197]
	v_lshlrev_b64 v[136:137], 12, v[186:187]
	v_lshl_add_u64 v[136:137], s[8:9], 0, v[136:137]
	v_add_f32_e32 v2, 1.0, v2
	v_rcp_f32_e32 v143, v2
	v_lshl_add_u64 v[136:137], v[136:137], 0, v[140:141]
	flat_store_dwordx4 v[136:137], v[152:155]
	v_pk_mul_f32 v[138:139], v[142:143], v[138:139]
	s_nop 0
	v_mul_f32_e32 v2, v138, v139
	v_and_b32_e32 v139, 0xffff0000, v148
	v_mul_f32_e32 v128, 0xbfb8aa3b, v139
	v_exp_f32_e32 v128, v128
	v_mov_b32_e32 v142, v129
	v_mov_b32_e32 v138, v101
	v_add_f32_e32 v128, 1.0, v128
	v_rcp_f32_e32 v143, v128
	s_nop 0
	v_pk_mul_f32 v[128:129], v[142:143], v[138:139]
	s_nop 0
	v_mul_f32_e32 v128, v128, v129
	v_lshlrev_b32_e32 v139, 16, v149
	v_cvt_pk_bf16_f32 v128, v2, v128
	v_mul_f32_e32 v2, 0xbfb8aa3b, v139
	v_exp_f32_e32 v2, v2
	v_mov_b32_e32 v142, v130
	v_mov_b32_e32 v138, v102
	v_add_f32_e32 v2, 1.0, v2
	v_rcp_f32_e32 v143, v2
	s_nop 0
	v_pk_mul_f32 v[138:139], v[142:143], v[138:139]
	s_nop 0
	v_mul_f32_e32 v2, v138, v139
	v_and_b32_e32 v139, 0xffff0000, v149
	v_mul_f32_e32 v129, 0xbfb8aa3b, v139
	v_exp_f32_e32 v129, v129
	v_mov_b32_e32 v142, v131
	v_mov_b32_e32 v138, v103
	v_lshl_add_u64 v[148:149], v[186:187], 0, s[52:53]
	v_add_f32_e32 v129, 1.0, v129
	v_rcp_f32_e32 v143, v129
	s_nop 0
	v_pk_mul_f32 v[130:131], v[142:143], v[138:139]
	s_nop 0
	v_mul_f32_e32 v129, v130, v131
	v_lshlrev_b32_e32 v131, 16, v150
	v_cvt_pk_bf16_f32 v129, v2, v129
	v_mul_f32_e32 v2, 0xbfb8aa3b, v131
	v_exp_f32_e32 v2, v2
	v_mov_b32_e32 v138, v124
	v_mov_b32_e32 v130, v92
	v_add_f32_e32 v2, 1.0, v2
	v_rcp_f32_e32 v139, v2
	s_nop 0
	v_pk_mul_f32 v[130:131], v[138:139], v[130:131]
; __device__ __forceinline__ size_t pidx(size_t row, int col) { return ((size_t)(col >> 8) * MTOK + row) * PLD + (col & 255); }
; __device__ __forceinline__ float bflo(unsigned v) { return __uint_as_float(v << 16); }
; __device__ __forceinline__ float bfhi(unsigned v) { return __uint_as_float(v & 0xffff0000u); }
; __device__ __forceinline__ float siluf_(float x) { return x * __builtin_amdgcn_rcpf(1.0f + __expf(-x)); }
;   __device__ __forceinline__ void operator()(EPI_ARGS) const {
;     ...
;       for (int ai = 0; ai < 2; ++ai) {
;         u32x4 z[4];
; #pragma unroll
;         for (int m = 0; m < 4; ++m) z[m] = *(const u32x4*)(proj + pidx(row0 + ai * HALF + m * 16, PZ + c));
;         __builtin_amdgcn_sched_barrier(0);
; #pragma unroll
;         for (int m = 0; m < 4; ++m) {
;           const size_t row = row0 + ai * HALF + m * 16;
;           const f32x4 v0 = acc[ai][bj][m][0], v1 = acc[ai][bj][m][1];
;           u32x4 o;
;           o.x = pack2(v0[0] * s0[0] * siluf_(bflo(z[m].x)), v0[1] * s0[1] * siluf_(bfhi(z[m].x)));
;           o.y = pack2(v0[2] * s0[2] * siluf_(bflo(z[m].y)), v0[3] * s0[3] * siluf_(bfhi(z[m].y)));
;           o.z = pack2(v1[0] * s1[0] * siluf_(bflo(z[m].z)), v1[1] * s1[1] * siluf_(bfhi(z[m].z)));
;           o.w = pack2(v1[2] * s1[2] * siluf_(bflo(z[m].w)), v1[3] * s1[3] * siluf_(bfhi(z[m].w)));
;           *(u32x4*)(y0 + row * DM + c) = o;
;         }
	s_nop 0
	v_mul_f32_e32 v2, v130, v131
	v_and_b32_e32 v131, 0xffff0000, v150
	v_mul_f32_e32 v124, 0xbfb8aa3b, v131
	v_exp_f32_e32 v124, v124
	v_mov_b32_e32 v138, v125
	v_mov_b32_e32 v130, v93
	v_add_f32_e32 v124, 1.0, v124
	v_rcp_f32_e32 v139, v124
	s_nop 0
	v_pk_mul_f32 v[124:125], v[138:139], v[130:131]
	s_nop 0
	v_mul_f32_e32 v124, v124, v125
	v_lshlrev_b32_e32 v125, 16, v151
	v_cvt_pk_bf16_f32 v130, v2, v124
	v_mul_f32_e32 v2, 0xbfb8aa3b, v125
	v_exp_f32_e32 v2, v2
	v_mov_b32_e32 v138, v126
	v_mov_b32_e32 v124, v94
	v_mov_b32_e32 v126, v100
	v_add_f32_e32 v2, 1.0, v2
	v_rcp_f32_e32 v139, v2
	s_nop 0
	v_pk_mul_f32 v[124:125], v[138:139], v[124:125]
	s_nop 0
	v_mul_f32_e32 v2, v124, v125
	v_and_b32_e32 v125, 0xffff0000, v151
	v_mul_f32_e32 v124, 0xbfb8aa3b, v125
	v_exp_f32_e32 v124, v124
	v_mov_b32_e32 v138, v127
	v_lshlrev_b32_e32 v127, 16, v144
	v_add_f32_e32 v124, 1.0, v124
	v_rcp_f32_e32 v139, v124
	v_mov_b32_e32 v124, v95
	v_pk_mul_f32 v[124:125], v[138:139], v[124:125]
	s_nop 0
	v_mul_f32_e32 v124, v124, v125
	v_cvt_pk_bf16_f32 v131, v2, v124
	v_mul_f32_e32 v2, 0xbfb8aa3b, v127
	v_exp_f32_e32 v2, v2
	v_lshlrev_b64 v[124:125], 12, v[194:195]
	v_lshl_add_u64 v[124:125], s[8:9], 0, v[124:125]
	v_lshl_add_u64 v[124:125], v[124:125], 0, v[140:141]
	v_add_f32_e32 v2, 1.0, v2
	flat_store_dwordx4 v[124:125], v[128:131]
	s_nop 1
	v_rcp_f32_e32 v129, v2
	v_mov_b32_e32 v128, v120
	v_lshlrev_b64 v[130:131], 9, v[148:149]
	v_pk_mul_f32 v[126:127], v[128:129], v[126:127]
	s_nop 0
	v_mul_f32_e32 v2, v126, v127
	v_and_b32_e32 v127, 0xffff0000, v144
	v_mul_f32_e32 v120, 0xbfb8aa3b, v127
	v_exp_f32_e32 v120, v120
	v_mov_b32_e32 v128, v121
	v_mov_b32_e32 v126, v101
	v_add_f32_e32 v120, 1.0, v120
	v_rcp_f32_e32 v129, v120
	s_nop 0
	v_pk_mul_f32 v[120:121], v[128:129], v[126:127]
	s_nop 0
	v_mul_f32_e32 v120, v120, v121
	v_lshlrev_b32_e32 v127, 16, v145
	v_cvt_pk_bf16_f32 v120, v2, v120
	v_mul_f32_e32 v2, 0xbfb8aa3b, v127
	v_exp_f32_e32 v2, v2
	v_mov_b32_e32 v128, v122
	v_mov_b32_e32 v126, v102
	v_add_f32_e32 v2, 1.0, v2
	v_rcp_f32_e32 v129, v2
	s_nop 0
	v_pk_mul_f32 v[126:127], v[128:129], v[126:127]
	s_nop 0
	v_mul_f32_e32 v2, v126, v127
	v_and_b32_e32 v127, 0xffff0000, v145
	v_mul_f32_e32 v121, 0xbfb8aa3b, v127
	v_exp_f32_e32 v121, v121
	v_mov_b32_e32 v128, v123
	v_mov_b32_e32 v126, v103
	v_add_f32_e32 v121, 1.0, v121
	v_rcp_f32_e32 v129, v121
	s_nop 0
	v_pk_mul_f32 v[122:123], v[128:129], v[126:127]
	s_nop 0
	v_mul_f32_e32 v121, v122, v123
	v_lshlrev_b32_e32 v123, 16, v146
	v_cvt_pk_bf16_f32 v121, v2, v121
	v_mul_f32_e32 v2, 0xbfb8aa3b, v123
	v_exp_f32_e32 v2, v2
	v_mov_b32_e32 v126, v116
	v_mov_b32_e32 v122, v92
	v_add_f32_e32 v2, 1.0, v2
	v_rcp_f32_e32 v127, v2
	s_nop 0
	v_pk_mul_f32 v[122:123], v[126:127], v[122:123]
	s_nop 0
	v_mul_f32_e32 v2, v122, v123
	v_and_b32_e32 v123, 0xffff0000, v146
	v_mul_f32_e32 v116, 0xbfb8aa3b, v123
	v_exp_f32_e32 v116, v116
	v_mov_b32_e32 v126, v117
	v_mov_b32_e32 v122, v93
	v_add_f32_e32 v116, 1.0, v116
	v_rcp_f32_e32 v127, v116
	s_nop 0
	v_pk_mul_f32 v[116:117], v[126:127], v[122:123]
	s_nop 0
	v_mul_f32_e32 v116, v116, v117
	v_lshlrev_b32_e32 v117, 16, v147
	v_cvt_pk_bf16_f32 v122, v2, v116
	v_mul_f32_e32 v2, 0xbfb8aa3b, v117
	v_exp_f32_e32 v2, v2
	v_mov_b32_e32 v126, v118
	v_mov_b32_e32 v116, v94
	v_mov_b32_e32 v118, v112
	v_add_f32_e32 v2, 1.0, v2
	v_rcp_f32_e32 v127, v2
	s_nop 0
	v_pk_mul_f32 v[116:117], v[126:127], v[116:117]
	s_nop 0
	v_mul_f32_e32 v2, v116, v117
	v_and_b32_e32 v117, 0xffff0000, v147
	v_mul_f32_e32 v116, 0xbfb8aa3b, v117
	v_exp_f32_e32 v116, v116
	v_mov_b32_e32 v126, v119
	v_lshl_add_u64 v[146:147], v[186:187], 0, s[4:5]
	s_mov_b64 s[4:5], 0xa0
	v_add_f32_e32 v116, 1.0, v116
	v_rcp_f32_e32 v127, v116
	v_mov_b32_e32 v116, v95
	v_lshl_add_u64 v[144:145], v[186:187], 0, s[4:5]
	s_mov_b64 s[4:5], 0xb0
	v_pk_mul_f32 v[116:117], v[126:127], v[116:117]
	v_lshl_add_u64 v[142:143], v[186:187], 0, s[4:5]
	v_mul_f32_e32 v116, v116, v117
	v_cvt_pk_bf16_f32 v123, v2, v116
	v_lshlrev_b64 v[116:117], 12, v[192:193]
	v_lshl_add_u64 v[116:117], s[8:9], 0, v[116:117]
	v_lshl_add_u64 v[128:129], v[116:117], 0, v[140:141]
	v_lshlrev_b32_e32 v117, 16, v132
	v_mul_f32_e32 v2, 0xbfb8aa3b, v117
	v_exp_f32_e32 v2, v2
	v_mov_b32_e32 v116, v100
	flat_store_dwordx4 v[128:129], v[120:123]
	v_lshlrev_b64 v[138:139], 9, v[142:143]
	v_add_f32_e32 v2, 1.0, v2
	v_rcp_f32_e32 v119, v2
	s_nop 0
	v_pk_mul_f32 v[116:117], v[118:119], v[116:117]
	s_nop 0
	v_mul_f32_e32 v2, v116, v117
	v_and_b32_e32 v117, 0xffff0000, v132
	v_mul_f32_e32 v112, 0xbfb8aa3b, v117
	v_exp_f32_e32 v112, v112
	v_mov_b32_e32 v118, v113
	v_mov_b32_e32 v116, v101
	v_add_f32_e32 v112, 1.0, v112
	v_rcp_f32_e32 v119, v112
	s_nop 0
	v_pk_mul_f32 v[112:113], v[118:119], v[116:117]
	s_nop 0
	v_mul_f32_e32 v112, v112, v113
	v_lshlrev_b32_e32 v117, 16, v133
	v_cvt_pk_bf16_f32 v112, v2, v112
	v_mul_f32_e32 v2, 0xbfb8aa3b, v117
	v_exp_f32_e32 v2, v2
	v_mov_b32_e32 v118, v114
	v_mov_b32_e32 v116, v102
	v_add_f32_e32 v2, 1.0, v2
	v_rcp_f32_e32 v119, v2
	s_nop 0
	v_pk_mul_f32 v[116:117], v[118:119], v[116:117]
	s_nop 0
	v_mul_f32_e32 v2, v116, v117
	v_and_b32_e32 v117, 0xffff0000, v133
	v_mul_f32_e32 v113, 0xbfb8aa3b, v117
	v_exp_f32_e32 v113, v113
	v_mov_b32_e32 v118, v115
	v_mov_b32_e32 v116, v103
	v_lshlrev_b64 v[132:133], 9, v[146:147]
	v_add_f32_e32 v113, 1.0, v113
	v_rcp_f32_e32 v119, v113
	s_nop 0
	v_pk_mul_f32 v[114:115], v[118:119], v[116:117]
	s_nop 0
	v_mul_f32_e32 v113, v114, v115
	v_lshlrev_b32_e32 v115, 16, v134
	v_cvt_pk_bf16_f32 v113, v2, v113
	v_mul_f32_e32 v2, 0xbfb8aa3b, v115
	v_exp_f32_e32 v2, v2
	v_mov_b32_e32 v116, v108
	v_mov_b32_e32 v114, v92
; __device__ __forceinline__ size_t pidx(size_t row, int col) { return ((size_t)(col >> 8) * MTOK + row) * PLD + (col & 255); }
; __device__ __forceinline__ float bflo(unsigned v) { return __uint_as_float(v << 16); }
; __device__ __forceinline__ float bfhi(unsigned v) { return __uint_as_float(v & 0xffff0000u); }
; __device__ __forceinline__ float siluf_(float x) { return x * __builtin_amdgcn_rcpf(1.0f + __expf(-x)); }
;   __device__ __forceinline__ void operator()(EPI_ARGS) const {
;     ...
;       for (int ai = 0; ai < 2; ++ai) {
;         u32x4 z[4];
; #pragma unroll
;         for (int m = 0; m < 4; ++m) z[m] = *(const u32x4*)(proj + pidx(row0 + ai * HALF + m * 16, PZ + c));
;         __builtin_amdgcn_sched_barrier(0);
; #pragma unroll
;         for (int m = 0; m < 4; ++m) {
;           const size_t row = row0 + ai * HALF + m * 16;
;           const f32x4 v0 = acc[ai][bj][m][0], v1 = acc[ai][bj][m][1];
;           u32x4 o;
;           o.x = pack2(v0[0] * s0[0] * siluf_(bflo(z[m].x)), v0[1] * s0[1] * siluf_(bfhi(z[m].x)));
;           o.y = pack2(v0[2] * s0[2] * siluf_(bflo(z[m].y)), v0[3] * s0[3] * siluf_(bfhi(z[m].y)));
;           o.z = pack2(v1[0] * s1[0] * siluf_(bflo(z[m].z)), v1[1] * s1[1] * siluf_(bfhi(z[m].z)));
;           o.w = pack2(v1[2] * s1[2] * siluf_(bflo(z[m].w)), v1[3] * s1[3] * siluf_(bfhi(z[m].w)));
;           *(u32x4*)(y0 + row * DM + c) = o;
;         }
	v_add_f32_e32 v2, 1.0, v2
	v_rcp_f32_e32 v117, v2
	s_nop 0
	v_pk_mul_f32 v[114:115], v[116:117], v[114:115]
	s_nop 0
	v_mul_f32_e32 v2, v114, v115
	v_and_b32_e32 v115, 0xffff0000, v134
	v_mul_f32_e32 v108, 0xbfb8aa3b, v115
	v_exp_f32_e32 v108, v108
	v_mov_b32_e32 v116, v109
	v_mov_b32_e32 v114, v93
	v_add_f32_e32 v108, 1.0, v108
	v_rcp_f32_e32 v117, v108
	s_nop 0
	v_pk_mul_f32 v[108:109], v[116:117], v[114:115]
	s_nop 0
	v_mul_f32_e32 v108, v108, v109
	v_lshlrev_b32_e32 v109, 16, v135
	v_cvt_pk_bf16_f32 v114, v2, v108
	v_mul_f32_e32 v2, 0xbfb8aa3b, v109
	v_exp_f32_e32 v2, v2
	v_mov_b32_e32 v116, v110
	v_mov_b32_e32 v108, v94
	v_add_f32_e32 v2, 1.0, v2
	v_rcp_f32_e32 v117, v2
	s_nop 0
	v_pk_mul_f32 v[108:109], v[116:117], v[108:109]
	s_nop 0
	v_mul_f32_e32 v2, v108, v109
	v_and_b32_e32 v109, 0xffff0000, v135
	v_mul_f32_e32 v108, 0xbfb8aa3b, v109
	v_exp_f32_e32 v108, v108
	v_mov_b32_e32 v116, v111
	v_lshlrev_b64 v[134:135], 9, v[144:145]
	v_add_f32_e32 v108, 1.0, v108
	v_rcp_f32_e32 v117, v108
	v_mov_b32_e32 v108, v95
	v_pk_mul_f32 v[108:109], v[116:117], v[108:109]
	s_nop 0
	v_mul_f32_e32 v108, v108, v109
	v_cvt_pk_bf16_f32 v115, v2, v108
	v_lshlrev_b64 v[108:109], 12, v[190:191]
	v_lshl_add_u64 v[108:109], s[8:9], 0, v[108:109]
	v_lshl_add_u64 v[126:127], v[108:109], 0, v[140:141]
	flat_store_dwordx4 v[126:127], v[112:115]
	v_lshl_add_u64 v[108:109], v[188:189], 0, v[130:131]
	flat_load_dwordx4 v[120:123], v[108:109]
	v_lshl_add_u64 v[108:109], v[188:189], 0, v[132:133]
	flat_load_dwordx4 v[116:119], v[108:109]
	v_lshl_add_u64 v[108:109], v[188:189], 0, v[134:135]
	flat_load_dwordx4 v[112:115], v[108:109]
	v_lshl_add_u64 v[108:109], v[188:189], 0, v[138:139]
	flat_load_dwordx4 v[108:111], v[108:109]
	s_waitcnt vmcnt(0) lgkmcnt(0)
	v_lshlrev_b32_e32 v151, 16, v120
	v_mul_f32_e32 v2, 0xbfb8aa3b, v151
	v_exp_f32_e32 v2, v2
	v_mov_b32_e32 v152, v104
	v_mov_b32_e32 v150, v100
	v_mov_b32_e32 v175, v3
	v_add_f32_e32 v2, 1.0, v2
	v_rcp_f32_e32 v153, v2
	s_nop 0
	v_pk_mul_f32 v[150:151], v[152:153], v[150:151]
	s_nop 0
	v_mul_f32_e32 v2, v150, v151
	v_and_b32_e32 v151, 0xffff0000, v120
	v_mul_f32_e32 v104, 0xbfb8aa3b, v151
	v_exp_f32_e32 v104, v104
	v_mov_b32_e32 v152, v105
	v_mov_b32_e32 v150, v101
	v_mov_b32_e32 v120, v103
	v_add_f32_e32 v104, 1.0, v104
	v_rcp_f32_e32 v153, v104
	s_nop 0
	v_pk_mul_f32 v[104:105], v[152:153], v[150:151]
	s_nop 0
	v_mul_f32_e32 v104, v104, v105
	v_lshlrev_b32_e32 v151, 16, v121
	v_cvt_pk_bf16_f32 v104, v2, v104
	v_mul_f32_e32 v2, 0xbfb8aa3b, v151
	v_exp_f32_e32 v2, v2
	v_and_b32_e32 v121, 0xffff0000, v121
	v_mul_f32_e32 v105, 0xbfb8aa3b, v121
	v_exp_f32_e32 v105, v105
	v_add_f32_e32 v2, 1.0, v2
	v_rcp_f32_e32 v153, v2
	v_mov_b32_e32 v152, v106
	v_mov_b32_e32 v150, v102
	v_add_f32_e32 v105, 1.0, v105
	v_pk_mul_f32 v[150:151], v[152:153], v[150:151]
	s_nop 0
	v_mul_f32_e32 v2, v150, v151
	v_rcp_f32_e32 v151, v105
	v_mov_b32_e32 v150, v107
	v_pk_mul_f32 v[106:107], v[150:151], v[120:121]
	s_nop 0
	v_mul_f32_e32 v105, v106, v107
	v_lshlrev_b32_e32 v107, 16, v122
	v_cvt_pk_bf16_f32 v105, v2, v105
	v_mul_f32_e32 v2, 0xbfb8aa3b, v107
	v_exp_f32_e32 v2, v2
	v_mov_b32_e32 v120, v96
	v_mov_b32_e32 v106, v92
	v_add_f32_e32 v2, 1.0, v2
	v_rcp_f32_e32 v121, v2
	s_nop 0
	v_pk_mul_f32 v[106:107], v[120:121], v[106:107]
	s_nop 0
	v_mul_f32_e32 v2, v106, v107
	v_and_b32_e32 v107, 0xffff0000, v122
	v_mul_f32_e32 v96, 0xbfb8aa3b, v107
	v_exp_f32_e32 v96, v96
	v_mov_b32_e32 v120, v97
	v_mov_b32_e32 v106, v93
	v_add_f32_e32 v96, 1.0, v96
	v_rcp_f32_e32 v121, v96
	s_nop 0
	v_pk_mul_f32 v[96:97], v[120:121], v[106:107]
	s_nop 0
	v_mul_f32_e32 v96, v96, v97
	v_lshlrev_b32_e32 v97, 16, v123
	v_cvt_pk_bf16_f32 v106, v2, v96
	v_mul_f32_e32 v2, 0xbfb8aa3b, v97
	v_exp_f32_e32 v2, v2
	v_mov_b32_e32 v120, v98
	v_mov_b32_e32 v96, v94
	v_mov_b32_e32 v98, v100
	v_add_f32_e32 v2, 1.0, v2
	v_rcp_f32_e32 v121, v2
	s_nop 0
	v_pk_mul_f32 v[96:97], v[120:121], v[96:97]
	s_nop 0
	v_mul_f32_e32 v2, v96, v97
	v_and_b32_e32 v97, 0xffff0000, v123
	v_mul_f32_e32 v96, 0xbfb8aa3b, v97
	v_exp_f32_e32 v96, v96
	v_mov_b32_e32 v120, v99
	v_lshlrev_b32_e32 v99, 16, v116
	v_add_f32_e32 v96, 1.0, v96
	v_rcp_f32_e32 v121, v96
	v_mov_b32_e32 v96, v95
	v_pk_mul_f32 v[96:97], v[120:121], v[96:97]
	s_nop 0
	v_mul_f32_e32 v96, v96, v97
	v_cvt_pk_bf16_f32 v107, v2, v96
	v_mul_f32_e32 v2, 0xbfb8aa3b, v99
	v_exp_f32_e32 v2, v2
	v_lshlrev_b64 v[96:97], 12, v[148:149]
	v_lshl_add_u64 v[96:97], s[8:9], 0, v[96:97]
	v_lshl_add_u64 v[96:97], v[96:97], 0, v[140:141]
	v_add_f32_e32 v2, 1.0, v2
	flat_store_dwordx4 v[96:97], v[104:107]
	s_nop 1
	v_rcp_f32_e32 v105, v2
	v_mov_b32_e32 v104, v88
	v_pk_mul_f32 v[98:99], v[104:105], v[98:99]
	s_nop 0
	v_mul_f32_e32 v2, v98, v99
	v_and_b32_e32 v99, 0xffff0000, v116
	v_mul_f32_e32 v88, 0xbfb8aa3b, v99
	v_exp_f32_e32 v88, v88
	v_mov_b32_e32 v104, v89
	v_mov_b32_e32 v98, v101
	v_add_f32_e32 v88, 1.0, v88
	v_rcp_f32_e32 v105, v88
	s_nop 0
	v_pk_mul_f32 v[88:89], v[104:105], v[98:99]
	s_nop 0
	v_mul_f32_e32 v88, v88, v89
	v_lshlrev_b32_e32 v99, 16, v117
	v_cvt_pk_bf16_f32 v88, v2, v88
	v_mul_f32_e32 v2, 0xbfb8aa3b, v99
	v_exp_f32_e32 v2, v2
	v_mov_b32_e32 v104, v90
	v_mov_b32_e32 v98, v102
	v_add_f32_e32 v2, 1.0, v2
	v_rcp_f32_e32 v105, v2
	s_nop 0
	v_pk_mul_f32 v[98:99], v[104:105], v[98:99]
	s_nop 0
	v_mul_f32_e32 v2, v98, v99
	v_and_b32_e32 v99, 0xffff0000, v117
	v_mul_f32_e32 v89, 0xbfb8aa3b, v99
	v_exp_f32_e32 v89, v89
	v_mov_b32_e32 v104, v91
	v_mov_b32_e32 v98, v103
	v_add_f32_e32 v89, 1.0, v89
	v_rcp_f32_e32 v105, v89
	s_nop 0
	v_pk_mul_f32 v[90:91], v[104:105], v[98:99]
	s_nop 0
	v_mul_f32_e32 v89, v90, v91
	v_lshlrev_b32_e32 v91, 16, v118
; __device__ __forceinline__ size_t pidx(size_t row, int col) { return ((size_t)(col >> 8) * MTOK + row) * PLD + (col & 255); }
; __device__ __forceinline__ float bflo(unsigned v) { return __uint_as_float(v << 16); }
; __device__ __forceinline__ float bfhi(unsigned v) { return __uint_as_float(v & 0xffff0000u); }
; __device__ __forceinline__ float siluf_(float x) { return x * __builtin_amdgcn_rcpf(1.0f + __expf(-x)); }
;   __device__ __forceinline__ void operator()(EPI_ARGS) const {
;     ...
;       const f32x4 s0 = *(const f32x4*)(psc + c), s1 = *(const f32x4*)(psc + c + 4);
; #pragma unroll
;       for (int ai = 0; ai < 2; ++ai) {
;         u32x4 z[4];
; #pragma unroll
;         for (int m = 0; m < 4; ++m) z[m] = *(const u32x4*)(proj + pidx(row0 + ai * HALF + m * 16, PZ + c));
;         __builtin_amdgcn_sched_barrier(0);
; #pragma unroll
;         for (int m = 0; m < 4; ++m) {
;           const size_t row = row0 + ai * HALF + m * 16;
;           const f32x4 v0 = acc[ai][bj][m][0], v1 = acc[ai][bj][m][1];
;           u32x4 o;
;           o.x = pack2(v0[0] * s0[0] * siluf_(bflo(z[m].x)), v0[1] * s0[1] * siluf_(bfhi(z[m].x)));
;           o.y = pack2(v0[2] * s0[2] * siluf_(bflo(z[m].y)), v0[3] * s0[3] * siluf_(bfhi(z[m].y)));
;           o.z = pack2(v1[0] * s1[0] * siluf_(bflo(z[m].z)), v1[1] * s1[1] * siluf_(bfhi(z[m].z)));
;           o.w = pack2(v1[2] * s1[2] * siluf_(bflo(z[m].w)), v1[3] * s1[3] * siluf_(bfhi(z[m].w)));
;           *(u32x4*)(y0 + row * DM + c) = o;
	v_cvt_pk_bf16_f32 v89, v2, v89
	v_mul_f32_e32 v2, 0xbfb8aa3b, v91
	v_exp_f32_e32 v2, v2
	v_mov_b32_e32 v98, v84
	v_mov_b32_e32 v90, v92
	v_add_f32_e32 v2, 1.0, v2
	v_rcp_f32_e32 v99, v2
	s_nop 0
	v_pk_mul_f32 v[90:91], v[98:99], v[90:91]
	s_nop 0
	v_mul_f32_e32 v2, v90, v91
	v_and_b32_e32 v91, 0xffff0000, v118
	v_mul_f32_e32 v84, 0xbfb8aa3b, v91
	v_exp_f32_e32 v84, v84
	v_mov_b32_e32 v98, v85
	v_mov_b32_e32 v90, v93
	v_add_f32_e32 v84, 1.0, v84
	v_rcp_f32_e32 v99, v84
	s_nop 0
	v_pk_mul_f32 v[84:85], v[98:99], v[90:91]
	s_nop 0
	v_mul_f32_e32 v84, v84, v85
	v_lshlrev_b32_e32 v85, 16, v119
	v_cvt_pk_bf16_f32 v90, v2, v84
	v_mul_f32_e32 v2, 0xbfb8aa3b, v85
	v_exp_f32_e32 v2, v2
	v_mov_b32_e32 v98, v86
	v_mov_b32_e32 v84, v94
	v_mov_b32_e32 v86, v80
	v_add_f32_e32 v2, 1.0, v2
	v_rcp_f32_e32 v99, v2
	s_nop 0
	v_pk_mul_f32 v[84:85], v[98:99], v[84:85]
	s_nop 0
	v_mul_f32_e32 v2, v84, v85
	v_and_b32_e32 v85, 0xffff0000, v119
	v_mul_f32_e32 v84, 0xbfb8aa3b, v85
	v_exp_f32_e32 v84, v84
	v_mov_b32_e32 v98, v87
	v_add_f32_e32 v84, 1.0, v84
	v_rcp_f32_e32 v99, v84
	v_mov_b32_e32 v84, v95
	v_pk_mul_f32 v[84:85], v[98:99], v[84:85]
	s_nop 0
	v_mul_f32_e32 v84, v84, v85
	v_cvt_pk_bf16_f32 v91, v2, v84
	v_lshlrev_b64 v[84:85], 12, v[146:147]
	v_lshl_add_u64 v[84:85], s[8:9], 0, v[84:85]
	v_lshl_add_u64 v[98:99], v[84:85], 0, v[140:141]
	v_lshlrev_b32_e32 v85, 16, v112
	v_mul_f32_e32 v2, 0xbfb8aa3b, v85
	v_exp_f32_e32 v2, v2
	v_mov_b32_e32 v84, v100
	flat_store_dwordx4 v[98:99], v[88:91]
	v_add_f32_e32 v2, 1.0, v2
	v_rcp_f32_e32 v87, v2
	s_nop 0
	v_pk_mul_f32 v[84:85], v[86:87], v[84:85]
	s_nop 0
	v_mul_f32_e32 v2, v84, v85
	v_and_b32_e32 v85, 0xffff0000, v112
	v_mul_f32_e32 v80, 0xbfb8aa3b, v85
	v_exp_f32_e32 v80, v80
	v_mov_b32_e32 v86, v81
	v_mov_b32_e32 v84, v101
	v_add_f32_e32 v80, 1.0, v80
	v_rcp_f32_e32 v87, v80
	s_nop 0
	v_pk_mul_f32 v[80:81], v[86:87], v[84:85]
	s_nop 0
	v_mul_f32_e32 v80, v80, v81
	v_lshlrev_b32_e32 v85, 16, v113
	v_cvt_pk_bf16_f32 v80, v2, v80
	v_mul_f32_e32 v2, 0xbfb8aa3b, v85
	v_exp_f32_e32 v2, v2
	v_mov_b32_e32 v86, v82
	v_mov_b32_e32 v84, v102
	v_add_f32_e32 v2, 1.0, v2
	v_rcp_f32_e32 v87, v2
	s_nop 0
	v_pk_mul_f32 v[84:85], v[86:87], v[84:85]
	s_nop 0
	v_mul_f32_e32 v2, v84, v85
	v_and_b32_e32 v85, 0xffff0000, v113
	v_mul_f32_e32 v81, 0xbfb8aa3b, v85
	v_exp_f32_e32 v81, v81
	v_mov_b32_e32 v86, v83
	v_mov_b32_e32 v84, v103
	v_add_f32_e32 v81, 1.0, v81
	v_rcp_f32_e32 v87, v81
	s_nop 0
	v_pk_mul_f32 v[82:83], v[86:87], v[84:85]
	s_nop 0
	v_mul_f32_e32 v81, v82, v83
	v_lshlrev_b32_e32 v83, 16, v114
	v_cvt_pk_bf16_f32 v81, v2, v81
	v_mul_f32_e32 v2, 0xbfb8aa3b, v83
	v_exp_f32_e32 v2, v2
	v_mov_b32_e32 v84, v76
	v_mov_b32_e32 v82, v92
	v_add_f32_e32 v2, 1.0, v2
	v_rcp_f32_e32 v85, v2
	s_nop 0
	v_pk_mul_f32 v[82:83], v[84:85], v[82:83]
	s_nop 0
	v_mul_f32_e32 v2, v82, v83
	v_and_b32_e32 v83, 0xffff0000, v114
	v_mul_f32_e32 v76, 0xbfb8aa3b, v83
	v_exp_f32_e32 v76, v76
	v_mov_b32_e32 v84, v77
	v_mov_b32_e32 v82, v93
	v_add_f32_e32 v76, 1.0, v76
	v_rcp_f32_e32 v85, v76
	s_nop 0
	v_pk_mul_f32 v[76:77], v[84:85], v[82:83]
	s_nop 0
	v_mul_f32_e32 v76, v76, v77
	v_lshlrev_b32_e32 v77, 16, v115
	v_cvt_pk_bf16_f32 v82, v2, v76
	v_mul_f32_e32 v2, 0xbfb8aa3b, v77
	v_exp_f32_e32 v2, v2
	v_mov_b32_e32 v84, v78
	v_mov_b32_e32 v76, v94
	v_mov_b32_e32 v78, v72
	v_add_f32_e32 v2, 1.0, v2
	v_rcp_f32_e32 v85, v2
	s_nop 0
	v_pk_mul_f32 v[76:77], v[84:85], v[76:77]
	s_nop 0
	v_mul_f32_e32 v2, v76, v77
	v_and_b32_e32 v77, 0xffff0000, v115
	v_mul_f32_e32 v76, 0xbfb8aa3b, v77
	v_exp_f32_e32 v76, v76
	v_mov_b32_e32 v84, v79
	v_add_f32_e32 v76, 1.0, v76
	v_rcp_f32_e32 v85, v76
	v_mov_b32_e32 v76, v95
	v_pk_mul_f32 v[76:77], v[84:85], v[76:77]
	s_nop 0
	v_mul_f32_e32 v76, v76, v77
	v_cvt_pk_bf16_f32 v83, v2, v76
	v_lshlrev_b64 v[76:77], 12, v[144:145]
	v_lshl_add_u64 v[76:77], s[8:9], 0, v[76:77]
	v_lshl_add_u64 v[104:105], v[76:77], 0, v[140:141]
	v_lshlrev_b32_e32 v77, 16, v108
	v_mul_f32_e32 v2, 0xbfb8aa3b, v77
	v_exp_f32_e32 v2, v2
	v_mov_b32_e32 v76, v100
	flat_store_dwordx4 v[104:105], v[80:83]
	v_add_f32_e32 v2, 1.0, v2
	v_rcp_f32_e32 v79, v2
	s_nop 0
	v_pk_mul_f32 v[76:77], v[78:79], v[76:77]
	s_nop 0
	v_mul_f32_e32 v2, v76, v77
	v_and_b32_e32 v77, 0xffff0000, v108
	v_mul_f32_e32 v72, 0xbfb8aa3b, v77
	v_exp_f32_e32 v72, v72
	v_mov_b32_e32 v78, v73
	v_mov_b32_e32 v76, v101
	v_add_f32_e32 v72, 1.0, v72
	v_rcp_f32_e32 v79, v72
	s_nop 0
	v_pk_mul_f32 v[72:73], v[78:79], v[76:77]
	s_nop 0
	v_mul_f32_e32 v72, v72, v73
	v_lshlrev_b32_e32 v77, 16, v109
	v_cvt_pk_bf16_f32 v72, v2, v72
	v_mul_f32_e32 v2, 0xbfb8aa3b, v77
	v_exp_f32_e32 v2, v2
	v_mov_b32_e32 v78, v74
	v_mov_b32_e32 v76, v102
	v_add_f32_e32 v2, 1.0, v2
	v_rcp_f32_e32 v79, v2
	s_nop 0
	v_pk_mul_f32 v[76:77], v[78:79], v[76:77]
	s_nop 0
	v_mul_f32_e32 v2, v76, v77
	v_and_b32_e32 v77, 0xffff0000, v109
	v_mul_f32_e32 v73, 0xbfb8aa3b, v77
	v_exp_f32_e32 v73, v73
	v_mov_b32_e32 v78, v75
	v_mov_b32_e32 v76, v103
	v_add_f32_e32 v73, 1.0, v73
	v_rcp_f32_e32 v79, v73
	s_nop 0
	v_pk_mul_f32 v[74:75], v[78:79], v[76:77]
	s_nop 0
	v_mul_f32_e32 v73, v74, v75
	v_lshlrev_b32_e32 v75, 16, v110
	v_cvt_pk_bf16_f32 v73, v2, v73
	v_mul_f32_e32 v2, 0xbfb8aa3b, v75
	v_exp_f32_e32 v2, v2
	v_mov_b32_e32 v76, v68
	v_mov_b32_e32 v74, v92
	v_add_f32_e32 v2, 1.0, v2
	v_rcp_f32_e32 v77, v2
	s_nop 0
	v_pk_mul_f32 v[74:75], v[76:77], v[74:75]
	s_nop 0
	v_mul_f32_e32 v2, v74, v75
	v_and_b32_e32 v75, 0xffff0000, v110
	v_mul_f32_e32 v68, 0xbfb8aa3b, v75
	v_exp_f32_e32 v68, v68
	v_mov_b32_e32 v76, v69
	v_mov_b32_e32 v74, v93
	v_add_f32_e32 v68, 1.0, v68
	v_rcp_f32_e32 v77, v68
	s_nop 0
	v_pk_mul_f32 v[68:69], v[76:77], v[74:75]
	s_nop 0
	v_mul_f32_e32 v68, v68, v69
	v_lshlrev_b32_e32 v69, 16, v111
	v_cvt_pk_bf16_f32 v74, v2, v68
	v_mul_f32_e32 v2, 0xbfb8aa3b, v69
	v_exp_f32_e32 v2, v2
	v_mov_b32_e32 v76, v70
	v_mov_b32_e32 v68, v94
	v_add_f32_e32 v2, 1.0, v2
	v_rcp_f32_e32 v77, v2
	s_nop 0
	v_pk_mul_f32 v[68:69], v[76:77], v[68:69]
	s_nop 0
	v_mul_f32_e32 v2, v68, v69
	v_and_b32_e32 v69, 0xffff0000, v111
	v_mul_f32_e32 v68, 0xbfb8aa3b, v69
	v_exp_f32_e32 v68, v68
	v_mov_b32_e32 v76, v71
	v_add_f32_e32 v68, 1.0, v68
	v_rcp_f32_e32 v77, v68
	v_mov_b32_e32 v68, v95
	v_lshl_add_u64 v[94:95], s[2:3], 0, v[174:175]
	v_pk_mul_f32 v[68:69], v[76:77], v[68:69]
	s_nop 0
	v_mul_f32_e32 v68, v68, v69
	v_cvt_pk_bf16_f32 v75, v2, v68
	v_lshlrev_b64 v[68:69], 12, v[142:143]
	v_lshl_add_u64 v[68:69], s[8:9], 0, v[68:69]
	v_lshl_add_u64 v[92:93], v[68:69], 0, v[140:141]
	flat_store_dwordx4 v[92:93], v[72:75]
	v_lshl_add_u64 v[76:77], v[94:95], 0, v[178:179]
	global_load_dwordx4 v[68:71], v[176:177], off offset:528
	global_load_dwordx4 v[72:75], v[176:177], off offset:512
	flat_load_dwordx4 v[88:91], v[76:77]
	v_lshl_add_u64 v[76:77], v[94:95], 0, v[180:181]
	flat_load_dwordx4 v[84:87], v[76:77]
	v_lshl_add_u64 v[76:77], v[94:95], 0, v[182:183]
	flat_load_dwordx4 v[80:83], v[76:77]
	v_lshl_add_u64 v[76:77], v[94:95], 0, v[184:185]
	flat_load_dwordx4 v[76:79], v[76:77]
	s_waitcnt vmcnt(0) lgkmcnt(0)
; __device__ __forceinline__ size_t pidx(size_t row, int col) { return ((size_t)(col >> 8) * MTOK + row) * PLD + (col & 255); }
; __device__ __forceinline__ float bflo(unsigned v) { return __uint_as_float(v << 16); }
; __device__ __forceinline__ float bfhi(unsigned v) { return __uint_as_float(v & 0xffff0000u); }
; __device__ __forceinline__ float siluf_(float x) { return x * __builtin_amdgcn_rcpf(1.0f + __expf(-x)); }
;   __device__ __forceinline__ void operator()(EPI_ARGS) const {
;     ...
;         for (int m = 0; m < 4; ++m) z[m] = *(const u32x4*)(proj + pidx(row0 + ai * HALF + m * 16, PZ + c));
;         __builtin_amdgcn_sched_barrier(0);
; #pragma unroll
;         for (int m = 0; m < 4; ++m) {
;           const size_t row = row0 + ai * HALF + m * 16;
;           const f32x4 v0 = acc[ai][bj][m][0], v1 = acc[ai][bj][m][1];
;           u32x4 o;
;           o.x = pack2(v0[0] * s0[0] * siluf_(bflo(z[m].x)), v0[1] * s0[1] * siluf_(bfhi(z[m].x)));
;           o.y = pack2(v0[2] * s0[2] * siluf_(bflo(z[m].y)), v0[3] * s0[3] * siluf_(bfhi(z[m].y)));
;           o.z = pack2(v1[0] * s1[0] * siluf_(bflo(z[m].z)), v1[1] * s1[1] * siluf_(bfhi(z[m].z)));
;           o.w = pack2(v1[2] * s1[2] * siluf_(bflo(z[m].w)), v1[3] * s1[3] * siluf_(bfhi(z[m].w)));
;           *(u32x4*)(y0 + row * DM + c) = o;
;         }
	v_lshlrev_b32_e32 v101, 16, v88
	v_mul_f32_e32 v2, 0xbfb8aa3b, v101
	v_exp_f32_e32 v2, v2
	v_mov_b32_e32 v102, v64
	v_mov_b32_e32 v100, v72
	v_add_f32_e32 v2, 1.0, v2
	v_rcp_f32_e32 v103, v2
	s_nop 0
	v_pk_mul_f32 v[100:101], v[102:103], v[100:101]
	s_nop 0
	v_mul_f32_e32 v2, v100, v101
	v_and_b32_e32 v101, 0xffff0000, v88
	v_mul_f32_e32 v64, 0xbfb8aa3b, v101
	v_exp_f32_e32 v64, v64
	v_mov_b32_e32 v102, v65
	v_mov_b32_e32 v100, v73
	v_mov_b32_e32 v88, v75
	v_add_f32_e32 v64, 1.0, v64
	v_rcp_f32_e32 v103, v64
	s_nop 0
	v_pk_mul_f32 v[64:65], v[102:103], v[100:101]
	s_nop 0
	v_mul_f32_e32 v64, v64, v65
	v_lshlrev_b32_e32 v101, 16, v89
	v_cvt_pk_bf16_f32 v64, v2, v64
	v_mul_f32_e32 v2, 0xbfb8aa3b, v101
	v_exp_f32_e32 v2, v2
	v_and_b32_e32 v89, 0xffff0000, v89
	v_mul_f32_e32 v65, 0xbfb8aa3b, v89
	v_exp_f32_e32 v65, v65
	v_add_f32_e32 v2, 1.0, v2
	v_rcp_f32_e32 v103, v2
	v_mov_b32_e32 v102, v66
	v_mov_b32_e32 v100, v74
	v_add_f32_e32 v65, 1.0, v65
	v_pk_mul_f32 v[100:101], v[102:103], v[100:101]
	s_nop 0
	v_mul_f32_e32 v2, v100, v101
	v_rcp_f32_e32 v101, v65
	v_mov_b32_e32 v100, v67
	v_pk_mul_f32 v[66:67], v[100:101], v[88:89]
	s_nop 0
	v_mul_f32_e32 v65, v66, v67
	v_lshlrev_b32_e32 v67, 16, v90
	v_cvt_pk_bf16_f32 v65, v2, v65
	v_mul_f32_e32 v2, 0xbfb8aa3b, v67
	v_exp_f32_e32 v2, v2
	v_mov_b32_e32 v88, v60
	v_mov_b32_e32 v66, v68
	v_add_f32_e32 v2, 1.0, v2
	v_rcp_f32_e32 v89, v2
	s_nop 0
	v_pk_mul_f32 v[66:67], v[88:89], v[66:67]
	s_nop 0
	v_mul_f32_e32 v2, v66, v67
	v_and_b32_e32 v67, 0xffff0000, v90
	v_mul_f32_e32 v60, 0xbfb8aa3b, v67
	v_exp_f32_e32 v60, v60
	v_mov_b32_e32 v88, v61
	v_mov_b32_e32 v66, v69
	v_add_f32_e32 v60, 1.0, v60
	v_rcp_f32_e32 v89, v60
	s_nop 0
	v_pk_mul_f32 v[60:61], v[88:89], v[66:67]
	s_nop 0
	v_mul_f32_e32 v60, v60, v61
	v_lshlrev_b32_e32 v61, 16, v91
	v_cvt_pk_bf16_f32 v66, v2, v60
	v_mul_f32_e32 v2, 0xbfb8aa3b, v61
	v_exp_f32_e32 v2, v2
	v_mov_b32_e32 v88, v62
	v_mov_b32_e32 v60, v70
	v_mov_b32_e32 v62, v56
	v_add_f32_e32 v2, 1.0, v2
	v_rcp_f32_e32 v89, v2
	s_nop 0
	v_pk_mul_f32 v[60:61], v[88:89], v[60:61]
	s_nop 0
	v_mul_f32_e32 v2, v60, v61
	v_and_b32_e32 v61, 0xffff0000, v91
	v_mul_f32_e32 v60, 0xbfb8aa3b, v61
	v_exp_f32_e32 v60, v60
	v_mov_b32_e32 v88, v63
	v_add_f32_e32 v60, 1.0, v60
	v_rcp_f32_e32 v89, v60
	v_mov_b32_e32 v60, v71
	v_pk_mul_f32 v[60:61], v[88:89], v[60:61]
	s_nop 0
	v_mul_f32_e32 v60, v60, v61
	v_lshlrev_b32_e32 v61, 16, v84
	v_cvt_pk_bf16_f32 v67, v2, v60
	v_mul_f32_e32 v2, 0xbfb8aa3b, v61
	v_exp_f32_e32 v2, v2
	v_mov_b32_e32 v60, v72
	flat_store_dwordx4 v[136:137], v[64:67] offset:256
	v_add_f32_e32 v2, 1.0, v2
	v_rcp_f32_e32 v63, v2
	s_nop 0
	v_pk_mul_f32 v[60:61], v[62:63], v[60:61]
	s_nop 0
	v_mul_f32_e32 v2, v60, v61
	v_and_b32_e32 v61, 0xffff0000, v84
	v_mul_f32_e32 v56, 0xbfb8aa3b, v61
	v_exp_f32_e32 v56, v56
	v_mov_b32_e32 v62, v57
	v_mov_b32_e32 v60, v73
	v_add_f32_e32 v56, 1.0, v56
	v_rcp_f32_e32 v63, v56
	s_nop 0
	v_pk_mul_f32 v[56:57], v[62:63], v[60:61]
	s_nop 0
	v_mul_f32_e32 v56, v56, v57
	v_lshlrev_b32_e32 v61, 16, v85
	v_cvt_pk_bf16_f32 v56, v2, v56
	v_mul_f32_e32 v2, 0xbfb8aa3b, v61
	v_exp_f32_e32 v2, v2
	v_mov_b32_e32 v62, v58
	v_mov_b32_e32 v60, v74
	v_add_f32_e32 v2, 1.0, v2
	v_rcp_f32_e32 v63, v2
	s_nop 0
	v_pk_mul_f32 v[60:61], v[62:63], v[60:61]
	s_nop 0
	v_mul_f32_e32 v2, v60, v61
	v_and_b32_e32 v61, 0xffff0000, v85
	v_mul_f32_e32 v57, 0xbfb8aa3b, v61
	v_exp_f32_e32 v57, v57
	v_mov_b32_e32 v62, v59
	v_mov_b32_e32 v60, v75
	v_add_f32_e32 v57, 1.0, v57
	v_rcp_f32_e32 v63, v57
	s_nop 0
	v_pk_mul_f32 v[58:59], v[62:63], v[60:61]
	s_nop 0
	v_mul_f32_e32 v57, v58, v59
	v_lshlrev_b32_e32 v59, 16, v86
	v_cvt_pk_bf16_f32 v57, v2, v57
	v_mul_f32_e32 v2, 0xbfb8aa3b, v59
	v_exp_f32_e32 v2, v2
	v_mov_b32_e32 v60, v52
	v_mov_b32_e32 v58, v68
	v_add_f32_e32 v2, 1.0, v2
	v_rcp_f32_e32 v61, v2
	s_nop 0
	v_pk_mul_f32 v[58:59], v[60:61], v[58:59]
	s_nop 0
	v_mul_f32_e32 v2, v58, v59
	v_and_b32_e32 v59, 0xffff0000, v86
	v_mul_f32_e32 v52, 0xbfb8aa3b, v59
	v_exp_f32_e32 v52, v52
	v_mov_b32_e32 v60, v53
	v_mov_b32_e32 v58, v69
	v_add_f32_e32 v52, 1.0, v52
	v_rcp_f32_e32 v61, v52
	s_nop 0
	v_pk_mul_f32 v[52:53], v[60:61], v[58:59]
	s_nop 0
	v_mul_f32_e32 v52, v52, v53
	v_lshlrev_b32_e32 v53, 16, v87
	v_cvt_pk_bf16_f32 v58, v2, v52
	v_mul_f32_e32 v2, 0xbfb8aa3b, v53
	v_exp_f32_e32 v2, v2
	v_mov_b32_e32 v60, v54
	v_mov_b32_e32 v52, v70
	v_mov_b32_e32 v54, v48
	v_add_f32_e32 v2, 1.0, v2
	v_rcp_f32_e32 v61, v2
	s_nop 0
	v_pk_mul_f32 v[52:53], v[60:61], v[52:53]
	s_nop 0
	v_mul_f32_e32 v2, v52, v53
	v_and_b32_e32 v53, 0xffff0000, v87
	v_mul_f32_e32 v52, 0xbfb8aa3b, v53
	v_exp_f32_e32 v52, v52
	v_mov_b32_e32 v60, v55
	v_add_f32_e32 v52, 1.0, v52
	v_rcp_f32_e32 v61, v52
	v_mov_b32_e32 v52, v71
	v_pk_mul_f32 v[52:53], v[60:61], v[52:53]
	s_nop 0
	v_mul_f32_e32 v52, v52, v53
	v_lshlrev_b32_e32 v53, 16, v80
	v_cvt_pk_bf16_f32 v59, v2, v52
	v_mul_f32_e32 v2, 0xbfb8aa3b, v53
	v_exp_f32_e32 v2, v2
	v_mov_b32_e32 v52, v72
	flat_store_dwordx4 v[124:125], v[56:59] offset:256
	v_add_f32_e32 v2, 1.0, v2
	v_rcp_f32_e32 v55, v2
	s_nop 0
	v_pk_mul_f32 v[52:53], v[54:55], v[52:53]
	s_nop 0
	v_mul_f32_e32 v2, v52, v53
	v_and_b32_e32 v53, 0xffff0000, v80
	v_mul_f32_e32 v48, 0xbfb8aa3b, v53
	v_exp_f32_e32 v48, v48
	v_mov_b32_e32 v54, v49
	v_mov_b32_e32 v52, v73
	v_add_f32_e32 v48, 1.0, v48
	v_rcp_f32_e32 v55, v48
	s_nop 0
	v_pk_mul_f32 v[48:49], v[54:55], v[52:53]
	s_nop 0
	v_mul_f32_e32 v48, v48, v49
	v_lshlrev_b32_e32 v53, 16, v81
	v_cvt_pk_bf16_f32 v48, v2, v48
	v_mul_f32_e32 v2, 0xbfb8aa3b, v53
	v_exp_f32_e32 v2, v2
	v_mov_b32_e32 v54, v50
	v_mov_b32_e32 v52, v74
	v_add_f32_e32 v2, 1.0, v2
	v_rcp_f32_e32 v55, v2
; __device__ __forceinline__ size_t pidx(size_t row, int col) { return ((size_t)(col >> 8) * MTOK + row) * PLD + (col & 255); }
; __device__ __forceinline__ float bflo(unsigned v) { return __uint_as_float(v << 16); }
; __device__ __forceinline__ float bfhi(unsigned v) { return __uint_as_float(v & 0xffff0000u); }
; __device__ __forceinline__ float siluf_(float x) { return x * __builtin_amdgcn_rcpf(1.0f + __expf(-x)); }
;   __device__ __forceinline__ void operator()(EPI_ARGS) const {
;     ...
;         for (int m = 0; m < 4; ++m) z[m] = *(const u32x4*)(proj + pidx(row0 + ai * HALF + m * 16, PZ + c));
;         __builtin_amdgcn_sched_barrier(0);
; #pragma unroll
;         for (int m = 0; m < 4; ++m) {
;           const size_t row = row0 + ai * HALF + m * 16;
;           const f32x4 v0 = acc[ai][bj][m][0], v1 = acc[ai][bj][m][1];
;           u32x4 o;
;           o.x = pack2(v0[0] * s0[0] * siluf_(bflo(z[m].x)), v0[1] * s0[1] * siluf_(bfhi(z[m].x)));
;           o.y = pack2(v0[2] * s0[2] * siluf_(bflo(z[m].y)), v0[3] * s0[3] * siluf_(bfhi(z[m].y)));
;           o.z = pack2(v1[0] * s1[0] * siluf_(bflo(z[m].z)), v1[1] * s1[1] * siluf_(bfhi(z[m].z)));
;           o.w = pack2(v1[2] * s1[2] * siluf_(bflo(z[m].w)), v1[3] * s1[3] * siluf_(bfhi(z[m].w)));
;           *(u32x4*)(y0 + row * DM + c) = o;
;         }
	s_nop 0
	v_pk_mul_f32 v[52:53], v[54:55], v[52:53]
	s_nop 0
	v_mul_f32_e32 v2, v52, v53
	v_and_b32_e32 v53, 0xffff0000, v81
	v_mul_f32_e32 v49, 0xbfb8aa3b, v53
	v_exp_f32_e32 v49, v49
	v_mov_b32_e32 v54, v51
	v_mov_b32_e32 v52, v75
	v_add_f32_e32 v49, 1.0, v49
	v_rcp_f32_e32 v55, v49
	s_nop 0
	v_pk_mul_f32 v[50:51], v[54:55], v[52:53]
	s_nop 0
	v_mul_f32_e32 v49, v50, v51
	v_lshlrev_b32_e32 v51, 16, v82
	v_cvt_pk_bf16_f32 v49, v2, v49
	v_mul_f32_e32 v2, 0xbfb8aa3b, v51
	v_exp_f32_e32 v2, v2
	v_mov_b32_e32 v52, v44
	v_mov_b32_e32 v50, v68
	v_add_f32_e32 v2, 1.0, v2
	v_rcp_f32_e32 v53, v2
	s_nop 0
	v_pk_mul_f32 v[50:51], v[52:53], v[50:51]
	s_nop 0
	v_mul_f32_e32 v2, v50, v51
	v_and_b32_e32 v51, 0xffff0000, v82
	v_mul_f32_e32 v44, 0xbfb8aa3b, v51
	v_exp_f32_e32 v44, v44
	v_mov_b32_e32 v52, v45
	v_mov_b32_e32 v50, v69
	v_add_f32_e32 v44, 1.0, v44
	v_rcp_f32_e32 v53, v44
	s_nop 0
	v_pk_mul_f32 v[44:45], v[52:53], v[50:51]
	s_nop 0
	v_mul_f32_e32 v44, v44, v45
	v_lshlrev_b32_e32 v45, 16, v83
	v_cvt_pk_bf16_f32 v50, v2, v44
	v_mul_f32_e32 v2, 0xbfb8aa3b, v45
	v_exp_f32_e32 v2, v2
	v_mov_b32_e32 v52, v46
	v_mov_b32_e32 v44, v70
	v_mov_b32_e32 v46, v40
	v_add_f32_e32 v2, 1.0, v2
	v_rcp_f32_e32 v53, v2
	s_nop 0
	v_pk_mul_f32 v[44:45], v[52:53], v[44:45]
	s_nop 0
	v_mul_f32_e32 v2, v44, v45
	v_and_b32_e32 v45, 0xffff0000, v83
	v_mul_f32_e32 v44, 0xbfb8aa3b, v45
	v_exp_f32_e32 v44, v44
	v_mov_b32_e32 v52, v47
	v_add_f32_e32 v44, 1.0, v44
	v_rcp_f32_e32 v53, v44
	v_mov_b32_e32 v44, v71
	v_pk_mul_f32 v[44:45], v[52:53], v[44:45]
	s_nop 0
	v_mul_f32_e32 v44, v44, v45
	v_lshlrev_b32_e32 v45, 16, v76
	v_cvt_pk_bf16_f32 v51, v2, v44
	v_mul_f32_e32 v2, 0xbfb8aa3b, v45
	v_exp_f32_e32 v2, v2
	v_mov_b32_e32 v44, v72
	flat_store_dwordx4 v[128:129], v[48:51] offset:256
	v_add_f32_e32 v2, 1.0, v2
	v_rcp_f32_e32 v47, v2
	s_nop 0
	v_pk_mul_f32 v[44:45], v[46:47], v[44:45]
	s_nop 0
	v_mul_f32_e32 v2, v44, v45
	v_and_b32_e32 v45, 0xffff0000, v76
	v_mul_f32_e32 v40, 0xbfb8aa3b, v45
	v_exp_f32_e32 v40, v40
	v_mov_b32_e32 v46, v41
	v_mov_b32_e32 v44, v73
	v_add_f32_e32 v40, 1.0, v40
	v_rcp_f32_e32 v47, v40
	s_nop 0
	v_pk_mul_f32 v[40:41], v[46:47], v[44:45]
	s_nop 0
	v_mul_f32_e32 v40, v40, v41
	v_lshlrev_b32_e32 v45, 16, v77
	v_cvt_pk_bf16_f32 v40, v2, v40
	v_mul_f32_e32 v2, 0xbfb8aa3b, v45
	v_exp_f32_e32 v2, v2
	v_mov_b32_e32 v46, v42
	v_mov_b32_e32 v44, v74
	v_add_f32_e32 v2, 1.0, v2
	v_rcp_f32_e32 v47, v2
	s_nop 0
	v_pk_mul_f32 v[44:45], v[46:47], v[44:45]
	s_nop 0
	v_mul_f32_e32 v2, v44, v45
	v_and_b32_e32 v45, 0xffff0000, v77
	v_mul_f32_e32 v41, 0xbfb8aa3b, v45
	v_exp_f32_e32 v41, v41
	v_mov_b32_e32 v46, v43
	v_mov_b32_e32 v44, v75
	v_add_f32_e32 v41, 1.0, v41
	v_rcp_f32_e32 v47, v41
	s_nop 0
	v_pk_mul_f32 v[42:43], v[46:47], v[44:45]
	s_nop 0
	v_mul_f32_e32 v41, v42, v43
	v_lshlrev_b32_e32 v43, 16, v78
	v_cvt_pk_bf16_f32 v41, v2, v41
	v_mul_f32_e32 v2, 0xbfb8aa3b, v43
	v_exp_f32_e32 v2, v2
	v_mov_b32_e32 v44, v36
	v_mov_b32_e32 v42, v68
	v_add_f32_e32 v2, 1.0, v2
	v_rcp_f32_e32 v45, v2
	s_nop 0
	v_pk_mul_f32 v[42:43], v[44:45], v[42:43]
	s_nop 0
	v_mul_f32_e32 v2, v42, v43
	v_and_b32_e32 v43, 0xffff0000, v78
	v_mul_f32_e32 v36, 0xbfb8aa3b, v43
	v_exp_f32_e32 v36, v36
	v_mov_b32_e32 v44, v37
	v_mov_b32_e32 v42, v69
	v_add_f32_e32 v36, 1.0, v36
	v_rcp_f32_e32 v45, v36
	s_nop 0
	v_pk_mul_f32 v[36:37], v[44:45], v[42:43]
	s_nop 0
	v_mul_f32_e32 v36, v36, v37
	v_lshlrev_b32_e32 v37, 16, v79
	v_cvt_pk_bf16_f32 v42, v2, v36
	v_mul_f32_e32 v2, 0xbfb8aa3b, v37
	v_exp_f32_e32 v2, v2
	v_mov_b32_e32 v44, v38
	v_mov_b32_e32 v36, v70
	v_add_f32_e32 v2, 1.0, v2
	v_rcp_f32_e32 v45, v2
	s_nop 0
	v_pk_mul_f32 v[36:37], v[44:45], v[36:37]
	s_nop 0
	v_mul_f32_e32 v2, v36, v37
	v_and_b32_e32 v37, 0xffff0000, v79
	v_mul_f32_e32 v36, 0xbfb8aa3b, v37
	v_exp_f32_e32 v36, v36
	v_mov_b32_e32 v44, v39
	v_add_f32_e32 v36, 1.0, v36
	v_rcp_f32_e32 v45, v36
	v_mov_b32_e32 v36, v71
	v_pk_mul_f32 v[36:37], v[44:45], v[36:37]
	s_nop 0
	v_mul_f32_e32 v36, v36, v37
	v_cvt_pk_bf16_f32 v43, v2, v36
	flat_store_dwordx4 v[126:127], v[40:43] offset:256
	v_lshl_add_u64 v[36:37], v[94:95], 0, v[130:131]
	flat_load_dwordx4 v[48:51], v[36:37]
	v_lshl_add_u64 v[36:37], v[94:95], 0, v[132:133]
	flat_load_dwordx4 v[44:47], v[36:37]
	v_lshl_add_u64 v[36:37], v[94:95], 0, v[134:135]
	flat_load_dwordx4 v[40:43], v[36:37]
	v_lshl_add_u64 v[36:37], v[94:95], 0, v[138:139]
	flat_load_dwordx4 v[36:39], v[36:37]
	s_waitcnt vmcnt(0) lgkmcnt(0)
; __device__ __forceinline__ float bflo(unsigned v) { return __uint_as_float(v << 16); }
; __device__ __forceinline__ float bfhi(unsigned v) { return __uint_as_float(v & 0xffff0000u); }
; __device__ __forceinline__ float siluf_(float x) { return x * __builtin_amdgcn_rcpf(1.0f + __expf(-x)); }
; template <class Epi, class AddrA, class AddrB>
; __device__ __forceinline__ void gemm_phase(const Sched S, const int lda, const int ldb, const int K, const AddrA addrA,
;                                            const AddrB addrB, const Epi E) {
;     ...
;     if (!has_next) break;
;   __device__ __forceinline__ void operator()(EPI_ARGS) const {
;     ...
;         for (int m = 0; m < 4; ++m) {
;           const size_t row = row0 + ai * HALF + m * 16;
;           const f32x4 v0 = acc[ai][bj][m][0], v1 = acc[ai][bj][m][1];
;           u32x4 o;
;           o.x = pack2(v0[0] * s0[0] * siluf_(bflo(z[m].x)), v0[1] * s0[1] * siluf_(bfhi(z[m].x)));
;           o.y = pack2(v0[2] * s0[2] * siluf_(bflo(z[m].y)), v0[3] * s0[3] * siluf_(bfhi(z[m].y)));
;           o.z = pack2(v1[0] * s1[0] * siluf_(bflo(z[m].z)), v1[1] * s1[1] * siluf_(bfhi(z[m].z)));
;           o.w = pack2(v1[2] * s1[2] * siluf_(bflo(z[m].w)), v1[3] * s1[3] * siluf_(bfhi(z[m].w)));
;           *(u32x4*)(y0 + row * DM + c) = o;
;         }
	v_lshlrev_b32_e32 v53, 16, v48
	v_mul_f32_e32 v2, 0xbfb8aa3b, v53
	v_exp_f32_e32 v2, v2
	v_mov_b32_e32 v54, v32
	v_mov_b32_e32 v52, v72
	s_and_b64 vcc, exec, s[18:19]
	v_add_f32_e32 v2, 1.0, v2
	v_rcp_f32_e32 v55, v2
	s_mov_b32 s33, s16
	s_mov_b32 s2, s14
	s_mov_b64 s[4:5], s[22:23]
	v_pk_mul_f32 v[52:53], v[54:55], v[52:53]
	v_mov_b32_e32 v54, v33
	v_mul_f32_e32 v2, v52, v53
	v_and_b32_e32 v53, 0xffff0000, v48
	v_mul_f32_e32 v32, 0xbfb8aa3b, v53
	v_exp_f32_e32 v32, v32
	v_mov_b32_e32 v52, v73
	v_mov_b32_e32 v48, v75
	s_mov_b64 s[6:7], s[20:21]
	v_add_f32_e32 v32, 1.0, v32
	v_rcp_f32_e32 v55, v32
	s_nop 0
	v_pk_mul_f32 v[32:33], v[54:55], v[52:53]
	s_nop 0
	v_mul_f32_e32 v32, v32, v33
	v_lshlrev_b32_e32 v53, 16, v49
	v_cvt_pk_bf16_f32 v32, v2, v32
	v_mul_f32_e32 v2, 0xbfb8aa3b, v53
	v_exp_f32_e32 v2, v2
	v_and_b32_e32 v49, 0xffff0000, v49
	v_mul_f32_e32 v33, 0xbfb8aa3b, v49
	v_exp_f32_e32 v33, v33
	v_add_f32_e32 v2, 1.0, v2
	v_rcp_f32_e32 v55, v2
	v_mov_b32_e32 v54, v34
	v_mov_b32_e32 v52, v74
	v_add_f32_e32 v33, 1.0, v33
	v_pk_mul_f32 v[52:53], v[54:55], v[52:53]
	s_nop 0
	v_mul_f32_e32 v2, v52, v53
	v_rcp_f32_e32 v53, v33
	v_mov_b32_e32 v52, v35
	v_pk_mul_f32 v[34:35], v[52:53], v[48:49]
	s_nop 0
	v_mul_f32_e32 v33, v34, v35
	v_lshlrev_b32_e32 v35, 16, v50
	v_cvt_pk_bf16_f32 v33, v2, v33
	v_mul_f32_e32 v2, 0xbfb8aa3b, v35
	v_exp_f32_e32 v2, v2
	v_mov_b32_e32 v48, v28
	v_mov_b32_e32 v34, v68
	v_add_f32_e32 v2, 1.0, v2
	v_rcp_f32_e32 v49, v2
	s_nop 0
	v_pk_mul_f32 v[34:35], v[48:49], v[34:35]
	s_nop 0
	v_mul_f32_e32 v2, v34, v35
	v_and_b32_e32 v35, 0xffff0000, v50
	v_mul_f32_e32 v28, 0xbfb8aa3b, v35
	v_exp_f32_e32 v28, v28
	v_mov_b32_e32 v48, v29
	v_mov_b32_e32 v34, v69
	v_add_f32_e32 v28, 1.0, v28
	v_rcp_f32_e32 v49, v28
	s_nop 0
	v_pk_mul_f32 v[28:29], v[48:49], v[34:35]
	s_nop 0
	v_mul_f32_e32 v28, v28, v29
	v_lshlrev_b32_e32 v29, 16, v51
	v_cvt_pk_bf16_f32 v34, v2, v28
	v_mul_f32_e32 v2, 0xbfb8aa3b, v29
	v_exp_f32_e32 v2, v2
	v_mov_b32_e32 v48, v30
	v_mov_b32_e32 v28, v70
	v_mov_b32_e32 v30, v24
	v_add_f32_e32 v2, 1.0, v2
	v_rcp_f32_e32 v49, v2
	s_nop 0
	v_pk_mul_f32 v[28:29], v[48:49], v[28:29]
	s_nop 0
	v_mul_f32_e32 v2, v28, v29
	v_and_b32_e32 v29, 0xffff0000, v51
	v_mul_f32_e32 v28, 0xbfb8aa3b, v29
	v_exp_f32_e32 v28, v28
	v_mov_b32_e32 v48, v31
	v_add_f32_e32 v28, 1.0, v28
	v_rcp_f32_e32 v49, v28
	v_mov_b32_e32 v28, v71
	v_pk_mul_f32 v[28:29], v[48:49], v[28:29]
	s_nop 0
	v_mul_f32_e32 v28, v28, v29
	v_lshlrev_b32_e32 v29, 16, v44
	v_cvt_pk_bf16_f32 v35, v2, v28
	v_mul_f32_e32 v2, 0xbfb8aa3b, v29
	v_exp_f32_e32 v2, v2
	v_mov_b32_e32 v28, v72
	flat_store_dwordx4 v[96:97], v[32:35] offset:256
	v_add_f32_e32 v2, 1.0, v2
	v_rcp_f32_e32 v31, v2
	s_nop 0
	v_pk_mul_f32 v[28:29], v[30:31], v[28:29]
	s_nop 0
	v_mul_f32_e32 v2, v28, v29
	v_and_b32_e32 v29, 0xffff0000, v44
	v_mul_f32_e32 v24, 0xbfb8aa3b, v29
	v_exp_f32_e32 v24, v24
	v_mov_b32_e32 v30, v25
	v_mov_b32_e32 v28, v73
	v_add_f32_e32 v24, 1.0, v24
	v_rcp_f32_e32 v31, v24
	s_nop 0
	v_pk_mul_f32 v[24:25], v[30:31], v[28:29]
	s_nop 0
	v_mul_f32_e32 v24, v24, v25
	v_lshlrev_b32_e32 v29, 16, v45
	v_cvt_pk_bf16_f32 v24, v2, v24
	v_mul_f32_e32 v2, 0xbfb8aa3b, v29
	v_exp_f32_e32 v2, v2
	v_mov_b32_e32 v30, v26
	v_mov_b32_e32 v28, v74
	v_add_f32_e32 v2, 1.0, v2
	v_rcp_f32_e32 v31, v2
	s_nop 0
	v_pk_mul_f32 v[28:29], v[30:31], v[28:29]
	s_nop 0
	v_mul_f32_e32 v2, v28, v29
	v_and_b32_e32 v29, 0xffff0000, v45
	v_mul_f32_e32 v25, 0xbfb8aa3b, v29
	v_exp_f32_e32 v25, v25
	v_mov_b32_e32 v30, v27
	v_mov_b32_e32 v28, v75
	v_add_f32_e32 v25, 1.0, v25
	v_rcp_f32_e32 v31, v25
	s_nop 0
	v_pk_mul_f32 v[26:27], v[30:31], v[28:29]
	s_nop 0
	v_mul_f32_e32 v25, v26, v27
	v_lshlrev_b32_e32 v27, 16, v46
	v_cvt_pk_bf16_f32 v25, v2, v25
	v_mul_f32_e32 v2, 0xbfb8aa3b, v27
	v_exp_f32_e32 v2, v2
	v_mov_b32_e32 v28, v20
	v_mov_b32_e32 v26, v68
	v_add_f32_e32 v2, 1.0, v2
	v_rcp_f32_e32 v29, v2
	s_nop 0
	v_pk_mul_f32 v[26:27], v[28:29], v[26:27]
	s_nop 0
	v_mul_f32_e32 v2, v26, v27
	v_and_b32_e32 v27, 0xffff0000, v46
	v_mul_f32_e32 v20, 0xbfb8aa3b, v27
	v_exp_f32_e32 v20, v20
	v_mov_b32_e32 v28, v21
	v_mov_b32_e32 v26, v69
	v_add_f32_e32 v20, 1.0, v20
	v_rcp_f32_e32 v29, v20
	s_nop 0
	v_pk_mul_f32 v[20:21], v[28:29], v[26:27]
	s_nop 0
	v_mul_f32_e32 v20, v20, v21
	v_lshlrev_b32_e32 v21, 16, v47
	v_cvt_pk_bf16_f32 v26, v2, v20
	v_mul_f32_e32 v2, 0xbfb8aa3b, v21
	v_exp_f32_e32 v2, v2
	v_mov_b32_e32 v28, v22
	v_mov_b32_e32 v20, v70
	v_mov_b32_e32 v22, v16
	v_add_f32_e32 v2, 1.0, v2
	v_rcp_f32_e32 v29, v2
	s_nop 0
	v_pk_mul_f32 v[20:21], v[28:29], v[20:21]
	s_nop 0
	v_mul_f32_e32 v2, v20, v21
	v_and_b32_e32 v21, 0xffff0000, v47
	v_mul_f32_e32 v20, 0xbfb8aa3b, v21
	v_exp_f32_e32 v20, v20
	v_mov_b32_e32 v28, v23
	v_add_f32_e32 v20, 1.0, v20
	v_rcp_f32_e32 v29, v20
	v_mov_b32_e32 v20, v71
	v_pk_mul_f32 v[20:21], v[28:29], v[20:21]
	s_nop 0
	v_mul_f32_e32 v20, v20, v21
	v_lshlrev_b32_e32 v21, 16, v40
	v_cvt_pk_bf16_f32 v27, v2, v20
	v_mul_f32_e32 v2, 0xbfb8aa3b, v21
	v_exp_f32_e32 v2, v2
	v_mov_b32_e32 v20, v72
	flat_store_dwordx4 v[98:99], v[24:27] offset:256
; __device__ __forceinline__ float bflo(unsigned v) { return __uint_as_float(v << 16); }
; __device__ __forceinline__ float bfhi(unsigned v) { return __uint_as_float(v & 0xffff0000u); }
; __device__ __forceinline__ float siluf_(float x) { return x * __builtin_amdgcn_rcpf(1.0f + __expf(-x)); }
; #define PG8_WAIT_V(n) asm volatile("s_waitcnt vmcnt(" #n ")" ::: "memory")
; #define PG8_BAR __builtin_amdgcn_s_barrier()
; template <class Epi, class AddrA, class AddrB>
; __device__ __forceinline__ void gemm_phase(const Sched S, const int lda, const int ldb, const int K, const AddrA addrA,
;                                            const AddrB addrB, const Epi E) {
;     ...
;   PG8_WAIT_V(0);
;   if (wr == 0) PG8_BAR;
;   PG8_BAR;
;   __device__ __forceinline__ void operator()(EPI_ARGS) const {
;     ...
;         for (int m = 0; m < 4; ++m) {
;           const size_t row = row0 + ai * HALF + m * 16;
;           const f32x4 v0 = acc[ai][bj][m][0], v1 = acc[ai][bj][m][1];
;           u32x4 o;
;           o.x = pack2(v0[0] * s0[0] * siluf_(bflo(z[m].x)), v0[1] * s0[1] * siluf_(bfhi(z[m].x)));
;           o.y = pack2(v0[2] * s0[2] * siluf_(bflo(z[m].y)), v0[3] * s0[3] * siluf_(bfhi(z[m].y)));
;           o.z = pack2(v1[0] * s1[0] * siluf_(bflo(z[m].z)), v1[1] * s1[1] * siluf_(bfhi(z[m].z)));
;           o.w = pack2(v1[2] * s1[2] * siluf_(bflo(z[m].w)), v1[3] * s1[3] * siluf_(bfhi(z[m].w)));
;           *(u32x4*)(y0 + row * DM + c) = o;
;         }
	v_add_f32_e32 v2, 1.0, v2
	v_rcp_f32_e32 v23, v2
	s_nop 0
	v_pk_mul_f32 v[20:21], v[22:23], v[20:21]
	s_nop 0
	v_mul_f32_e32 v2, v20, v21
	v_and_b32_e32 v21, 0xffff0000, v40
	v_mul_f32_e32 v16, 0xbfb8aa3b, v21
	v_exp_f32_e32 v16, v16
	v_mov_b32_e32 v22, v17
	v_mov_b32_e32 v20, v73
	v_add_f32_e32 v16, 1.0, v16
	v_rcp_f32_e32 v23, v16
	s_nop 0
	v_pk_mul_f32 v[16:17], v[22:23], v[20:21]
	s_nop 0
	v_mul_f32_e32 v16, v16, v17
	v_lshlrev_b32_e32 v21, 16, v41
	v_cvt_pk_bf16_f32 v16, v2, v16
	v_mul_f32_e32 v2, 0xbfb8aa3b, v21
	v_exp_f32_e32 v2, v2
	v_mov_b32_e32 v22, v18
	v_mov_b32_e32 v20, v74
	v_add_f32_e32 v2, 1.0, v2
	v_rcp_f32_e32 v23, v2
	s_nop 0
	v_pk_mul_f32 v[20:21], v[22:23], v[20:21]
	s_nop 0
	v_mul_f32_e32 v2, v20, v21
	v_and_b32_e32 v21, 0xffff0000, v41
	v_mul_f32_e32 v17, 0xbfb8aa3b, v21
	v_exp_f32_e32 v17, v17
	v_mov_b32_e32 v22, v19
	v_mov_b32_e32 v20, v75
	v_add_f32_e32 v17, 1.0, v17
	v_rcp_f32_e32 v23, v17
	s_nop 0
	v_pk_mul_f32 v[18:19], v[22:23], v[20:21]
	s_nop 0
	v_mul_f32_e32 v17, v18, v19
	v_lshlrev_b32_e32 v19, 16, v42
	v_cvt_pk_bf16_f32 v17, v2, v17
	v_mul_f32_e32 v2, 0xbfb8aa3b, v19
	v_exp_f32_e32 v2, v2
	v_mov_b32_e32 v20, v12
	v_mov_b32_e32 v18, v68
	v_add_f32_e32 v2, 1.0, v2
	v_rcp_f32_e32 v21, v2
	s_nop 0
	v_pk_mul_f32 v[18:19], v[20:21], v[18:19]
	s_nop 0
	v_mul_f32_e32 v2, v18, v19
	v_and_b32_e32 v19, 0xffff0000, v42
	v_mul_f32_e32 v12, 0xbfb8aa3b, v19
	v_exp_f32_e32 v12, v12
	v_mov_b32_e32 v20, v13
	v_mov_b32_e32 v18, v69
	v_add_f32_e32 v12, 1.0, v12
	v_rcp_f32_e32 v21, v12
	s_nop 0
	v_pk_mul_f32 v[12:13], v[20:21], v[18:19]
	s_nop 0
	v_mul_f32_e32 v12, v12, v13
	v_lshlrev_b32_e32 v13, 16, v43
	v_cvt_pk_bf16_f32 v18, v2, v12
	v_mul_f32_e32 v2, 0xbfb8aa3b, v13
	v_exp_f32_e32 v2, v2
	v_mov_b32_e32 v20, v14
	v_mov_b32_e32 v12, v70
	v_mov_b32_e32 v14, v8
	v_add_f32_e32 v2, 1.0, v2
	v_rcp_f32_e32 v21, v2
	s_nop 0
	v_pk_mul_f32 v[12:13], v[20:21], v[12:13]
	s_nop 0
	v_mul_f32_e32 v2, v12, v13
	v_and_b32_e32 v13, 0xffff0000, v43
	v_mul_f32_e32 v12, 0xbfb8aa3b, v13
	v_exp_f32_e32 v12, v12
	v_mov_b32_e32 v20, v15
	v_add_f32_e32 v12, 1.0, v12
	v_rcp_f32_e32 v21, v12
	v_mov_b32_e32 v12, v71
	v_pk_mul_f32 v[12:13], v[20:21], v[12:13]
	s_nop 0
	v_mul_f32_e32 v12, v12, v13
	v_lshlrev_b32_e32 v13, 16, v36
	v_cvt_pk_bf16_f32 v19, v2, v12
	v_mul_f32_e32 v2, 0xbfb8aa3b, v13
	v_exp_f32_e32 v2, v2
	v_mov_b32_e32 v12, v72
	flat_store_dwordx4 v[104:105], v[16:19] offset:256
	v_add_f32_e32 v2, 1.0, v2
	v_rcp_f32_e32 v15, v2
	s_nop 0
	v_pk_mul_f32 v[12:13], v[14:15], v[12:13]
	s_nop 0
	v_mul_f32_e32 v2, v12, v13
	v_and_b32_e32 v13, 0xffff0000, v36
	v_mul_f32_e32 v8, 0xbfb8aa3b, v13
	v_exp_f32_e32 v8, v8
	v_mov_b32_e32 v14, v9
	v_mov_b32_e32 v12, v73
	v_add_f32_e32 v8, 1.0, v8
	v_rcp_f32_e32 v15, v8
	s_nop 0
	v_pk_mul_f32 v[8:9], v[14:15], v[12:13]
	s_nop 0
	v_mul_f32_e32 v8, v8, v9
	v_lshlrev_b32_e32 v13, 16, v37
	v_cvt_pk_bf16_f32 v8, v2, v8
	v_mul_f32_e32 v2, 0xbfb8aa3b, v13
	v_exp_f32_e32 v2, v2
	v_mov_b32_e32 v14, v10
	v_mov_b32_e32 v12, v74
	v_add_f32_e32 v2, 1.0, v2
	v_rcp_f32_e32 v15, v2
	s_nop 0
	v_pk_mul_f32 v[12:13], v[14:15], v[12:13]
	s_nop 0
	v_mul_f32_e32 v2, v12, v13
	v_and_b32_e32 v13, 0xffff0000, v37
	v_mul_f32_e32 v9, 0xbfb8aa3b, v13
	v_exp_f32_e32 v9, v9
	v_mov_b32_e32 v14, v11
	v_mov_b32_e32 v12, v75
	v_add_f32_e32 v9, 1.0, v9
	v_rcp_f32_e32 v15, v9
	s_nop 0
	v_pk_mul_f32 v[10:11], v[14:15], v[12:13]
	s_nop 0
	v_mul_f32_e32 v9, v10, v11
	v_lshlrev_b32_e32 v11, 16, v38
	v_cvt_pk_bf16_f32 v9, v2, v9
	v_mul_f32_e32 v2, 0xbfb8aa3b, v11
	v_exp_f32_e32 v2, v2
	v_mov_b32_e32 v12, v4
	v_mov_b32_e32 v10, v68
	v_add_f32_e32 v2, 1.0, v2
	v_rcp_f32_e32 v13, v2
	s_nop 0
	v_pk_mul_f32 v[10:11], v[12:13], v[10:11]
	s_nop 0
	v_mul_f32_e32 v2, v10, v11
	v_and_b32_e32 v11, 0xffff0000, v38
	v_mul_f32_e32 v4, 0xbfb8aa3b, v11
	v_exp_f32_e32 v4, v4
	v_mov_b32_e32 v12, v5
	v_mov_b32_e32 v10, v69
	v_add_f32_e32 v4, 1.0, v4
	v_rcp_f32_e32 v13, v4
	s_nop 0
	v_pk_mul_f32 v[4:5], v[12:13], v[10:11]
	s_nop 0
	v_mul_f32_e32 v4, v4, v5
	v_lshlrev_b32_e32 v5, 16, v39
	v_cvt_pk_bf16_f32 v10, v2, v4
	v_mul_f32_e32 v2, 0xbfb8aa3b, v5
	v_exp_f32_e32 v2, v2
	v_mov_b32_e32 v12, v6
	v_mov_b32_e32 v4, v70
	v_add_f32_e32 v2, 1.0, v2
	v_rcp_f32_e32 v13, v2
	s_nop 0
	v_pk_mul_f32 v[4:5], v[12:13], v[4:5]
	s_nop 0
	v_mul_f32_e32 v2, v4, v5
	v_and_b32_e32 v5, 0xffff0000, v39
	v_mul_f32_e32 v4, 0xbfb8aa3b, v5
	v_exp_f32_e32 v4, v4
	v_mov_b32_e32 v12, v7
	v_add_f32_e32 v4, 1.0, v4
	v_rcp_f32_e32 v13, v4
	v_mov_b32_e32 v4, v71
	v_pk_mul_f32 v[4:5], v[12:13], v[4:5]
	s_nop 0
	v_mul_f32_e32 v4, v4, v5
	v_cvt_pk_bf16_f32 v11, v2, v4
	flat_store_dwordx4 v[92:93], v[8:11] offset:256
	s_cbranch_vccz .LBB0_482
	s_waitcnt vmcnt(0)
	v_readlane_b32 s44, v244, 59
	v_readlane_b32 s40, v243, 18
	s_cmpk_gt_u32 s24, 0xff
	s_mov_b32 s43, 0x800000
	v_readlane_b32 s45, v244, 60
	v_readlane_b32 s46, v244, 61
	v_readlane_b32 s47, v244, 62
	v_readlane_b32 s48, v244, 63
	v_readlane_b32 s49, v243, 0
	v_readlane_b32 s50, v243, 1
	v_readlane_b32 s51, v243, 2
	v_readlane_b32 s41, v243, 19
	s_cbranch_scc1 .LBB0_489
	s_barrier

; #define PG8_WAIT_V(n) asm volatile("s_waitcnt vmcnt(" #n ")" ::: "memory")
; #define PG8_WAIT_L(n) asm volatile("s_waitcnt lgkmcnt(" #n ")" ::: "memory")
; #define PG8_BAR __builtin_amdgcn_s_barrier()
; #define PG8_SCHED __builtin_amdgcn_sched_barrier(0)
; template <class Epi, class AddrA, class AddrB>
; __device__ __forceinline__ void gemm_phase(const Sched S, const int lda, const int ldb, const int K, const AddrA addrA,
;                                            const AddrB addrB, const Epi E) {
;     ...
;       PG8_LDB(B0, 0, 0); PG8_SCHED; PG8_LDA(At, 0, 0); PG8_STAGE(PG8_SA(1, 1), a1 + hstepA, voffA);
;       PG8_WAIT_L(8); PG8_BAR; PG8_WAIT_L(0); PG8_MMA(0, 0, At, B0); PG8_BAR; PG8_SCHED;
;       PG8_LDB(B1, 0, 1); PG8_STAGE(PG8_SB(0, 0), b2, voffB);
;       PG8_BAR; PG8_WAIT_L(0); PG8_MMA(0, 1, At, B1); PG8_BAR;
;       PG8_LDA(At, 0, 1); PG8_STAGE(PG8_SA(0, 0), a2, voffA);
;       PG8_BAR; PG8_WAIT_L(0); PG8_MMA(1, 0, At, B0); PG8_BAR; PG8_SCHED;
;       PG8_STAGE(PG8_SB(0, 1), b2 + hstepB, voffB);
;       PG8_WAIT_V(6); PG8_BAR; PG8_MMA(1, 1, At, B1); PG8_BAR;
.LBB0_543:
	s_add_i32 s43, 0, 0x10000
	v_add_u32_e32 v0, s43, v167
	ds_read_b128 v[132:135], v0
	ds_read_b128 v[136:139], v0 offset:1024
	ds_read_b128 v[140:143], v0 offset:2048
	ds_read_b128 v[144:147], v0 offset:3072
	s_add_i32 m0, s28, 0xc000
	ds_read_b128 v[148:151], v188
	ds_read_b128 v[152:155], v188 offset:1024
	ds_read_b128 v[156:159], v188 offset:2048
	ds_read_b128 v[160:163], v188 offset:3072
	ds_read_b128 v[182:185], v188 offset:4096
	ds_read_b128 v[190:193], v188 offset:5120
	ds_read_b128 v[194:197], v188 offset:6144
	ds_read_b128 v[212:215], v188 offset:7168
	global_load_lds_dwordx4 v180, s[2:3]
	s_add_i32 m0, s28, 0xe000
	s_nop 0
	global_load_lds_dwordx4 v178, s[2:3]
	s_waitcnt lgkmcnt(6)
	s_setprio 1
	s_barrier
	v_mfma_f32_16x16x32_bf16 v[128:131], v[132:135], v[148:151], v[128:131]
	v_mfma_f32_16x16x32_bf16 v[128:131], v[136:139], v[152:155], v[128:131]
	s_waitcnt lgkmcnt(0)
	v_mfma_f32_16x16x32_bf16 v[120:123], v[132:135], v[156:159], v[120:123]
	v_mfma_f32_16x16x32_bf16 v[120:123], v[136:139], v[160:163], v[120:123]
	v_mfma_f32_16x16x32_bf16 v[112:115], v[132:135], v[182:185], v[112:115]
	v_mfma_f32_16x16x32_bf16 v[112:115], v[136:139], v[190:193], v[112:115]
	v_mfma_f32_16x16x32_bf16 v[104:107], v[132:135], v[194:197], v[104:107]
	v_mfma_f32_16x16x32_bf16 v[104:107], v[136:139], v[212:215], v[104:107]
	v_mfma_f32_16x16x32_bf16 v[124:127], v[140:143], v[148:151], v[124:127]
	v_mfma_f32_16x16x32_bf16 v[124:127], v[144:147], v[152:155], v[124:127]
	v_mfma_f32_16x16x32_bf16 v[116:119], v[140:143], v[156:159], v[116:119]
	v_mfma_f32_16x16x32_bf16 v[116:119], v[144:147], v[160:163], v[116:119]
	v_mfma_f32_16x16x32_bf16 v[108:111], v[140:143], v[182:185], v[108:111]
	v_mfma_f32_16x16x32_bf16 v[108:111], v[144:147], v[190:193], v[108:111]
	v_mfma_f32_16x16x32_bf16 v[100:103], v[140:143], v[194:197], v[100:103]
	v_mfma_f32_16x16x32_bf16 v[100:103], v[144:147], v[212:215], v[100:103]
	s_barrier
	s_setprio 0
	s_add_u32 s4, s2, 0xfff80080
	s_addc_u32 s5, s3, -1
	s_cmp_eq_u32 s42, 28
	s_cselect_b32 s7, s1, s5
	s_cselect_b32 s6, s9, s4
	s_cselect_b32 s5, s13, s41
	s_cselect_b32 s4, s15, s33
	s_add_i32 s46, 0, 0x14000
	v_add_u32_e32 v0, s46, v167
	s_add_i32 s43, s43, s27
	ds_read_b128 v[216:219], v0
	ds_read_b128 v[220:223], v0 offset:1024
	ds_read_b128 v[224:227], v0 offset:2048
	ds_read_b128 v[228:231], v0 offset:3072
	s_add_u32 s98, s4, 0x80
	s_addc_u32 s99, s5, 0
	s_mov_b32 m0, s43
	s_nop 0
	global_load_lds_dwordx4 v172, s[4:5]
	s_add_i32 m0, s43, 0x2000
	s_nop 0
	global_load_lds_dwordx4 v168, s[4:5]
	s_mov_b32 m0, s28
	s_add_u32 s100, s6, 0x80
	s_addc_u32 s101, s7, 0
	s_waitcnt lgkmcnt(2)
	s_setprio 1
	s_barrier
	v_mfma_f32_16x16x32_bf16 v[96:99], v[216:219], v[148:151], v[96:99]
	v_mfma_f32_16x16x32_bf16 v[96:99], v[220:223], v[152:155], v[96:99]
	s_waitcnt lgkmcnt(0)
	v_mfma_f32_16x16x32_bf16 v[88:91], v[216:219], v[156:159], v[88:91]
	v_mfma_f32_16x16x32_bf16 v[88:91], v[220:223], v[160:163], v[88:91]
	v_mfma_f32_16x16x32_bf16 v[80:83], v[216:219], v[182:185], v[80:83]
	v_mfma_f32_16x16x32_bf16 v[80:83], v[220:223], v[190:193], v[80:83]
	v_mfma_f32_16x16x32_bf16 v[72:75], v[216:219], v[194:197], v[72:75]
	v_mfma_f32_16x16x32_bf16 v[72:75], v[220:223], v[212:215], v[72:75]
	v_mfma_f32_16x16x32_bf16 v[92:95], v[224:227], v[148:151], v[92:95]
	v_mfma_f32_16x16x32_bf16 v[92:95], v[228:231], v[152:155], v[92:95]
	v_mfma_f32_16x16x32_bf16 v[84:87], v[224:227], v[156:159], v[84:87]
	v_mfma_f32_16x16x32_bf16 v[84:87], v[228:231], v[160:163], v[84:87]
	v_mfma_f32_16x16x32_bf16 v[76:79], v[224:227], v[182:185], v[76:79]
	v_mfma_f32_16x16x32_bf16 v[76:79], v[228:231], v[190:193], v[76:79]
	v_mfma_f32_16x16x32_bf16 v[68:71], v[224:227], v[194:197], v[68:71]
	v_mfma_f32_16x16x32_bf16 v[68:71], v[228:231], v[212:215], v[68:71]
	s_barrier
	s_setprio 0
	ds_read_b128 v[148:151], v188 offset:16384
	ds_read_b128 v[152:155], v188 offset:17408
	ds_read_b128 v[156:159], v188 offset:18432
	ds_read_b128 v[160:163], v188 offset:19456
	ds_read_b128 v[182:185], v188 offset:20480
	ds_read_b128 v[190:193], v188 offset:21504
	ds_read_b128 v[194:197], v188 offset:22528
	ds_read_b128 v[212:215], v188 offset:23552
	global_load_lds_dwordx4 v174, s[6:7]
	s_mov_b32 m0, s29
	s_nop 0
	global_load_lds_dwordx4 v170, s[6:7]
	s_waitcnt lgkmcnt(6)
	s_setprio 1
	s_barrier
	v_mfma_f32_16x16x32_bf16 v[64:67], v[132:135], v[148:151], v[64:67]
	v_mfma_f32_16x16x32_bf16 v[64:67], v[136:139], v[152:155], v[64:67]
	s_waitcnt lgkmcnt(0)
	v_mfma_f32_16x16x32_bf16 v[56:59], v[132:135], v[156:159], v[56:59]
	v_mfma_f32_16x16x32_bf16 v[56:59], v[136:139], v[160:163], v[56:59]
	v_mfma_f32_16x16x32_bf16 v[48:51], v[132:135], v[182:185], v[48:51]
	v_mfma_f32_16x16x32_bf16 v[48:51], v[136:139], v[190:193], v[48:51]
	v_mfma_f32_16x16x32_bf16 v[40:43], v[132:135], v[194:197], v[40:43]
	v_mfma_f32_16x16x32_bf16 v[40:43], v[136:139], v[212:215], v[40:43]
	v_mfma_f32_16x16x32_bf16 v[60:63], v[140:143], v[148:151], v[60:63]
	v_mfma_f32_16x16x32_bf16 v[60:63], v[144:147], v[152:155], v[60:63]
	v_mfma_f32_16x16x32_bf16 v[52:55], v[140:143], v[156:159], v[52:55]
	v_mfma_f32_16x16x32_bf16 v[52:55], v[144:147], v[160:163], v[52:55]
	v_mfma_f32_16x16x32_bf16 v[44:47], v[140:143], v[182:185], v[44:47]
	v_mfma_f32_16x16x32_bf16 v[44:47], v[144:147], v[190:193], v[44:47]
	v_mfma_f32_16x16x32_bf16 v[36:39], v[140:143], v[194:197], v[36:39]
	v_mfma_f32_16x16x32_bf16 v[36:39], v[144:147], v[212:215], v[36:39]
	s_barrier
	s_setprio 0
	s_add_u32 s44, s4, 0x80000
	s_addc_u32 s45, s5, 0
	s_add_i32 s43, s46, s27
	s_mov_b32 m0, s43
	s_nop 0
	global_load_lds_dwordx4 v172, s[44:45]
	s_add_i32 m0, s43, 0x2000
	s_nop 0
	global_load_lds_dwordx4 v168, s[44:45]
	s_add_i32 s43, 0, 0x18000
	v_add_u32_e32 v2, s43, v167
	s_waitcnt vmcnt(6)
	s_setprio 1
	s_barrier
; #define PG8_WAIT_V(n) asm volatile("s_waitcnt vmcnt(" #n ")" ::: "memory")
; #define PG8_WAIT_L(n) asm volatile("s_waitcnt lgkmcnt(" #n ")" ::: "memory")
; #define PG8_BAR __builtin_amdgcn_s_barrier()
; #define PG8_SCHED __builtin_amdgcn_sched_barrier(0)
; template <class Epi, class AddrA, class AddrB>
; __device__ __forceinline__ void gemm_phase(const Sched S, const int lda, const int ldb, const int K, const AddrA addrA,
;                                            const AddrB addrB, const Epi E) {
;     ...
;       PG8_LDA(At, 0, 1); PG8_STAGE(PG8_SA(0, 0), a2, voffA);
;       PG8_BAR; PG8_WAIT_L(0); PG8_MMA(1, 0, At, B0); PG8_BAR; PG8_SCHED;
;       PG8_STAGE(PG8_SB(0, 1), b2 + hstepB, voffB);
;       PG8_WAIT_V(6); PG8_BAR; PG8_MMA(1, 1, At, B1); PG8_BAR;
;       PG8_LDB(B0, 1, 0); PG8_SCHED; PG8_LDA(At, 1, 0); PG8_STAGE(PG8_SA(0, 1), a2 + hstepA, voffA);
;       PG8_WAIT_L(8); PG8_BAR; PG8_WAIT_L(0); PG8_MMA(0, 0, At, B0); PG8_BAR; PG8_SCHED;
;       PG8_LDB(B1, 1, 1); PG8_STAGE(PG8_SB(1, 0), b3, voffB);
;       PG8_BAR; PG8_WAIT_L(0); PG8_MMA(0, 1, At, B1); PG8_BAR;
;       PG8_LDA(At, 1, 1); PG8_STAGE(PG8_SA(1, 0), a3, voffA);
;       PG8_BAR; PG8_WAIT_L(0); PG8_MMA(1, 0, At, B0); PG8_BAR; PG8_SCHED;
	v_mfma_f32_16x16x32_bf16 v[32:35], v[216:219], v[148:151], v[32:35]
	v_mfma_f32_16x16x32_bf16 v[32:35], v[220:223], v[152:155], v[32:35]
	v_mfma_f32_16x16x32_bf16 v[24:27], v[216:219], v[156:159], v[24:27]
	v_mfma_f32_16x16x32_bf16 v[24:27], v[220:223], v[160:163], v[24:27]
	v_mfma_f32_16x16x32_bf16 v[16:19], v[216:219], v[182:185], v[16:19]
	v_mfma_f32_16x16x32_bf16 v[16:19], v[220:223], v[190:193], v[16:19]
	v_mfma_f32_16x16x32_bf16 v[8:11], v[216:219], v[194:197], v[8:11]
	v_mfma_f32_16x16x32_bf16 v[8:11], v[220:223], v[212:215], v[8:11]
	v_mfma_f32_16x16x32_bf16 v[28:31], v[224:227], v[148:151], v[28:31]
	v_mfma_f32_16x16x32_bf16 v[28:31], v[228:231], v[152:155], v[28:31]
	v_mfma_f32_16x16x32_bf16 v[20:23], v[224:227], v[156:159], v[20:23]
	v_mfma_f32_16x16x32_bf16 v[20:23], v[228:231], v[160:163], v[20:23]
	v_mfma_f32_16x16x32_bf16 v[12:15], v[224:227], v[182:185], v[12:15]
	v_mfma_f32_16x16x32_bf16 v[12:15], v[228:231], v[190:193], v[12:15]
	v_mfma_f32_16x16x32_bf16 v[4:7], v[224:227], v[194:197], v[4:7]
	v_mfma_f32_16x16x32_bf16 v[4:7], v[228:231], v[212:215], v[4:7]
	s_barrier
	s_setprio 0
	ds_read_b128 v[132:135], v2
	ds_read_b128 v[136:139], v2 offset:1024
	ds_read_b128 v[140:143], v2 offset:2048
	ds_read_b128 v[144:147], v2 offset:3072
	s_add_u32 s6, s6, 0x80000
	s_addc_u32 s7, s7, 0
	s_mov_b32 m0, s30
	ds_read_b128 v[148:151], v188 offset:32768
	ds_read_b128 v[152:155], v188 offset:33792
	ds_read_b128 v[156:159], v188 offset:34816
	ds_read_b128 v[160:163], v188 offset:35840
	ds_read_b128 v[182:185], v188 offset:36864
	ds_read_b128 v[190:193], v188 offset:37888
	ds_read_b128 v[194:197], v188 offset:38912
	ds_read_b128 v[212:215], v188 offset:39936
	global_load_lds_dwordx4 v174, s[6:7]
	s_mov_b32 m0, s31
	s_nop 0
	global_load_lds_dwordx4 v170, s[6:7]
	s_waitcnt lgkmcnt(6)
	s_setprio 1
	s_barrier
	v_mfma_f32_16x16x32_bf16 v[128:131], v[132:135], v[148:151], v[128:131]
	v_mfma_f32_16x16x32_bf16 v[128:131], v[136:139], v[152:155], v[128:131]
	s_waitcnt lgkmcnt(0)
	v_mfma_f32_16x16x32_bf16 v[120:123], v[132:135], v[156:159], v[120:123]
	v_mfma_f32_16x16x32_bf16 v[120:123], v[136:139], v[160:163], v[120:123]
	v_mfma_f32_16x16x32_bf16 v[112:115], v[132:135], v[182:185], v[112:115]
	v_mfma_f32_16x16x32_bf16 v[112:115], v[136:139], v[190:193], v[112:115]
	v_mfma_f32_16x16x32_bf16 v[104:107], v[132:135], v[194:197], v[104:107]
	v_mfma_f32_16x16x32_bf16 v[104:107], v[136:139], v[212:215], v[104:107]
	v_mfma_f32_16x16x32_bf16 v[124:127], v[140:143], v[148:151], v[124:127]
	v_mfma_f32_16x16x32_bf16 v[124:127], v[144:147], v[152:155], v[124:127]
	v_mfma_f32_16x16x32_bf16 v[116:119], v[140:143], v[156:159], v[116:119]
	v_mfma_f32_16x16x32_bf16 v[116:119], v[144:147], v[160:163], v[116:119]
	v_mfma_f32_16x16x32_bf16 v[108:111], v[140:143], v[182:185], v[108:111]
	v_mfma_f32_16x16x32_bf16 v[108:111], v[144:147], v[190:193], v[108:111]
	v_mfma_f32_16x16x32_bf16 v[100:103], v[140:143], v[194:197], v[100:103]
	v_mfma_f32_16x16x32_bf16 v[100:103], v[144:147], v[212:215], v[100:103]
	s_barrier
	s_setprio 0
	s_add_i32 s6, 0, 0x1c000
	s_add_i32 s7, s43, s27
	v_add_u32_e32 v2, s6, v167
	s_mov_b32 m0, s7
	ds_read_b128 v[216:219], v2
	ds_read_b128 v[220:223], v2 offset:1024
	ds_read_b128 v[224:227], v2 offset:2048
	ds_read_b128 v[228:231], v2 offset:3072
	global_load_lds_dwordx4 v172, s[98:99]
	s_add_i32 m0, s7, 0x2000
	s_nop 0
	global_load_lds_dwordx4 v168, s[98:99]
	s_mov_b32 m0, s38
	s_waitcnt lgkmcnt(2)
	s_setprio 1
	s_barrier
	v_mfma_f32_16x16x32_bf16 v[96:99], v[216:219], v[148:151], v[96:99]
	v_mfma_f32_16x16x32_bf16 v[96:99], v[220:223], v[152:155], v[96:99]
	s_waitcnt lgkmcnt(0)
	v_mfma_f32_16x16x32_bf16 v[88:91], v[216:219], v[156:159], v[88:91]
	v_mfma_f32_16x16x32_bf16 v[88:91], v[220:223], v[160:163], v[88:91]
	v_mfma_f32_16x16x32_bf16 v[80:83], v[216:219], v[182:185], v[80:83]
	v_mfma_f32_16x16x32_bf16 v[80:83], v[220:223], v[190:193], v[80:83]
	v_mfma_f32_16x16x32_bf16 v[72:75], v[216:219], v[194:197], v[72:75]
	v_mfma_f32_16x16x32_bf16 v[72:75], v[220:223], v[212:215], v[72:75]
	v_mfma_f32_16x16x32_bf16 v[92:95], v[224:227], v[148:151], v[92:95]
	v_mfma_f32_16x16x32_bf16 v[92:95], v[228:231], v[152:155], v[92:95]
	v_mfma_f32_16x16x32_bf16 v[84:87], v[224:227], v[156:159], v[84:87]
	v_mfma_f32_16x16x32_bf16 v[84:87], v[228:231], v[160:163], v[84:87]
	v_mfma_f32_16x16x32_bf16 v[76:79], v[224:227], v[182:185], v[76:79]
	v_mfma_f32_16x16x32_bf16 v[76:79], v[228:231], v[190:193], v[76:79]
	v_mfma_f32_16x16x32_bf16 v[68:71], v[224:227], v[194:197], v[68:71]
	v_mfma_f32_16x16x32_bf16 v[68:71], v[228:231], v[212:215], v[68:71]
	s_barrier
	s_setprio 0
	ds_read_b128 v[148:151], v188 offset:49152
	ds_read_b128 v[152:155], v188 offset:50176
	ds_read_b128 v[156:159], v188 offset:51200
	ds_read_b128 v[160:163], v188 offset:52224
	ds_read_b128 v[182:185], v188 offset:53248
	ds_read_b128 v[190:193], v188 offset:54272
	ds_read_b128 v[194:197], v188 offset:55296
	ds_read_b128 v[212:215], v188 offset:56320
	global_load_lds_dwordx4 v174, s[100:101]
	s_mov_b32 m0, s39
	s_nop 0
	global_load_lds_dwordx4 v170, s[100:101]
	s_waitcnt lgkmcnt(6)
	s_setprio 1
	s_barrier
; template <class Epi, class AddrA, class AddrB>
; __device__ __forceinline__ void gemm_phase(const Sched S, const int lda, const int ldb, const int K, const AddrA addrA,
;                                            const AddrB addrB, const Epi E) {
;     ...
;       PG8_LDB(B0, 1, 0); PG8_SCHED; PG8_LDA(At, 1, 0); PG8_STAGE(PG8_SA(0, 1), a2 + hstepA, voffA);
;       PG8_WAIT_L(8); PG8_BAR; PG8_WAIT_L(0); PG8_MMA(0, 0, At, B0); PG8_BAR; PG8_SCHED;
;       PG8_LDB(B1, 1, 1); PG8_STAGE(PG8_SB(1, 0), b3, voffB);
;       PG8_BAR; PG8_WAIT_L(0); PG8_MMA(0, 1, At, B1); PG8_BAR;
;       PG8_LDA(At, 1, 1); PG8_STAGE(PG8_SA(1, 0), a3, voffA);
;       PG8_BAR; PG8_WAIT_L(0); PG8_MMA(1, 0, At, B0); PG8_BAR; PG8_SCHED;
;       PG8_STAGE(PG8_SB(1, 1), b3 + hstepB, voffB);
;       PG8_WAIT_V(6); PG8_BAR; PG8_MMA(1, 1, At, B1); PG8_BAR;
;   __device__ __forceinline__ void operator()(EPI_ARGS) const {
;     const int col0 = u.pn * 256 + wc * 32 + 8 * fq;
;     const int br = u.br, brn = br < 2 ? br + 1 : 2;
;     const unsigned loff0 = (unsigned)((wr * 64 + fr) * PLD + wc * 32 + 8 * fq);
;     const bf16_t* pc = proj + ((size_t)((GT + br * DM) / 256 + u.pn) * MTOK + (size_t)u.pm * 256) * PLD;
;     const bf16_t* pn_ = proj + ((size_t)((GT + brn * DM) / 256 + u.pn) * MTOK + (size_t)u.pm * 256) * PLD;
;     bf16_t* mrow = merged + ((size_t)u.pm * 256 + wr * 64 + fr) * DM + col0;
; #pragma unroll
;     for (int bj = 0; bj < 2; ++bj) {
;       const int c = col0 + bj * HALF;
;       float gc[8], gn[8];
;       {
;         const f32x4 a0 = *(const f32x4*)(bg + br * DM + c), a1 = *(const f32x4*)(bg + br * DM + c + 4);
;         const f32x4 b0 = *(const f32x4*)(bg + brn * DM + c), b1 = *(const f32x4*)(bg + brn * DM + c + 4);
; #pragma unroll
;         for (int k = 0; k < 4; ++k) { gc[k] = a0[k]; gc[4 + k] = a1[k]; gn[k] = b0[k]; gn[4 + k] = b1[k]; }
;       }
; #pragma unroll
;       for (int ai = 0; ai < 2; ++ai) {
;         unsigned loff = loff0;
;         asm volatile("" : "+v"(loff));
;         u32x4 zc[4], zn[4];
; #pragma unroll
;         for (int m = 0; m < 4; ++m) {
;           const unsigned o = loff + (unsigned)((ai * HALF + m * 16) * PLD + bj * HALF);
;           zc[m] = *(const u32x4*)(pc + o);
;           zn[m] = *(const u32x4*)(pn_ + o);
;         }
;         __builtin_amdgcn_sched_barrier(0);
;         if (br < 2) {
; #pragma unroll
;           for (int m = 0; m < 4; ++m) {
	v_mfma_f32_16x16x32_bf16 v[64:67], v[132:135], v[148:151], v[64:67]
	v_mfma_f32_16x16x32_bf16 v[64:67], v[136:139], v[152:155], v[64:67]
	s_waitcnt lgkmcnt(0)
	v_mfma_f32_16x16x32_bf16 v[56:59], v[132:135], v[156:159], v[56:59]
	v_mfma_f32_16x16x32_bf16 v[56:59], v[136:139], v[160:163], v[56:59]
	v_mfma_f32_16x16x32_bf16 v[48:51], v[132:135], v[182:185], v[48:51]
	v_mfma_f32_16x16x32_bf16 v[48:51], v[136:139], v[190:193], v[48:51]
	v_mfma_f32_16x16x32_bf16 v[40:43], v[132:135], v[194:197], v[40:43]
	v_mfma_f32_16x16x32_bf16 v[40:43], v[136:139], v[212:215], v[40:43]
	v_mfma_f32_16x16x32_bf16 v[60:63], v[140:143], v[148:151], v[60:63]
	v_mfma_f32_16x16x32_bf16 v[60:63], v[144:147], v[152:155], v[60:63]
	v_mfma_f32_16x16x32_bf16 v[52:55], v[140:143], v[156:159], v[52:55]
	v_mfma_f32_16x16x32_bf16 v[52:55], v[144:147], v[160:163], v[52:55]
	v_mfma_f32_16x16x32_bf16 v[44:47], v[140:143], v[182:185], v[44:47]
	v_mfma_f32_16x16x32_bf16 v[44:47], v[144:147], v[190:193], v[44:47]
	v_mfma_f32_16x16x32_bf16 v[36:39], v[140:143], v[194:197], v[36:39]
	v_mfma_f32_16x16x32_bf16 v[36:39], v[144:147], v[212:215], v[36:39]
	s_barrier
	s_setprio 0
	s_add_u32 s4, s4, 0x80080
	s_addc_u32 s5, s5, 0
	s_add_i32 s6, s6, s27
	s_mov_b32 m0, s6
	s_nop 0
	global_load_lds_dwordx4 v172, s[4:5]
	s_add_i32 m0, s6, 0x2000
	s_nop 0
	global_load_lds_dwordx4 v168, s[4:5]
	s_add_i32 s42, s42, 2
	s_add_u32 s33, s33, 0x100
	s_addc_u32 s41, s41, 0
	s_add_u32 s2, s2, 0x100
	s_addc_u32 s3, s3, 0
	s_waitcnt vmcnt(6)
	s_setprio 1
	s_barrier
	v_mfma_f32_16x16x32_bf16 v[32:35], v[216:219], v[148:151], v[32:35]
	v_mfma_f32_16x16x32_bf16 v[32:35], v[220:223], v[152:155], v[32:35]
	v_mfma_f32_16x16x32_bf16 v[24:27], v[216:219], v[156:159], v[24:27]
	v_mfma_f32_16x16x32_bf16 v[24:27], v[220:223], v[160:163], v[24:27]
	v_mfma_f32_16x16x32_bf16 v[16:19], v[216:219], v[182:185], v[16:19]
	v_mfma_f32_16x16x32_bf16 v[16:19], v[220:223], v[190:193], v[16:19]
	v_mfma_f32_16x16x32_bf16 v[8:11], v[216:219], v[194:197], v[8:11]
	v_mfma_f32_16x16x32_bf16 v[8:11], v[220:223], v[212:215], v[8:11]
	v_mfma_f32_16x16x32_bf16 v[28:31], v[224:227], v[148:151], v[28:31]
	v_mfma_f32_16x16x32_bf16 v[28:31], v[228:231], v[152:155], v[28:31]
	v_mfma_f32_16x16x32_bf16 v[20:23], v[224:227], v[156:159], v[20:23]
	v_mfma_f32_16x16x32_bf16 v[20:23], v[228:231], v[160:163], v[20:23]
	v_mfma_f32_16x16x32_bf16 v[12:15], v[224:227], v[182:185], v[12:15]
	v_mfma_f32_16x16x32_bf16 v[12:15], v[228:231], v[190:193], v[12:15]
	v_mfma_f32_16x16x32_bf16 v[4:7], v[224:227], v[194:197], v[4:7]
	v_mfma_f32_16x16x32_bf16 v[4:7], v[228:231], v[212:215], v[4:7]
	s_barrier
	s_setprio 0
	s_cmp_gt_u32 s42, 29
	s_cbranch_scc0 .LBB0_543
	s_cmp_gt_i32 s10, 1
	s_cselect_b64 s[6:7], -1, 0
	s_lshl_b32 s42, s10, 11
	s_add_i32 s2, s42, 0x4c00
	s_ashr_i32 s2, s2, 8
	s_add_i32 s2, s2, s11
	s_ashr_i32 s3, s2, 31
	s_min_i32 s1, s10, 1
	s_ashr_i32 s9, s8, 31
	s_lshl_b64 s[2:3], s[2:3], 23
	s_add_u32 s2, s34, s2
	s_addc_u32 s3, s35, s3
	s_lshl_b64 s[4:5], s[8:9], 17
	s_add_u32 s2, s2, s4
	s_addc_u32 s3, s3, s5
	s_lshl_b32 s1, s1, 11
	s_add_i32 s44, s1, 0x800
	s_addk_i32 s1, 0x5400
	s_ashr_i32 s1, s1, 8
	s_add_i32 s46, s1, s11
	s_ashr_i32 s47, s46, 31
	s_lshl_b64 s[46:47], s[46:47], 23
	s_add_u32 s1, s34, s46
	v_lshl_or_b32 v132, s11, 8, v187
	s_addc_u32 s11, s35, s47
	s_add_u32 s4, s1, s4
	s_addc_u32 s5, s11, s5
	s_ashr_i32 s43, s42, 31
	s_lshl_b64 s[8:9], s[8:9], 20
	s_ashr_i32 s45, s44, 31
	s_lshl_b64 s[42:43], s[42:43], 2
	s_add_u32 s42, s36, s42
	s_addc_u32 s43, s37, s43
	s_lshl_b64 s[44:45], s[44:45], 2
	s_add_u32 s44, s36, s44
	v_lshl_add_u64 v[0:1], v[176:177], 0, s[8:9]
	v_ashrrev_i32_e32 v133, 31, v132
	s_addc_u32 s45, s37, s45
	v_lshl_add_u64 v[0:1], v[132:133], 1, v[0:1]
	v_lshlrev_b64 v[132:133], 2, v[132:133]
	v_lshl_add_u64 v[182:183], s[42:43], 0, v[132:133]
	v_lshl_add_u64 v[184:185], s[44:45], 0, v[132:133]
	v_mov_b32_e32 v2, v186
	global_load_dwordx4 v[144:147], v[182:183], off
	global_load_dwordx4 v[136:139], v[182:183], off offset:16
	global_load_dwordx4 v[140:143], v[184:185], off
	global_load_dwordx4 v[132:135], v[184:185], off offset:16
	s_cmp_lt_i32 s10, 2
	v_lshlrev_b64 v[148:149], 1, v[2:3]
	v_lshl_add_u64 v[150:151], s[2:3], 0, v[148:149]
	v_lshl_add_u64 v[148:149], s[4:5], 0, v[148:149]
	flat_load_dwordx4 v[190:193], v[150:151]
	flat_load_dwordx4 v[160:163], v[148:149]
	v_add_u32_e32 v148, 0x1000, v2
	v_mov_b32_e32 v149, v3
	v_lshlrev_b64 v[148:149], 1, v[148:149]
	v_lshl_add_u64 v[150:151], s[2:3], 0, v[148:149]
	v_lshl_add_u64 v[148:149], s[4:5], 0, v[148:149]
	flat_load_dwordx4 v[194:197], v[150:151]
	flat_load_dwordx4 v[156:159], v[148:149]
	v_add_u32_e32 v148, 0x2000, v2
	v_mov_b32_e32 v149, v3
	v_lshlrev_b64 v[148:149], 1, v[148:149]
	v_lshl_add_u64 v[150:151], s[2:3], 0, v[148:149]
	v_lshl_add_u64 v[148:149], s[4:5], 0, v[148:149]
	v_add_u32_e32 v2, 0x3000, v2
	flat_load_dwordx4 v[234:237], v[150:151]
	flat_load_dwordx4 v[152:155], v[148:149]
	v_lshlrev_b64 v[148:149], 1, v[2:3]
	v_lshl_add_u64 v[150:151], s[2:3], 0, v[148:149]
	v_lshl_add_u64 v[148:149], s[4:5], 0, v[148:149]
	flat_load_dwordx4 v[238:241], v[150:151]
	s_nop 0
	flat_load_dwordx4 v[148:151], v[148:149]
	s_waitcnt vmcnt(0) lgkmcnt(0)
	v_lshlrev_b32_e32 v2, 16, v190
	v_and_b32_e32 v189, 0xffff0000, v190
	v_lshlrev_b32_e32 v190, 16, v191
	v_and_b32_e32 v191, 0xffff0000, v191
	v_lshlrev_b32_e32 v212, 16, v192
	v_and_b32_e32 v192, 0xffff0000, v192
	v_lshlrev_b32_e32 v213, 16, v193
	v_and_b32_e32 v193, 0xffff0000, v193
	v_add_f32_e32 v2, v144, v2
	v_add_f32_e32 v189, v145, v189
	v_add_f32_e32 v190, v146, v190
	v_add_f32_e32 v191, v147, v191
	v_add_f32_e32 v212, v136, v212
	v_add_f32_e32 v192, v137, v192
	v_add_f32_e32 v213, v138, v213
	v_add_f32_e32 v193, v139, v193
	s_mov_b64 s[8:9], -1
	v_max_f32_e32 v233, 0xc2200000, v2
	v_max_f32_e32 v232, 0xc2200000, v189
	v_max_f32_e32 v231, 0xc2200000, v190
	v_max_f32_e32 v230, 0xc2200000, v191
	v_max_f32_e32 v229, 0xc2200000, v212
	v_max_f32_e32 v228, 0xc2200000, v192
	v_max_f32_e32 v227, 0xc2200000, v213
	v_max_f32_e32 v226, 0xc2200000, v193
	v_lshlrev_b32_e32 v225, 16, v194
	v_and_b32_e32 v224, 0xffff0000, v194
	v_lshlrev_b32_e32 v223, 16, v195
	v_and_b32_e32 v222, 0xffff0000, v195
	v_lshlrev_b32_e32 v221, 16, v196
	v_and_b32_e32 v220, 0xffff0000, v196
	v_lshlrev_b32_e32 v219, 16, v197
	v_and_b32_e32 v218, 0xffff0000, v197
	v_lshlrev_b32_e32 v217, 16, v234
	v_and_b32_e32 v216, 0xffff0000, v234
	v_lshlrev_b32_e32 v215, 16, v235
	v_and_b32_e32 v214, 0xffff0000, v235
	v_lshlrev_b32_e32 v213, 16, v236
	v_and_b32_e32 v212, 0xffff0000, v236
	v_lshlrev_b32_e32 v197, 16, v237
	v_and_b32_e32 v196, 0xffff0000, v237
	v_lshlrev_b32_e32 v195, 16, v238
	v_and_b32_e32 v194, 0xffff0000, v238
	v_lshlrev_b32_e32 v193, 16, v239
	v_and_b32_e32 v192, 0xffff0000, v239
	v_lshlrev_b32_e32 v191, 16, v240
	v_and_b32_e32 v190, 0xffff0000, v240
	v_lshlrev_b32_e32 v189, 16, v241
	v_and_b32_e32 v2, 0xffff0000, v241
	s_cbranch_scc1 .LBB0_546
; __device__ __forceinline__ float sigmoidf_(float x) { return __builtin_amdgcn_rcpf(1.0f + __expf(-x)); }
;   __device__ __forceinline__ void operator()(EPI_ARGS) const {
;     ...
;           for (int m = 0; m < 4; ++m) {
;             float xc[8], y[8];
;             unpack8(zc[m], xc);
; #pragma unroll
;             for (int k = 0; k < 8; ++k) y[k] = acc[ai][bj][m][k >> 2][k & 3] * sigmoidf_(fmaxf(xc[k] + gc[k], -40.f));
;             u32x4 o;
;             o.x = pack2(y[0], y[1]); o.y = pack2(y[2], y[3]); o.z = pack2(y[4], y[5]); o.w = pack2(y[6], y[7]);
;             *(u32x4*)(mrow + (size_t)(ai * HALF + m * 16) * DM + bj * HALF) = o;
	v_mul_f32_e32 v234, 0xbfb8aa3b, v233
	v_mul_f32_e32 v235, 0xbfb8aa3b, v232
	v_mul_f32_e32 v236, 0xbfb8aa3b, v231
	v_exp_f32_e32 v234, v234
	v_exp_f32_e32 v235, v235
	v_exp_f32_e32 v236, v236
	v_mul_f32_e32 v237, 0xbfb8aa3b, v230
	v_exp_f32_e32 v237, v237
	v_mul_f32_e32 v238, 0xbfb8aa3b, v229
	v_mul_f32_e32 v239, 0xbfb8aa3b, v228
	v_add_f32_e32 v234, 1.0, v234
	v_add_f32_e32 v235, 1.0, v235
	v_add_f32_e32 v236, 1.0, v236
	v_exp_f32_e32 v238, v238
	v_exp_f32_e32 v239, v239
	v_mul_f32_e32 v240, 0xbfb8aa3b, v227
	v_mul_f32_e32 v241, 0xbfb8aa3b, v226
	v_rcp_f32_e32 v234, v234
	v_rcp_f32_e32 v235, v235
	v_rcp_f32_e32 v236, v236
	v_add_f32_e32 v237, 1.0, v237
	v_exp_f32_e32 v240, v240
	v_exp_f32_e32 v241, v241
	v_rcp_f32_e32 v237, v237
	v_add_f32_e32 v238, 1.0, v238
	v_add_f32_e32 v239, 1.0, v239
	v_mul_f32_e32 v234, v128, v234
	v_mul_f32_e32 v235, v129, v235
	v_mul_f32_e32 v236, v130, v236
	v_rcp_f32_e32 v238, v238
	v_rcp_f32_e32 v239, v239
	v_add_f32_e32 v240, 1.0, v240
	v_add_f32_e32 v241, 1.0, v241
	v_mul_f32_e32 v237, v131, v237
	v_rcp_f32_e32 v240, v240
	v_rcp_f32_e32 v241, v241
	v_cvt_pk_bf16_f32 v234, v234, v235
	v_cvt_pk_bf16_f32 v235, v236, v237
	v_add_f32_e32 v236, v144, v225
	v_max_f32_e32 v236, 0xc2200000, v236
	v_mul_f32_e32 v236, 0xbfb8aa3b, v236
	v_mul_f32_e32 v238, v124, v238
	v_mul_f32_e32 v239, v125, v239
	v_exp_f32_e32 v242, v236
	v_cvt_pk_bf16_f32 v236, v238, v239
	v_mul_f32_e32 v240, v126, v240
	v_mul_f32_e32 v241, v127, v241
	v_cvt_pk_bf16_f32 v237, v240, v241
	flat_store_dwordx4 v[0:1], v[234:237]
	v_add_f32_e32 v238, v136, v221
	v_max_f32_e32 v238, 0xc2200000, v238
	v_add_f32_e32 v235, v145, v224
	v_add_f32_e32 v236, v146, v223
	v_max_f32_e32 v235, 0xc2200000, v235
	v_max_f32_e32 v236, 0xc2200000, v236
	v_add_f32_e32 v237, v147, v222
	v_add_f32_e32 v239, v137, v220
	v_mul_f32_e32 v235, 0xbfb8aa3b, v235
	v_mul_f32_e32 v236, 0xbfb8aa3b, v236
	v_max_f32_e32 v237, 0xc2200000, v237
	v_mul_f32_e32 v238, 0xbfb8aa3b, v238
	v_max_f32_e32 v239, 0xc2200000, v239
	v_exp_f32_e32 v235, v235
	v_exp_f32_e32 v236, v236
	v_mul_f32_e32 v237, 0xbfb8aa3b, v237
	v_exp_f32_e32 v238, v238
	v_mul_f32_e32 v239, 0xbfb8aa3b, v239
	v_add_f32_e32 v240, v138, v219
	v_exp_f32_e32 v237, v237
	v_exp_f32_e32 v239, v239
	v_max_f32_e32 v240, 0xc2200000, v240
	v_add_f32_e32 v241, v139, v218
	v_mul_f32_e32 v240, 0xbfb8aa3b, v240
	v_max_f32_e32 v241, 0xc2200000, v241
	v_exp_f32_e32 v240, v240
	v_mul_f32_e32 v241, 0xbfb8aa3b, v241
	v_add_f32_e32 v234, 1.0, v242
	v_add_f32_e32 v235, 1.0, v235
	v_add_f32_e32 v236, 1.0, v236
	v_add_f32_e32 v238, 1.0, v238
	v_exp_f32_e32 v241, v241
	v_rcp_f32_e32 v234, v234
	v_rcp_f32_e32 v235, v235
	v_rcp_f32_e32 v236, v236
	v_add_f32_e32 v237, 1.0, v237
	v_rcp_f32_e32 v238, v238
	v_add_f32_e32 v239, 1.0, v239
	v_rcp_f32_e32 v237, v237
	v_rcp_f32_e32 v239, v239
	v_add_f32_e32 v240, 1.0, v240
	v_rcp_f32_e32 v240, v240
	v_add_f32_e32 v241, 1.0, v241
	v_mul_f32_e32 v234, v120, v234
	v_mul_f32_e32 v235, v121, v235
	v_mul_f32_e32 v236, v122, v236
	v_rcp_f32_e32 v241, v241
	v_mul_f32_e32 v238, v116, v238
	v_mul_f32_e32 v237, v123, v237
	v_mul_f32_e32 v239, v117, v239
	v_cvt_pk_bf16_f32 v234, v234, v235
	v_cvt_pk_bf16_f32 v235, v236, v237
	v_cvt_pk_bf16_f32 v236, v238, v239
	v_add_f32_e32 v238, v144, v217
	v_max_f32_e32 v238, 0xc2200000, v238
	v_mul_f32_e32 v240, v118, v240
	v_mul_f32_e32 v238, 0xbfb8aa3b, v238
	v_mul_f32_e32 v241, v119, v241
	v_cvt_pk_bf16_f32 v237, v240, v241
	v_exp_f32_e32 v240, v238
	v_add_co_u32_e32 v238, vcc, s67, v0
	v_add_f32_e32 v241, v139, v196
	s_nop 0
	v_addc_co_u32_e32 v239, vcc, 0, v1, vcc
	flat_store_dwordx4 v[238:239], v[234:237]
	v_add_f32_e32 v238, v136, v213
	v_max_f32_e32 v238, 0xc2200000, v238
	v_add_f32_e32 v235, v145, v216
	v_add_f32_e32 v236, v146, v215
	v_max_f32_e32 v235, 0xc2200000, v235
; __device__ __forceinline__ float sigmoidf_(float x) { return __builtin_amdgcn_rcpf(1.0f + __expf(-x)); }
;   __device__ __forceinline__ void operator()(EPI_ARGS) const {
;     ...
;           for (int m = 0; m < 4; ++m) {
;             float xc[8], y[8];
;             unpack8(zc[m], xc);
; #pragma unroll
;             for (int k = 0; k < 8; ++k) y[k] = acc[ai][bj][m][k >> 2][k & 3] * sigmoidf_(fmaxf(xc[k] + gc[k], -40.f));
;             u32x4 o;
;             o.x = pack2(y[0], y[1]); o.y = pack2(y[2], y[3]); o.z = pack2(y[4], y[5]); o.w = pack2(y[6], y[7]);
;             *(u32x4*)(mrow + (size_t)(ai * HALF + m * 16) * DM + bj * HALF) = o;
	v_max_f32_e32 v236, 0xc2200000, v236
	v_add_f32_e32 v237, v147, v214
	v_add_f32_e32 v239, v137, v212
	v_mul_f32_e32 v235, 0xbfb8aa3b, v235
	v_mul_f32_e32 v236, 0xbfb8aa3b, v236
	v_max_f32_e32 v237, 0xc2200000, v237
	v_mul_f32_e32 v238, 0xbfb8aa3b, v238
	v_max_f32_e32 v239, 0xc2200000, v239
	v_add_f32_e32 v234, 1.0, v240
	v_exp_f32_e32 v235, v235
	v_exp_f32_e32 v236, v236
	v_mul_f32_e32 v237, 0xbfb8aa3b, v237
	v_exp_f32_e32 v238, v238
	v_mul_f32_e32 v239, 0xbfb8aa3b, v239
	v_add_f32_e32 v240, v138, v197
	v_exp_f32_e32 v237, v237
	v_exp_f32_e32 v239, v239
	v_max_f32_e32 v240, 0xc2200000, v240
	v_mul_f32_e32 v240, 0xbfb8aa3b, v240
	v_max_f32_e32 v241, 0xc2200000, v241
	v_exp_f32_e32 v240, v240
	v_mul_f32_e32 v241, 0xbfb8aa3b, v241
	v_add_f32_e32 v235, 1.0, v235
	v_add_f32_e32 v236, 1.0, v236
	v_add_f32_e32 v238, 1.0, v238
	v_exp_f32_e32 v241, v241
	v_rcp_f32_e32 v234, v234
	v_rcp_f32_e32 v235, v235
	v_rcp_f32_e32 v236, v236
	v_add_f32_e32 v237, 1.0, v237
	v_rcp_f32_e32 v238, v238
	v_add_f32_e32 v239, 1.0, v239
	v_rcp_f32_e32 v237, v237
	v_rcp_f32_e32 v239, v239
	v_add_f32_e32 v240, 1.0, v240
	v_rcp_f32_e32 v240, v240
	v_add_f32_e32 v241, 1.0, v241
	v_mul_f32_e32 v234, v112, v234
	v_mul_f32_e32 v235, v113, v235
	v_mul_f32_e32 v236, v114, v236
	v_rcp_f32_e32 v241, v241
	v_mul_f32_e32 v238, v108, v238
	v_mul_f32_e32 v237, v115, v237
	v_mul_f32_e32 v239, v109, v239
	v_cvt_pk_bf16_f32 v234, v234, v235
	v_cvt_pk_bf16_f32 v235, v236, v237
	v_cvt_pk_bf16_f32 v236, v238, v239
	v_add_f32_e32 v238, v144, v195
	v_max_f32_e32 v238, 0xc2200000, v238
	v_mul_f32_e32 v240, v110, v240
	v_mul_f32_e32 v238, 0xbfb8aa3b, v238
	s_mov_b32 s1, 0x20000
	v_mul_f32_e32 v241, v111, v241
	v_cvt_pk_bf16_f32 v237, v240, v241
	v_exp_f32_e32 v240, v238
	v_add_co_u32_e32 v238, vcc, s1, v0
	v_add_f32_e32 v241, v139, v2
	s_nop 0
	v_addc_co_u32_e32 v239, vcc, 0, v1, vcc
	flat_store_dwordx4 v[238:239], v[234:237]
	v_add_f32_e32 v238, v136, v191
	v_max_f32_e32 v238, 0xc2200000, v238
	v_add_f32_e32 v235, v145, v194
	v_add_f32_e32 v236, v146, v193
	v_max_f32_e32 v235, 0xc2200000, v235
	v_max_f32_e32 v236, 0xc2200000, v236
	v_add_f32_e32 v237, v147, v192
	v_add_f32_e32 v239, v137, v190
	v_mul_f32_e32 v235, 0xbfb8aa3b, v235
	v_mul_f32_e32 v236, 0xbfb8aa3b, v236
	v_max_f32_e32 v237, 0xc2200000, v237
	v_mul_f32_e32 v238, 0xbfb8aa3b, v238
	v_max_f32_e32 v239, 0xc2200000, v239
	v_add_f32_e32 v234, 1.0, v240
	v_exp_f32_e32 v235, v235
	v_exp_f32_e32 v236, v236
	v_mul_f32_e32 v237, 0xbfb8aa3b, v237
	v_exp_f32_e32 v238, v238
	v_mul_f32_e32 v239, 0xbfb8aa3b, v239
	v_add_f32_e32 v240, v138, v189
	v_exp_f32_e32 v237, v237
	v_exp_f32_e32 v239, v239
	v_max_f32_e32 v240, 0xc2200000, v240
	v_max_f32_e32 v241, 0xc2200000, v241
	v_mul_f32_e32 v240, 0xbfb8aa3b, v240
	v_mul_f32_e32 v241, 0xbfb8aa3b, v241
	v_exp_f32_e32 v240, v240
	v_exp_f32_e32 v241, v241
	v_add_f32_e32 v235, 1.0, v235
	v_add_f32_e32 v236, 1.0, v236
	v_add_f32_e32 v238, 1.0, v238
	v_rcp_f32_e32 v234, v234
	v_rcp_f32_e32 v235, v235
	v_rcp_f32_e32 v236, v236
	v_add_f32_e32 v237, 1.0, v237
	v_rcp_f32_e32 v238, v238
	v_add_f32_e32 v239, 1.0, v239
	v_rcp_f32_e32 v237, v237
	v_rcp_f32_e32 v239, v239
	v_add_f32_e32 v240, 1.0, v240
	v_add_f32_e32 v241, 1.0, v241
	v_rcp_f32_e32 v240, v240
	v_rcp_f32_e32 v241, v241
	v_mul_f32_e32 v234, v104, v234
	v_mul_f32_e32 v235, v105, v235
	v_mul_f32_e32 v236, v106, v236
	v_mul_f32_e32 v238, v100, v238
	v_mul_f32_e32 v237, v107, v237
	v_mul_f32_e32 v239, v101, v239
	v_cvt_pk_bf16_f32 v234, v234, v235
	v_cvt_pk_bf16_f32 v235, v236, v237
	v_cvt_pk_bf16_f32 v236, v238, v239
	v_add_co_u32_e32 v238, vcc, 0x30000, v0
	s_mov_b64 s[8:9], 0
	s_nop 0
	v_addc_co_u32_e32 v239, vcc, 0, v1, vcc
	v_mul_f32_e32 v240, v102, v240
	v_mul_f32_e32 v241, v103, v241
	v_cvt_pk_bf16_f32 v237, v240, v241
	flat_store_dwordx4 v[238:239], v[234:237]

; #define PG8_WAIT_V(n) asm volatile("s_waitcnt vmcnt(" #n ")" ::: "memory")
; #define PG8_WAIT_L(n) asm volatile("s_waitcnt lgkmcnt(" #n ")" ::: "memory")
; #define PG8_BAR __builtin_amdgcn_s_barrier()
; #define PG8_SCHED __builtin_amdgcn_sched_barrier(0)
; template <class Epi, class AddrA, class AddrB>
; __device__ __forceinline__ void gemm_phase(const Sched S, const int lda, const int ldb, const int K, const AddrA addrA,
;                                            const AddrB addrB, const Epi E) {
;     ...
;     const bool has_next = S.next(ui + 1, nxt);
;     const char* nA = has_next ? addrA(nxt) : cA;
;     const char* nB = has_next ? addrB(nxt) : cB;
;     for (int t = 0; t < nt; t += 2) {
;       const bool last = (t == nt - 2);
;       const char* a1 = cA + (size_t)(t + 1) * kstep;
;       const char* a2 = last ? nA : cA + (size_t)(t + 2) * kstep;
;       const char* b2 = last ? nB : cB + (size_t)(t + 2) * kstep;
;       const char* a3 = a2 + kstep;
;       const char* b3 = b2 + kstep;
;       PG8_LDB(B0, 0, 0); PG8_SCHED; PG8_LDA(At, 0, 0); PG8_STAGE(PG8_SA(1, 1), a1 + hstepA, voffA);
;       PG8_WAIT_L(8); PG8_BAR; PG8_WAIT_L(0); PG8_MMA(0, 0, At, B0); PG8_BAR; PG8_SCHED;
;       PG8_LDB(B1, 0, 1); PG8_STAGE(PG8_SB(0, 0), b2, voffB);
;       PG8_BAR; PG8_WAIT_L(0); PG8_MMA(0, 1, At, B1); PG8_BAR;
;       PG8_LDA(At, 0, 1); PG8_STAGE(PG8_SA(0, 0), a2, voffA);
;       PG8_BAR; PG8_WAIT_L(0); PG8_MMA(1, 0, At, B0); PG8_BAR; PG8_SCHED;
;       PG8_STAGE(PG8_SB(0, 1), b2 + hstepB, voffB);
;       PG8_WAIT_V(6); PG8_BAR; PG8_MMA(1, 1, At, B1); PG8_BAR;
.LBB0_618:
	s_ashr_i32 s3, s2, 31
	s_lshl_b64 s[8:9], s[2:3], 20
	s_add_u32 s8, s23, s8
	s_addc_u32 s9, s24, s9
	s_and_b64 s[10:11], s[18:19], exec
	s_cselect_b32 s3, s9, s17
	s_cselect_b32 s13, s8, s16
	s_ashr_i32 s5, s4, 31
	s_lshl_b64 s[10:11], s[4:5], 20
	s_add_u32 s10, s21, s10
	s_addc_u32 s11, s22, s11
	s_and_b64 s[18:19], s[18:19], exec
	s_cselect_b32 s5, s11, s15
	s_cselect_b32 s35, s10, s14
	s_add_u32 s36, s14, 0x100
	s_addc_u32 s37, s15, 0
	s_add_u32 s14, s16, 0x80080
	s_addc_u32 s15, s17, 0
	s_mov_b32 s38, -2
	s_add_i32 s39, 0, 0x10000
	v_add_u32_e32 v142, s39, v144
	ds_read_b128 v[148:151], v142
	ds_read_b128 v[152:155], v142 offset:1024
	ds_read_b128 v[156:159], v142 offset:2048
	ds_read_b128 v[160:163], v142 offset:3072
	s_add_i32 m0, s26, 0xc000
	ds_read_b128 v[168:171], v146
	ds_read_b128 v[172:175], v146 offset:1024
	ds_read_b128 v[176:179], v146 offset:2048
	ds_read_b128 v[180:183], v146 offset:3072
	ds_read_b128 v[184:187], v146 offset:4096
	ds_read_b128 v[188:191], v146 offset:5120
	ds_read_b128 v[192:195], v146 offset:6144
	ds_read_b128 v[212:215], v146 offset:7168
	global_load_lds_dwordx4 v140, s[14:15]
	s_add_i32 m0, s26, 0xe000
	s_nop 0
	global_load_lds_dwordx4 v138, s[14:15]
	s_waitcnt lgkmcnt(6)
	s_setprio 1
	s_barrier
	v_mfma_f32_16x16x32_bf16 v[128:131], v[148:151], v[168:171], 0
	v_mfma_f32_16x16x32_bf16 v[128:131], v[152:155], v[172:175], v[128:131]
	s_waitcnt lgkmcnt(0)
	v_mfma_f32_16x16x32_bf16 v[120:123], v[148:151], v[176:179], 0
	v_mfma_f32_16x16x32_bf16 v[120:123], v[152:155], v[180:183], v[120:123]
	v_mfma_f32_16x16x32_bf16 v[112:115], v[148:151], v[184:187], 0
	v_mfma_f32_16x16x32_bf16 v[112:115], v[152:155], v[188:191], v[112:115]
	v_mfma_f32_16x16x32_bf16 v[104:107], v[148:151], v[192:195], 0
	v_mfma_f32_16x16x32_bf16 v[104:107], v[152:155], v[212:215], v[104:107]
	v_mfma_f32_16x16x32_bf16 v[124:127], v[156:159], v[168:171], 0
	v_mfma_f32_16x16x32_bf16 v[124:127], v[160:163], v[172:175], v[124:127]
	v_mfma_f32_16x16x32_bf16 v[116:119], v[156:159], v[176:179], 0
	v_mfma_f32_16x16x32_bf16 v[116:119], v[160:163], v[180:183], v[116:119]
	v_mfma_f32_16x16x32_bf16 v[108:111], v[156:159], v[184:187], 0
	v_mfma_f32_16x16x32_bf16 v[108:111], v[160:163], v[188:191], v[108:111]
	v_mfma_f32_16x16x32_bf16 v[100:103], v[156:159], v[192:195], 0
	v_mfma_f32_16x16x32_bf16 v[100:103], v[160:163], v[212:215], v[100:103]
	s_barrier
	s_setprio 0
	s_add_u32 s16, s14, 0xfff80080
	s_addc_u32 s17, s15, -1
	s_cmp_eq_u32 s38, 28
	s_cselect_b32 s19, s3, s17
	s_cselect_b32 s18, s13, s16
	s_cselect_b32 s17, s5, s37
	s_cselect_b32 s16, s35, s36
	s_add_i32 s42, 0, 0x14000
	v_add_u32_e32 v142, s42, v144
	s_add_i32 s39, s39, s25
	ds_read_b128 v[216:219], v142
	ds_read_b128 v[220:223], v142 offset:1024
	ds_read_b128 v[224:227], v142 offset:2048
	ds_read_b128 v[228:231], v142 offset:3072
	s_add_u32 s98, s16, 0x80
	s_addc_u32 s99, s17, 0
	s_mov_b32 m0, s39
	s_nop 0
	global_load_lds_dwordx4 v2, s[16:17]
	s_add_i32 m0, s39, 0x2000
	s_nop 0
	global_load_lds_dwordx4 v0, s[16:17]
	s_mov_b32 m0, s26
	s_add_u32 s100, s18, 0x80
	s_addc_u32 s101, s19, 0
	s_waitcnt lgkmcnt(2)
	s_setprio 1
	s_barrier
	v_mfma_f32_16x16x32_bf16 v[96:99], v[216:219], v[168:171], 0
	v_mfma_f32_16x16x32_bf16 v[96:99], v[220:223], v[172:175], v[96:99]
	s_waitcnt lgkmcnt(0)
	v_mfma_f32_16x16x32_bf16 v[88:91], v[216:219], v[176:179], 0
	v_mfma_f32_16x16x32_bf16 v[88:91], v[220:223], v[180:183], v[88:91]
	v_mfma_f32_16x16x32_bf16 v[80:83], v[216:219], v[184:187], 0
	v_mfma_f32_16x16x32_bf16 v[80:83], v[220:223], v[188:191], v[80:83]
	v_mfma_f32_16x16x32_bf16 v[72:75], v[216:219], v[192:195], 0
	v_mfma_f32_16x16x32_bf16 v[72:75], v[220:223], v[212:215], v[72:75]
	v_mfma_f32_16x16x32_bf16 v[92:95], v[224:227], v[168:171], 0
	v_mfma_f32_16x16x32_bf16 v[92:95], v[228:231], v[172:175], v[92:95]
	v_mfma_f32_16x16x32_bf16 v[84:87], v[224:227], v[176:179], 0
	v_mfma_f32_16x16x32_bf16 v[84:87], v[228:231], v[180:183], v[84:87]
	v_mfma_f32_16x16x32_bf16 v[76:79], v[224:227], v[184:187], 0
	v_mfma_f32_16x16x32_bf16 v[76:79], v[228:231], v[188:191], v[76:79]
	v_mfma_f32_16x16x32_bf16 v[68:71], v[224:227], v[192:195], 0
	v_mfma_f32_16x16x32_bf16 v[68:71], v[228:231], v[212:215], v[68:71]
	s_barrier
	s_setprio 0
	ds_read_b128 v[168:171], v146 offset:16384
	ds_read_b128 v[172:175], v146 offset:17408
	ds_read_b128 v[176:179], v146 offset:18432
	ds_read_b128 v[180:183], v146 offset:19456
	ds_read_b128 v[184:187], v146 offset:20480
	ds_read_b128 v[188:191], v146 offset:21504
	ds_read_b128 v[192:195], v146 offset:22528
	ds_read_b128 v[212:215], v146 offset:23552
	global_load_lds_dwordx4 v134, s[18:19]
	s_mov_b32 m0, s27
	s_nop 0
	global_load_lds_dwordx4 v132, s[18:19]
	s_waitcnt lgkmcnt(6)
	s_setprio 1
	s_barrier
	v_mfma_f32_16x16x32_bf16 v[64:67], v[148:151], v[168:171], 0
	v_mfma_f32_16x16x32_bf16 v[64:67], v[152:155], v[172:175], v[64:67]
	s_waitcnt lgkmcnt(0)
	v_mfma_f32_16x16x32_bf16 v[56:59], v[148:151], v[176:179], 0
	v_mfma_f32_16x16x32_bf16 v[56:59], v[152:155], v[180:183], v[56:59]
	v_mfma_f32_16x16x32_bf16 v[48:51], v[148:151], v[184:187], 0
	v_mfma_f32_16x16x32_bf16 v[48:51], v[152:155], v[188:191], v[48:51]
	v_mfma_f32_16x16x32_bf16 v[40:43], v[148:151], v[192:195], 0
	v_mfma_f32_16x16x32_bf16 v[40:43], v[152:155], v[212:215], v[40:43]
	v_mfma_f32_16x16x32_bf16 v[60:63], v[156:159], v[168:171], 0
	v_mfma_f32_16x16x32_bf16 v[60:63], v[160:163], v[172:175], v[60:63]
	v_mfma_f32_16x16x32_bf16 v[52:55], v[156:159], v[176:179], 0
	v_mfma_f32_16x16x32_bf16 v[52:55], v[160:163], v[180:183], v[52:55]
	v_mfma_f32_16x16x32_bf16 v[44:47], v[156:159], v[184:187], 0
	v_mfma_f32_16x16x32_bf16 v[44:47], v[160:163], v[188:191], v[44:47]
	v_mfma_f32_16x16x32_bf16 v[36:39], v[156:159], v[192:195], 0
	v_mfma_f32_16x16x32_bf16 v[36:39], v[160:163], v[212:215], v[36:39]
	s_barrier
; #define PG8_WAIT_V(n) asm volatile("s_waitcnt vmcnt(" #n ")" ::: "memory")
; #define PG8_WAIT_L(n) asm volatile("s_waitcnt lgkmcnt(" #n ")" ::: "memory")
; #define PG8_BAR __builtin_amdgcn_s_barrier()
; #define PG8_SCHED __builtin_amdgcn_sched_barrier(0)
; template <class Epi, class AddrA, class AddrB>
; __device__ __forceinline__ void gemm_phase(const Sched S, const int lda, const int ldb, const int K, const AddrA addrA,
;                                            const AddrB addrB, const Epi E) {
;     ...
;       PG8_BAR; PG8_WAIT_L(0); PG8_MMA(1, 0, At, B0); PG8_BAR; PG8_SCHED;
;       PG8_STAGE(PG8_SB(0, 1), b2 + hstepB, voffB);
;       PG8_WAIT_V(6); PG8_BAR; PG8_MMA(1, 1, At, B1); PG8_BAR;
;       PG8_LDB(B0, 1, 0); PG8_SCHED; PG8_LDA(At, 1, 0); PG8_STAGE(PG8_SA(0, 1), a2 + hstepA, voffA);
;       PG8_WAIT_L(8); PG8_BAR; PG8_WAIT_L(0); PG8_MMA(0, 0, At, B0); PG8_BAR; PG8_SCHED;
;       PG8_LDB(B1, 1, 1); PG8_STAGE(PG8_SB(1, 0), b3, voffB);
;       PG8_BAR; PG8_WAIT_L(0); PG8_MMA(0, 1, At, B1); PG8_BAR;
;       PG8_LDA(At, 1, 1); PG8_STAGE(PG8_SA(1, 0), a3, voffA);
;       PG8_BAR; PG8_WAIT_L(0); PG8_MMA(1, 0, At, B0); PG8_BAR; PG8_SCHED;
	s_setprio 0
	s_add_u32 s40, s16, 0x80000
	s_addc_u32 s41, s17, 0
	s_add_i32 s39, s42, s25
	s_mov_b32 m0, s39
	s_nop 0
	global_load_lds_dwordx4 v2, s[40:41]
	s_add_i32 m0, s39, 0x2000
	s_nop 0
	global_load_lds_dwordx4 v0, s[40:41]
	s_add_i32 s39, 0, 0x18000
	v_add_u32_e32 v147, s39, v144
	s_waitcnt vmcnt(6)
	s_setprio 1
	s_barrier
	v_mfma_f32_16x16x32_bf16 v[32:35], v[216:219], v[168:171], 0
	v_mfma_f32_16x16x32_bf16 v[32:35], v[220:223], v[172:175], v[32:35]
	v_mfma_f32_16x16x32_bf16 v[24:27], v[216:219], v[176:179], 0
	v_mfma_f32_16x16x32_bf16 v[24:27], v[220:223], v[180:183], v[24:27]
	v_mfma_f32_16x16x32_bf16 v[16:19], v[216:219], v[184:187], 0
	v_mfma_f32_16x16x32_bf16 v[16:19], v[220:223], v[188:191], v[16:19]
	v_mfma_f32_16x16x32_bf16 v[8:11], v[216:219], v[192:195], 0
	v_mfma_f32_16x16x32_bf16 v[8:11], v[220:223], v[212:215], v[8:11]
	v_mfma_f32_16x16x32_bf16 v[28:31], v[224:227], v[168:171], 0
	v_mfma_f32_16x16x32_bf16 v[28:31], v[228:231], v[172:175], v[28:31]
	v_mfma_f32_16x16x32_bf16 v[20:23], v[224:227], v[176:179], 0
	v_mfma_f32_16x16x32_bf16 v[20:23], v[228:231], v[180:183], v[20:23]
	v_mfma_f32_16x16x32_bf16 v[12:15], v[224:227], v[184:187], 0
	v_mfma_f32_16x16x32_bf16 v[12:15], v[228:231], v[188:191], v[12:15]
	v_mfma_f32_16x16x32_bf16 v[4:7], v[224:227], v[192:195], 0
	v_mfma_f32_16x16x32_bf16 v[4:7], v[228:231], v[212:215], v[4:7]
	s_barrier
	s_setprio 0
	ds_read_b128 v[148:151], v147
	ds_read_b128 v[152:155], v147 offset:1024
	ds_read_b128 v[156:159], v147 offset:2048
	ds_read_b128 v[160:163], v147 offset:3072
	s_add_u32 s18, s18, 0x80000
	s_addc_u32 s19, s19, 0
	s_mov_b32 m0, s28
	ds_read_b128 v[168:171], v146 offset:32768
	ds_read_b128 v[172:175], v146 offset:33792
	ds_read_b128 v[176:179], v146 offset:34816
	ds_read_b128 v[180:183], v146 offset:35840
	ds_read_b128 v[184:187], v146 offset:36864
	ds_read_b128 v[188:191], v146 offset:37888
	ds_read_b128 v[192:195], v146 offset:38912
	ds_read_b128 v[212:215], v146 offset:39936
	global_load_lds_dwordx4 v134, s[18:19]
	s_mov_b32 m0, s29
	s_nop 0
	global_load_lds_dwordx4 v132, s[18:19]
	s_waitcnt lgkmcnt(6)
	s_setprio 1
	s_barrier
	v_mfma_f32_16x16x32_bf16 v[128:131], v[148:151], v[168:171], v[128:131]
	v_mfma_f32_16x16x32_bf16 v[128:131], v[152:155], v[172:175], v[128:131]
	s_waitcnt lgkmcnt(0)
	v_mfma_f32_16x16x32_bf16 v[120:123], v[148:151], v[176:179], v[120:123]
	v_mfma_f32_16x16x32_bf16 v[120:123], v[152:155], v[180:183], v[120:123]
	v_mfma_f32_16x16x32_bf16 v[112:115], v[148:151], v[184:187], v[112:115]
	v_mfma_f32_16x16x32_bf16 v[112:115], v[152:155], v[188:191], v[112:115]
	v_mfma_f32_16x16x32_bf16 v[104:107], v[148:151], v[192:195], v[104:107]
	v_mfma_f32_16x16x32_bf16 v[104:107], v[152:155], v[212:215], v[104:107]
	v_mfma_f32_16x16x32_bf16 v[124:127], v[156:159], v[168:171], v[124:127]
	v_mfma_f32_16x16x32_bf16 v[124:127], v[160:163], v[172:175], v[124:127]
	v_mfma_f32_16x16x32_bf16 v[116:119], v[156:159], v[176:179], v[116:119]
	v_mfma_f32_16x16x32_bf16 v[116:119], v[160:163], v[180:183], v[116:119]
	v_mfma_f32_16x16x32_bf16 v[108:111], v[156:159], v[184:187], v[108:111]
	v_mfma_f32_16x16x32_bf16 v[108:111], v[160:163], v[188:191], v[108:111]
	v_mfma_f32_16x16x32_bf16 v[100:103], v[156:159], v[192:195], v[100:103]
	v_mfma_f32_16x16x32_bf16 v[100:103], v[160:163], v[212:215], v[100:103]
	s_barrier
	s_setprio 0
	s_add_i32 s18, 0, 0x1c000
	s_add_i32 s19, s39, s25
	v_add_u32_e32 v147, s18, v144
	s_mov_b32 m0, s19
	ds_read_b128 v[216:219], v147
	ds_read_b128 v[220:223], v147 offset:1024
	ds_read_b128 v[224:227], v147 offset:2048
	ds_read_b128 v[228:231], v147 offset:3072
	global_load_lds_dwordx4 v2, s[98:99]
	s_add_i32 m0, s19, 0x2000
	s_nop 0
	global_load_lds_dwordx4 v0, s[98:99]
	s_mov_b32 m0, s30
	s_waitcnt lgkmcnt(2)
	s_setprio 1
	s_barrier
	v_mfma_f32_16x16x32_bf16 v[96:99], v[216:219], v[168:171], v[96:99]
	v_mfma_f32_16x16x32_bf16 v[96:99], v[220:223], v[172:175], v[96:99]
	s_waitcnt lgkmcnt(0)
	v_mfma_f32_16x16x32_bf16 v[88:91], v[216:219], v[176:179], v[88:91]
	v_mfma_f32_16x16x32_bf16 v[88:91], v[220:223], v[180:183], v[88:91]
	v_mfma_f32_16x16x32_bf16 v[80:83], v[216:219], v[184:187], v[80:83]
	v_mfma_f32_16x16x32_bf16 v[80:83], v[220:223], v[188:191], v[80:83]
	v_mfma_f32_16x16x32_bf16 v[72:75], v[216:219], v[192:195], v[72:75]
	v_mfma_f32_16x16x32_bf16 v[72:75], v[220:223], v[212:215], v[72:75]
	v_mfma_f32_16x16x32_bf16 v[92:95], v[224:227], v[168:171], v[92:95]
	v_mfma_f32_16x16x32_bf16 v[92:95], v[228:231], v[172:175], v[92:95]
	v_mfma_f32_16x16x32_bf16 v[84:87], v[224:227], v[176:179], v[84:87]
	v_mfma_f32_16x16x32_bf16 v[84:87], v[228:231], v[180:183], v[84:87]
	v_mfma_f32_16x16x32_bf16 v[76:79], v[224:227], v[184:187], v[76:79]
	v_mfma_f32_16x16x32_bf16 v[76:79], v[228:231], v[188:191], v[76:79]
	v_mfma_f32_16x16x32_bf16 v[68:71], v[224:227], v[192:195], v[68:71]
	v_mfma_f32_16x16x32_bf16 v[68:71], v[228:231], v[212:215], v[68:71]
	s_barrier
	s_setprio 0
	ds_read_b128 v[168:171], v146 offset:49152
	ds_read_b128 v[172:175], v146 offset:50176
	ds_read_b128 v[176:179], v146 offset:51200
	ds_read_b128 v[180:183], v146 offset:52224
	ds_read_b128 v[184:187], v146 offset:53248
	ds_read_b128 v[188:191], v146 offset:54272
	ds_read_b128 v[192:195], v146 offset:55296
	ds_read_b128 v[212:215], v146 offset:56320
	global_load_lds_dwordx4 v134, s[100:101]
	s_mov_b32 m0, s31
	s_nop 0
	global_load_lds_dwordx4 v132, s[100:101]
	s_waitcnt lgkmcnt(6)
	s_setprio 1
	s_barrier
; #define PG8_WAIT_V(n) asm volatile("s_waitcnt vmcnt(" #n ")" ::: "memory")
; #define PG8_WAIT_L(n) asm volatile("s_waitcnt lgkmcnt(" #n ")" ::: "memory")
; #define PG8_BAR __builtin_amdgcn_s_barrier()
; #define PG8_SCHED __builtin_amdgcn_sched_barrier(0)
; template <class Epi, class AddrA, class AddrB>
; __device__ __forceinline__ void gemm_phase(const Sched S, const int lda, const int ldb, const int K, const AddrA addrA,
;                                            const AddrB addrB, const Epi E) {
;     ...
;       PG8_LDB(B0, 0, 0); PG8_SCHED; PG8_LDA(At, 0, 0); PG8_STAGE(PG8_SA(1, 1), a1 + hstepA, voffA);
;       PG8_WAIT_L(8); PG8_BAR; PG8_WAIT_L(0); PG8_MMA(0, 0, At, B0); PG8_BAR; PG8_SCHED;
;       PG8_LDB(B1, 0, 1); PG8_STAGE(PG8_SB(0, 0), b2, voffB);
;       PG8_BAR; PG8_WAIT_L(0); PG8_MMA(0, 1, At, B1); PG8_BAR;
;     ...
;       PG8_BAR; PG8_WAIT_L(0); PG8_MMA(0, 1, At, B1); PG8_BAR;
;       PG8_LDA(At, 1, 1); PG8_STAGE(PG8_SA(1, 0), a3, voffA);
;       PG8_BAR; PG8_WAIT_L(0); PG8_MMA(1, 0, At, B0); PG8_BAR; PG8_SCHED;
;       PG8_STAGE(PG8_SB(1, 1), b3 + hstepB, voffB);
;       PG8_WAIT_V(6); PG8_BAR; PG8_MMA(1, 1, At, B1); PG8_BAR;
	v_mfma_f32_16x16x32_bf16 v[64:67], v[148:151], v[168:171], v[64:67]
	v_mfma_f32_16x16x32_bf16 v[64:67], v[152:155], v[172:175], v[64:67]
	s_waitcnt lgkmcnt(0)
	v_mfma_f32_16x16x32_bf16 v[56:59], v[148:151], v[176:179], v[56:59]
	v_mfma_f32_16x16x32_bf16 v[56:59], v[152:155], v[180:183], v[56:59]
	v_mfma_f32_16x16x32_bf16 v[48:51], v[148:151], v[184:187], v[48:51]
	v_mfma_f32_16x16x32_bf16 v[48:51], v[152:155], v[188:191], v[48:51]
	v_mfma_f32_16x16x32_bf16 v[40:43], v[148:151], v[192:195], v[40:43]
	v_mfma_f32_16x16x32_bf16 v[40:43], v[152:155], v[212:215], v[40:43]
	v_mfma_f32_16x16x32_bf16 v[60:63], v[156:159], v[168:171], v[60:63]
	v_mfma_f32_16x16x32_bf16 v[60:63], v[160:163], v[172:175], v[60:63]
	v_mfma_f32_16x16x32_bf16 v[52:55], v[156:159], v[176:179], v[52:55]
	v_mfma_f32_16x16x32_bf16 v[52:55], v[160:163], v[180:183], v[52:55]
	v_mfma_f32_16x16x32_bf16 v[44:47], v[156:159], v[184:187], v[44:47]
	v_mfma_f32_16x16x32_bf16 v[44:47], v[160:163], v[188:191], v[44:47]
	v_mfma_f32_16x16x32_bf16 v[36:39], v[156:159], v[192:195], v[36:39]
	v_mfma_f32_16x16x32_bf16 v[36:39], v[160:163], v[212:215], v[36:39]
	s_barrier
	s_setprio 0
	s_add_u32 s16, s16, 0x80080
	s_addc_u32 s17, s17, 0
	s_add_i32 s18, s18, s25
	s_mov_b32 m0, s18
	s_nop 0
	global_load_lds_dwordx4 v2, s[16:17]
	s_add_i32 m0, s18, 0x2000
	s_nop 0
	global_load_lds_dwordx4 v0, s[16:17]
	s_add_i32 s38, s38, 2
	s_add_u32 s36, s36, 0x100
	s_addc_u32 s37, s37, 0
	s_add_u32 s14, s14, 0x100
	s_addc_u32 s15, s15, 0
	s_waitcnt vmcnt(6)
	s_setprio 1
	s_barrier
	v_mfma_f32_16x16x32_bf16 v[32:35], v[216:219], v[168:171], v[32:35]
	v_mfma_f32_16x16x32_bf16 v[32:35], v[220:223], v[172:175], v[32:35]
	v_mfma_f32_16x16x32_bf16 v[24:27], v[216:219], v[176:179], v[24:27]
	v_mfma_f32_16x16x32_bf16 v[24:27], v[220:223], v[180:183], v[24:27]
	v_mfma_f32_16x16x32_bf16 v[16:19], v[216:219], v[184:187], v[16:19]
	v_mfma_f32_16x16x32_bf16 v[16:19], v[220:223], v[188:191], v[16:19]
	v_mfma_f32_16x16x32_bf16 v[8:11], v[216:219], v[192:195], v[8:11]
	v_mfma_f32_16x16x32_bf16 v[8:11], v[220:223], v[212:215], v[8:11]
	v_mfma_f32_16x16x32_bf16 v[28:31], v[224:227], v[168:171], v[28:31]
	v_mfma_f32_16x16x32_bf16 v[28:31], v[228:231], v[172:175], v[28:31]
	v_mfma_f32_16x16x32_bf16 v[20:23], v[224:227], v[176:179], v[20:23]
	v_mfma_f32_16x16x32_bf16 v[20:23], v[228:231], v[180:183], v[20:23]
	v_mfma_f32_16x16x32_bf16 v[12:15], v[224:227], v[184:187], v[12:15]
	v_mfma_f32_16x16x32_bf16 v[12:15], v[228:231], v[188:191], v[12:15]
	v_mfma_f32_16x16x32_bf16 v[4:7], v[224:227], v[192:195], v[4:7]
	v_mfma_f32_16x16x32_bf16 v[4:7], v[228:231], v[212:215], v[4:7]
	s_barrier
	s_setprio 0
	s_cmp_gt_u32 s38, 29
.LBB0_619:
	s_add_i32 s39, 0, 0x10000
	v_add_u32_e32 v142, s39, v144
	ds_read_b128 v[148:151], v142
	ds_read_b128 v[152:155], v142 offset:1024
	ds_read_b128 v[156:159], v142 offset:2048
	ds_read_b128 v[160:163], v142 offset:3072
	s_add_i32 m0, s26, 0xc000
	ds_read_b128 v[168:171], v146
	ds_read_b128 v[172:175], v146 offset:1024
	ds_read_b128 v[176:179], v146 offset:2048
	ds_read_b128 v[180:183], v146 offset:3072
	ds_read_b128 v[184:187], v146 offset:4096
	ds_read_b128 v[188:191], v146 offset:5120
	ds_read_b128 v[192:195], v146 offset:6144
	ds_read_b128 v[212:215], v146 offset:7168
	global_load_lds_dwordx4 v140, s[14:15]
	s_add_i32 m0, s26, 0xe000
	s_nop 0
	global_load_lds_dwordx4 v138, s[14:15]
	s_waitcnt lgkmcnt(6)
	s_setprio 1
	s_barrier
	v_mfma_f32_16x16x32_bf16 v[128:131], v[148:151], v[168:171], v[128:131]
	v_mfma_f32_16x16x32_bf16 v[128:131], v[152:155], v[172:175], v[128:131]
	s_waitcnt lgkmcnt(0)
	v_mfma_f32_16x16x32_bf16 v[120:123], v[148:151], v[176:179], v[120:123]
	v_mfma_f32_16x16x32_bf16 v[120:123], v[152:155], v[180:183], v[120:123]
	v_mfma_f32_16x16x32_bf16 v[112:115], v[148:151], v[184:187], v[112:115]
	v_mfma_f32_16x16x32_bf16 v[112:115], v[152:155], v[188:191], v[112:115]
	v_mfma_f32_16x16x32_bf16 v[104:107], v[148:151], v[192:195], v[104:107]
	v_mfma_f32_16x16x32_bf16 v[104:107], v[152:155], v[212:215], v[104:107]
	v_mfma_f32_16x16x32_bf16 v[124:127], v[156:159], v[168:171], v[124:127]
	v_mfma_f32_16x16x32_bf16 v[124:127], v[160:163], v[172:175], v[124:127]
	v_mfma_f32_16x16x32_bf16 v[116:119], v[156:159], v[176:179], v[116:119]
	v_mfma_f32_16x16x32_bf16 v[116:119], v[160:163], v[180:183], v[116:119]
	v_mfma_f32_16x16x32_bf16 v[108:111], v[156:159], v[184:187], v[108:111]
	v_mfma_f32_16x16x32_bf16 v[108:111], v[160:163], v[188:191], v[108:111]
	v_mfma_f32_16x16x32_bf16 v[100:103], v[156:159], v[192:195], v[100:103]
	v_mfma_f32_16x16x32_bf16 v[100:103], v[160:163], v[212:215], v[100:103]
	s_barrier
	s_setprio 0
	s_add_u32 s16, s14, 0xfff80080
	s_addc_u32 s17, s15, -1
	s_cmp_eq_u32 s38, 28
	s_cselect_b32 s19, s3, s17
	s_cselect_b32 s18, s13, s16
	s_cselect_b32 s17, s5, s37
	s_cselect_b32 s16, s35, s36
	s_add_i32 s42, 0, 0x14000
	v_add_u32_e32 v142, s42, v144
	s_add_i32 s39, s39, s25
	ds_read_b128 v[216:219], v142
	ds_read_b128 v[220:223], v142 offset:1024
	ds_read_b128 v[224:227], v142 offset:2048
	ds_read_b128 v[228:231], v142 offset:3072
	s_add_u32 s98, s16, 0x80
	s_addc_u32 s99, s17, 0
	s_mov_b32 m0, s39
	s_nop 0
	global_load_lds_dwordx4 v2, s[16:17]
	s_add_i32 m0, s39, 0x2000
	s_nop 0
	global_load_lds_dwordx4 v0, s[16:17]
	s_mov_b32 m0, s26
	s_add_u32 s100, s18, 0x80
	s_addc_u32 s101, s19, 0
	s_waitcnt lgkmcnt(2)
	s_setprio 1
	s_barrier
; #define PG8_WAIT_V(n) asm volatile("s_waitcnt vmcnt(" #n ")" ::: "memory")
; #define PG8_WAIT_L(n) asm volatile("s_waitcnt lgkmcnt(" #n ")" ::: "memory")
; #define PG8_BAR __builtin_amdgcn_s_barrier()
; #define PG8_SCHED __builtin_amdgcn_sched_barrier(0)
; template <class Epi, class AddrA, class AddrB>
; __device__ __forceinline__ void gemm_phase(const Sched S, const int lda, const int ldb, const int K, const AddrA addrA,
;                                            const AddrB addrB, const Epi E) {
;     ...
;       PG8_LDB(B1, 0, 1); PG8_STAGE(PG8_SB(0, 0), b2, voffB);
;       PG8_BAR; PG8_WAIT_L(0); PG8_MMA(0, 1, At, B1); PG8_BAR;
;       PG8_LDA(At, 0, 1); PG8_STAGE(PG8_SA(0, 0), a2, voffA);
;       PG8_BAR; PG8_WAIT_L(0); PG8_MMA(1, 0, At, B0); PG8_BAR; PG8_SCHED;
;       PG8_STAGE(PG8_SB(0, 1), b2 + hstepB, voffB);
;       PG8_WAIT_V(6); PG8_BAR; PG8_MMA(1, 1, At, B1); PG8_BAR;
;       PG8_LDB(B0, 1, 0); PG8_SCHED; PG8_LDA(At, 1, 0); PG8_STAGE(PG8_SA(0, 1), a2 + hstepA, voffA);
;       PG8_WAIT_L(8); PG8_BAR; PG8_WAIT_L(0); PG8_MMA(0, 0, At, B0); PG8_BAR; PG8_SCHED;
;       PG8_LDB(B1, 1, 1); PG8_STAGE(PG8_SB(1, 0), b3, voffB);
;       PG8_BAR; PG8_WAIT_L(0); PG8_MMA(0, 1, At, B1); PG8_BAR;
	v_mfma_f32_16x16x32_bf16 v[96:99], v[216:219], v[168:171], v[96:99]
	v_mfma_f32_16x16x32_bf16 v[96:99], v[220:223], v[172:175], v[96:99]
	s_waitcnt lgkmcnt(0)
	v_mfma_f32_16x16x32_bf16 v[88:91], v[216:219], v[176:179], v[88:91]
	v_mfma_f32_16x16x32_bf16 v[88:91], v[220:223], v[180:183], v[88:91]
	v_mfma_f32_16x16x32_bf16 v[80:83], v[216:219], v[184:187], v[80:83]
	v_mfma_f32_16x16x32_bf16 v[80:83], v[220:223], v[188:191], v[80:83]
	v_mfma_f32_16x16x32_bf16 v[72:75], v[216:219], v[192:195], v[72:75]
	v_mfma_f32_16x16x32_bf16 v[72:75], v[220:223], v[212:215], v[72:75]
	v_mfma_f32_16x16x32_bf16 v[92:95], v[224:227], v[168:171], v[92:95]
	v_mfma_f32_16x16x32_bf16 v[92:95], v[228:231], v[172:175], v[92:95]
	v_mfma_f32_16x16x32_bf16 v[84:87], v[224:227], v[176:179], v[84:87]
	v_mfma_f32_16x16x32_bf16 v[84:87], v[228:231], v[180:183], v[84:87]
	v_mfma_f32_16x16x32_bf16 v[76:79], v[224:227], v[184:187], v[76:79]
	v_mfma_f32_16x16x32_bf16 v[76:79], v[228:231], v[188:191], v[76:79]
	v_mfma_f32_16x16x32_bf16 v[68:71], v[224:227], v[192:195], v[68:71]
	v_mfma_f32_16x16x32_bf16 v[68:71], v[228:231], v[212:215], v[68:71]
	s_barrier
	s_setprio 0
	ds_read_b128 v[168:171], v146 offset:16384
	ds_read_b128 v[172:175], v146 offset:17408
	ds_read_b128 v[176:179], v146 offset:18432
	ds_read_b128 v[180:183], v146 offset:19456
	ds_read_b128 v[184:187], v146 offset:20480
	ds_read_b128 v[188:191], v146 offset:21504
	ds_read_b128 v[192:195], v146 offset:22528
	ds_read_b128 v[212:215], v146 offset:23552
	global_load_lds_dwordx4 v134, s[18:19]
	s_mov_b32 m0, s27
	s_nop 0
	global_load_lds_dwordx4 v132, s[18:19]
	s_waitcnt lgkmcnt(6)
	s_setprio 1
	s_barrier
	v_mfma_f32_16x16x32_bf16 v[64:67], v[148:151], v[168:171], v[64:67]
	v_mfma_f32_16x16x32_bf16 v[64:67], v[152:155], v[172:175], v[64:67]
	s_waitcnt lgkmcnt(0)
	v_mfma_f32_16x16x32_bf16 v[56:59], v[148:151], v[176:179], v[56:59]
	v_mfma_f32_16x16x32_bf16 v[56:59], v[152:155], v[180:183], v[56:59]
	v_mfma_f32_16x16x32_bf16 v[48:51], v[148:151], v[184:187], v[48:51]
	v_mfma_f32_16x16x32_bf16 v[48:51], v[152:155], v[188:191], v[48:51]
	v_mfma_f32_16x16x32_bf16 v[40:43], v[148:151], v[192:195], v[40:43]
	v_mfma_f32_16x16x32_bf16 v[40:43], v[152:155], v[212:215], v[40:43]
	v_mfma_f32_16x16x32_bf16 v[60:63], v[156:159], v[168:171], v[60:63]
	v_mfma_f32_16x16x32_bf16 v[60:63], v[160:163], v[172:175], v[60:63]
	v_mfma_f32_16x16x32_bf16 v[52:55], v[156:159], v[176:179], v[52:55]
	v_mfma_f32_16x16x32_bf16 v[52:55], v[160:163], v[180:183], v[52:55]
	v_mfma_f32_16x16x32_bf16 v[44:47], v[156:159], v[184:187], v[44:47]
	v_mfma_f32_16x16x32_bf16 v[44:47], v[160:163], v[188:191], v[44:47]
	v_mfma_f32_16x16x32_bf16 v[36:39], v[156:159], v[192:195], v[36:39]
	v_mfma_f32_16x16x32_bf16 v[36:39], v[160:163], v[212:215], v[36:39]
	s_barrier
	s_setprio 0
	s_add_u32 s40, s16, 0x80000
	s_addc_u32 s41, s17, 0
	s_add_i32 s39, s42, s25
	s_mov_b32 m0, s39
	s_nop 0
	global_load_lds_dwordx4 v2, s[40:41]
	s_add_i32 m0, s39, 0x2000
	s_nop 0
	global_load_lds_dwordx4 v0, s[40:41]
	s_add_i32 s39, 0, 0x18000
	v_add_u32_e32 v147, s39, v144
	s_waitcnt vmcnt(6)
	s_setprio 1
	s_barrier
	v_mfma_f32_16x16x32_bf16 v[32:35], v[216:219], v[168:171], v[32:35]
	v_mfma_f32_16x16x32_bf16 v[32:35], v[220:223], v[172:175], v[32:35]
	v_mfma_f32_16x16x32_bf16 v[24:27], v[216:219], v[176:179], v[24:27]
	v_mfma_f32_16x16x32_bf16 v[24:27], v[220:223], v[180:183], v[24:27]
	v_mfma_f32_16x16x32_bf16 v[16:19], v[216:219], v[184:187], v[16:19]
	v_mfma_f32_16x16x32_bf16 v[16:19], v[220:223], v[188:191], v[16:19]
	v_mfma_f32_16x16x32_bf16 v[8:11], v[216:219], v[192:195], v[8:11]
	v_mfma_f32_16x16x32_bf16 v[8:11], v[220:223], v[212:215], v[8:11]
	v_mfma_f32_16x16x32_bf16 v[28:31], v[224:227], v[168:171], v[28:31]
	v_mfma_f32_16x16x32_bf16 v[28:31], v[228:231], v[172:175], v[28:31]
	v_mfma_f32_16x16x32_bf16 v[20:23], v[224:227], v[176:179], v[20:23]
	v_mfma_f32_16x16x32_bf16 v[20:23], v[228:231], v[180:183], v[20:23]
	v_mfma_f32_16x16x32_bf16 v[12:15], v[224:227], v[184:187], v[12:15]
	v_mfma_f32_16x16x32_bf16 v[12:15], v[228:231], v[188:191], v[12:15]
	v_mfma_f32_16x16x32_bf16 v[4:7], v[224:227], v[192:195], v[4:7]
	v_mfma_f32_16x16x32_bf16 v[4:7], v[228:231], v[212:215], v[4:7]
	s_barrier
	s_setprio 0
	ds_read_b128 v[148:151], v147
	ds_read_b128 v[152:155], v147 offset:1024
	ds_read_b128 v[156:159], v147 offset:2048
	ds_read_b128 v[160:163], v147 offset:3072
	s_add_u32 s18, s18, 0x80000
	s_addc_u32 s19, s19, 0
	s_mov_b32 m0, s28
	ds_read_b128 v[168:171], v146 offset:32768
	ds_read_b128 v[172:175], v146 offset:33792
	ds_read_b128 v[176:179], v146 offset:34816
	ds_read_b128 v[180:183], v146 offset:35840
	ds_read_b128 v[184:187], v146 offset:36864
	ds_read_b128 v[188:191], v146 offset:37888
	ds_read_b128 v[192:195], v146 offset:38912
	ds_read_b128 v[212:215], v146 offset:39936
	global_load_lds_dwordx4 v134, s[18:19]
	s_mov_b32 m0, s29
	s_nop 0
	global_load_lds_dwordx4 v132, s[18:19]
	s_waitcnt lgkmcnt(6)
	s_setprio 1
	s_barrier
	v_mfma_f32_16x16x32_bf16 v[128:131], v[148:151], v[168:171], v[128:131]
	v_mfma_f32_16x16x32_bf16 v[128:131], v[152:155], v[172:175], v[128:131]
	s_waitcnt lgkmcnt(0)
	v_mfma_f32_16x16x32_bf16 v[120:123], v[148:151], v[176:179], v[120:123]
	v_mfma_f32_16x16x32_bf16 v[120:123], v[152:155], v[180:183], v[120:123]
	v_mfma_f32_16x16x32_bf16 v[112:115], v[148:151], v[184:187], v[112:115]
	v_mfma_f32_16x16x32_bf16 v[112:115], v[152:155], v[188:191], v[112:115]
	v_mfma_f32_16x16x32_bf16 v[104:107], v[148:151], v[192:195], v[104:107]
	v_mfma_f32_16x16x32_bf16 v[104:107], v[152:155], v[212:215], v[104:107]
	v_mfma_f32_16x16x32_bf16 v[124:127], v[156:159], v[168:171], v[124:127]
	v_mfma_f32_16x16x32_bf16 v[124:127], v[160:163], v[172:175], v[124:127]
	v_mfma_f32_16x16x32_bf16 v[116:119], v[156:159], v[176:179], v[116:119]
	v_mfma_f32_16x16x32_bf16 v[116:119], v[160:163], v[180:183], v[116:119]
	v_mfma_f32_16x16x32_bf16 v[108:111], v[156:159], v[184:187], v[108:111]
	v_mfma_f32_16x16x32_bf16 v[108:111], v[160:163], v[188:191], v[108:111]
	v_mfma_f32_16x16x32_bf16 v[100:103], v[156:159], v[192:195], v[100:103]
	v_mfma_f32_16x16x32_bf16 v[100:103], v[160:163], v[212:215], v[100:103]
	s_barrier
; #define PG8_WAIT_V(n) asm volatile("s_waitcnt vmcnt(" #n ")" ::: "memory")
; #define PG8_WAIT_L(n) asm volatile("s_waitcnt lgkmcnt(" #n ")" ::: "memory")
; #define PG8_BAR __builtin_amdgcn_s_barrier()
; #define PG8_SCHED __builtin_amdgcn_sched_barrier(0)
; template <class Epi, class AddrA, class AddrB>
; __device__ __forceinline__ void gemm_phase(const Sched S, const int lda, const int ldb, const int K, const AddrA addrA,
;                                            const AddrB addrB, const Epi E) {
;     ...
;       PG8_BAR; PG8_WAIT_L(0); PG8_MMA(0, 1, At, B1); PG8_BAR;
;       PG8_LDA(At, 1, 1); PG8_STAGE(PG8_SA(1, 0), a3, voffA);
;       PG8_BAR; PG8_WAIT_L(0); PG8_MMA(1, 0, At, B0); PG8_BAR; PG8_SCHED;
;       PG8_STAGE(PG8_SB(1, 1), b3 + hstepB, voffB);
;       PG8_WAIT_V(6); PG8_BAR; PG8_MMA(1, 1, At, B1); PG8_BAR;
	s_setprio 0
	s_add_i32 s18, 0, 0x1c000
	s_add_i32 s19, s39, s25
	v_add_u32_e32 v147, s18, v144
	s_mov_b32 m0, s19
	ds_read_b128 v[216:219], v147
	ds_read_b128 v[220:223], v147 offset:1024
	ds_read_b128 v[224:227], v147 offset:2048
	ds_read_b128 v[228:231], v147 offset:3072
	global_load_lds_dwordx4 v2, s[98:99]
	s_add_i32 m0, s19, 0x2000
	s_nop 0
	global_load_lds_dwordx4 v0, s[98:99]
	s_mov_b32 m0, s30
	s_waitcnt lgkmcnt(2)
	s_setprio 1
	s_barrier
	v_mfma_f32_16x16x32_bf16 v[96:99], v[216:219], v[168:171], v[96:99]
	v_mfma_f32_16x16x32_bf16 v[96:99], v[220:223], v[172:175], v[96:99]
	s_waitcnt lgkmcnt(0)
	v_mfma_f32_16x16x32_bf16 v[88:91], v[216:219], v[176:179], v[88:91]
	v_mfma_f32_16x16x32_bf16 v[88:91], v[220:223], v[180:183], v[88:91]
	v_mfma_f32_16x16x32_bf16 v[80:83], v[216:219], v[184:187], v[80:83]
	v_mfma_f32_16x16x32_bf16 v[80:83], v[220:223], v[188:191], v[80:83]
	v_mfma_f32_16x16x32_bf16 v[72:75], v[216:219], v[192:195], v[72:75]
	v_mfma_f32_16x16x32_bf16 v[72:75], v[220:223], v[212:215], v[72:75]
	v_mfma_f32_16x16x32_bf16 v[92:95], v[224:227], v[168:171], v[92:95]
	v_mfma_f32_16x16x32_bf16 v[92:95], v[228:231], v[172:175], v[92:95]
	v_mfma_f32_16x16x32_bf16 v[84:87], v[224:227], v[176:179], v[84:87]
	v_mfma_f32_16x16x32_bf16 v[84:87], v[228:231], v[180:183], v[84:87]
	v_mfma_f32_16x16x32_bf16 v[76:79], v[224:227], v[184:187], v[76:79]
	v_mfma_f32_16x16x32_bf16 v[76:79], v[228:231], v[188:191], v[76:79]
	v_mfma_f32_16x16x32_bf16 v[68:71], v[224:227], v[192:195], v[68:71]
	v_mfma_f32_16x16x32_bf16 v[68:71], v[228:231], v[212:215], v[68:71]
	s_barrier
	s_setprio 0
	ds_read_b128 v[168:171], v146 offset:49152
	ds_read_b128 v[172:175], v146 offset:50176
	ds_read_b128 v[176:179], v146 offset:51200
	ds_read_b128 v[180:183], v146 offset:52224
	ds_read_b128 v[184:187], v146 offset:53248
	ds_read_b128 v[188:191], v146 offset:54272
	ds_read_b128 v[192:195], v146 offset:55296
	ds_read_b128 v[212:215], v146 offset:56320
	global_load_lds_dwordx4 v134, s[100:101]
	s_mov_b32 m0, s31
	s_nop 0
	global_load_lds_dwordx4 v132, s[100:101]
	s_waitcnt lgkmcnt(6)
	s_setprio 1
	s_barrier
	v_mfma_f32_16x16x32_bf16 v[64:67], v[148:151], v[168:171], v[64:67]
	v_mfma_f32_16x16x32_bf16 v[64:67], v[152:155], v[172:175], v[64:67]
	s_waitcnt lgkmcnt(0)
	v_mfma_f32_16x16x32_bf16 v[56:59], v[148:151], v[176:179], v[56:59]
	v_mfma_f32_16x16x32_bf16 v[56:59], v[152:155], v[180:183], v[56:59]
	v_mfma_f32_16x16x32_bf16 v[48:51], v[148:151], v[184:187], v[48:51]
	v_mfma_f32_16x16x32_bf16 v[48:51], v[152:155], v[188:191], v[48:51]
	v_mfma_f32_16x16x32_bf16 v[40:43], v[148:151], v[192:195], v[40:43]
	v_mfma_f32_16x16x32_bf16 v[40:43], v[152:155], v[212:215], v[40:43]
	v_mfma_f32_16x16x32_bf16 v[60:63], v[156:159], v[168:171], v[60:63]
	v_mfma_f32_16x16x32_bf16 v[60:63], v[160:163], v[172:175], v[60:63]
	v_mfma_f32_16x16x32_bf16 v[52:55], v[156:159], v[176:179], v[52:55]
	v_mfma_f32_16x16x32_bf16 v[52:55], v[160:163], v[180:183], v[52:55]
	v_mfma_f32_16x16x32_bf16 v[44:47], v[156:159], v[184:187], v[44:47]
	v_mfma_f32_16x16x32_bf16 v[44:47], v[160:163], v[188:191], v[44:47]
	v_mfma_f32_16x16x32_bf16 v[36:39], v[156:159], v[192:195], v[36:39]
	v_mfma_f32_16x16x32_bf16 v[36:39], v[160:163], v[212:215], v[36:39]
	s_barrier
	s_setprio 0
	s_add_u32 s16, s16, 0x80080
	s_addc_u32 s17, s17, 0
	s_add_i32 s18, s18, s25
	s_mov_b32 m0, s18
	s_nop 0
	global_load_lds_dwordx4 v2, s[16:17]
	s_add_i32 m0, s18, 0x2000
	s_nop 0
	global_load_lds_dwordx4 v0, s[16:17]
	s_add_i32 s38, s38, 2
	s_add_u32 s36, s36, 0x100
	s_addc_u32 s37, s37, 0
	s_add_u32 s14, s14, 0x100
	s_addc_u32 s15, s15, 0
	s_waitcnt vmcnt(6)
	s_setprio 1
	s_barrier
	v_mfma_f32_16x16x32_bf16 v[32:35], v[216:219], v[168:171], v[32:35]
	v_mfma_f32_16x16x32_bf16 v[32:35], v[220:223], v[172:175], v[32:35]
	v_mfma_f32_16x16x32_bf16 v[24:27], v[216:219], v[176:179], v[24:27]
	v_mfma_f32_16x16x32_bf16 v[24:27], v[220:223], v[180:183], v[24:27]
	v_mfma_f32_16x16x32_bf16 v[16:19], v[216:219], v[184:187], v[16:19]
	v_mfma_f32_16x16x32_bf16 v[16:19], v[220:223], v[188:191], v[16:19]
	v_mfma_f32_16x16x32_bf16 v[8:11], v[216:219], v[192:195], v[8:11]
	v_mfma_f32_16x16x32_bf16 v[8:11], v[220:223], v[212:215], v[8:11]
	v_mfma_f32_16x16x32_bf16 v[28:31], v[224:227], v[168:171], v[28:31]
	v_mfma_f32_16x16x32_bf16 v[28:31], v[228:231], v[172:175], v[28:31]
	v_mfma_f32_16x16x32_bf16 v[20:23], v[224:227], v[176:179], v[20:23]
	v_mfma_f32_16x16x32_bf16 v[20:23], v[228:231], v[180:183], v[20:23]
	v_mfma_f32_16x16x32_bf16 v[12:15], v[224:227], v[184:187], v[12:15]
	v_mfma_f32_16x16x32_bf16 v[12:15], v[228:231], v[188:191], v[12:15]
	v_mfma_f32_16x16x32_bf16 v[4:7], v[224:227], v[192:195], v[4:7]
	v_mfma_f32_16x16x32_bf16 v[4:7], v[228:231], v[212:215], v[4:7]
	s_barrier
	s_setprio 0
	s_cmp_gt_u32 s38, 29
	s_cbranch_scc0 .LBB0_619
;   __device__ __forceinline__ void operator()(EPI_ARGS) const {
;     const size_t row0 = (size_t)u.pm * 256 + wr * 64 + fr;
;     const int col0 = u.pn * 256 + wc * 32 + 8 * fq;
; #pragma unroll
;     for (int ai = 0; ai < 2; ++ai)
; #pragma unroll
;       for (int bj = 0; bj < 2; ++bj) {
;         f32x4 x0[4], x1[4];
; #pragma unroll
;         for (int m = 0; m < 4; ++m) {
;           const size_t o = (row0 + ai * HALF + m * 16) * DM + col0 + bj * HALF;
;           x0[m] = *(const f32x4*)(xres + o);
;           x1[m] = *(const f32x4*)(xres + o + 4);
;         }
;         __builtin_amdgcn_sched_barrier(0);
; #pragma unroll
;         for (int m = 0; m < 4; ++m) {
;           const size_t o = (row0 + ai * HALF + m * 16) * DM + col0 + bj * HALF;
;           *(f32x4*)(hbuf + o) = acc[ai][bj][m][0] + x0[m] * ALPHA;
;           *(f32x4*)(hbuf + o + 4) = acc[ai][bj][m][1] + x1[m] * ALPHA;
;         }
	s_ashr_i32 s13, s12, 31
	v_lshl_or_b32 v142, s34, 8, v145
	v_ashrrev_i32_e32 v143, 31, v142
	s_lshl_b64 s[12:13], s[12:13], 21
	v_lshlrev_b64 v[184:185], 2, v[142:143]
	v_lshl_add_u64 v[188:189], s[12:13], 0, v[136:137]
	v_lshl_add_u64 v[186:187], s[0:1], 0, v[184:185]
	v_or_b32_e32 v190, 0x20000, v188
	v_mov_b32_e32 v191, v189
	v_or_b32_e32 v192, 0x40000, v188
	v_mov_b32_e32 v193, v189
	v_or_b32_e32 v194, 0x60000, v188
	v_mov_b32_e32 v195, v189
	v_lshl_add_u64 v[142:143], v[186:187], 0, v[188:189]
	v_lshl_add_u64 v[160:161], v[186:187], 0, v[190:191]
	v_lshl_add_u64 v[172:173], v[186:187], 0, v[192:193]
	v_lshl_add_u64 v[180:181], v[186:187], 0, v[194:195]
	flat_load_dwordx4 v[148:151], v[142:143]
	flat_load_dwordx4 v[152:155], v[142:143] offset:16
	flat_load_dwordx4 v[156:159], v[160:161]
	s_nop 0
	flat_load_dwordx4 v[160:163], v[160:161] offset:16
	s_nop 0
	flat_load_dwordx4 v[168:171], v[172:173]
	s_nop 0
	flat_load_dwordx4 v[172:175], v[172:173] offset:16
	s_nop 0
	flat_load_dwordx4 v[176:179], v[180:181]
	s_nop 0
	flat_load_dwordx4 v[180:183], v[180:181] offset:16
	v_lshl_add_u64 v[184:185], s[48:49], 0, v[184:185]
	s_mov_b32 s14, 0x3fb504f3
	s_waitcnt vmcnt(0) lgkmcnt(0)
	v_pk_fma_f32 v[148:149], v[148:149], s[14:15], v[128:129] op_sel_hi:[1,0,1]
	v_lshl_add_u64 v[128:129], v[184:185], 0, v[188:189]
	v_pk_fma_f32 v[126:127], v[154:155], s[14:15], v[126:127] op_sel_hi:[1,0,1]
	v_pk_fma_f32 v[124:125], v[152:153], s[14:15], v[124:125] op_sel_hi:[1,0,1]
	global_store_dwordx4 v[128:129], v[124:127], off offset:16
	v_pk_fma_f32 v[118:119], v[162:163], s[14:15], v[118:119] op_sel_hi:[1,0,1]
	v_pk_fma_f32 v[116:117], v[160:161], s[14:15], v[116:117] op_sel_hi:[1,0,1]
	v_lshl_add_u64 v[124:125], v[184:185], 0, v[190:191]
	v_pk_fma_f32 v[122:123], v[158:159], s[14:15], v[122:123] op_sel_hi:[1,0,1]
	v_pk_fma_f32 v[120:121], v[156:157], s[14:15], v[120:121] op_sel_hi:[1,0,1]
	global_store_dwordx4 v[124:125], v[116:119], off offset:16
	v_pk_fma_f32 v[110:111], v[174:175], s[14:15], v[110:111] op_sel_hi:[1,0,1]
	v_pk_fma_f32 v[108:109], v[172:173], s[14:15], v[108:109] op_sel_hi:[1,0,1]
	v_lshl_add_u64 v[116:117], v[184:185], 0, v[192:193]
	s_mov_b64 s[12:13], 0x200
	v_pk_fma_f32 v[150:151], v[150:151], s[14:15], v[130:131] op_sel_hi:[1,0,1]
	global_store_dwordx4 v[124:125], v[120:123], off
	v_pk_fma_f32 v[114:115], v[170:171], s[14:15], v[114:115] op_sel_hi:[1,0,1]
	v_pk_fma_f32 v[112:113], v[168:169], s[14:15], v[112:113] op_sel_hi:[1,0,1]
	global_store_dwordx4 v[116:117], v[108:111], off offset:16
	v_pk_fma_f32 v[106:107], v[178:179], s[14:15], v[106:107] op_sel_hi:[1,0,1]
	v_pk_fma_f32 v[104:105], v[176:177], s[14:15], v[104:105] op_sel_hi:[1,0,1]
	v_lshl_add_u64 v[108:109], v[184:185], 0, v[194:195]
	v_pk_fma_f32 v[102:103], v[182:183], s[14:15], v[102:103] op_sel_hi:[1,0,1]
	v_pk_fma_f32 v[100:101], v[180:181], s[14:15], v[100:101] op_sel_hi:[1,0,1]
	v_lshl_add_u64 v[124:125], v[186:187], 0, s[12:13]
	global_store_dwordx4 v[128:129], v[148:151], off
	global_store_dwordx4 v[116:117], v[112:115], off
	global_store_dwordx4 v[108:109], v[104:107], off
	global_store_dwordx4 v[108:109], v[100:103], off offset:16
	v_lshl_add_u64 v[112:113], v[124:125], 0, v[190:191]
	v_lshl_add_u64 v[120:121], v[124:125], 0, v[192:193]
	v_lshl_add_u64 v[130:131], v[124:125], 0, v[194:195]
	flat_load_dwordx4 v[100:103], v[142:143] offset:512
	flat_load_dwordx4 v[104:107], v[142:143] offset:528
	flat_load_dwordx4 v[108:111], v[112:113]
	s_nop 0
	flat_load_dwordx4 v[112:115], v[112:113] offset:16
	s_nop 0
	flat_load_dwordx4 v[116:119], v[120:121]
	s_nop 0
	flat_load_dwordx4 v[120:123], v[120:121] offset:16
	s_nop 0
	flat_load_dwordx4 v[124:127], v[130:131]
	flat_load_dwordx4 v[148:151], v[130:131] offset:16
	s_mov_b32 s3, 0x100000
	s_waitcnt vmcnt(0) lgkmcnt(0)
	v_pk_fma_f32 v[96:97], v[100:101], s[14:15], v[96:97] op_sel_hi:[1,0,1]
	v_add_co_u32_e32 v100, vcc, s3, v142
	s_mov_b32 s5, 0x120000
	s_nop 0
	v_addc_co_u32_e32 v101, vcc, 0, v143, vcc
	v_pk_fma_f32 v[98:99], v[102:103], s[14:15], v[98:99] op_sel_hi:[1,0,1]
	v_add_co_u32_e32 v102, vcc, s5, v142
	v_lshl_add_u64 v[130:131], v[184:185], 0, s[12:13]
	v_pk_fma_f32 v[94:95], v[106:107], s[14:15], v[94:95] op_sel_hi:[1,0,1]
	v_pk_fma_f32 v[92:93], v[104:105], s[14:15], v[92:93] op_sel_hi:[1,0,1]
	v_addc_co_u32_e32 v103, vcc, 0, v143, vcc
	s_mov_b32 s12, 0x140000
	global_store_dwordx4 v[128:129], v[92:95], off offset:528
	v_pk_fma_f32 v[86:87], v[114:115], s[14:15], v[86:87] op_sel_hi:[1,0,1]
	v_pk_fma_f32 v[84:85], v[112:113], s[14:15], v[84:85] op_sel_hi:[1,0,1]
	v_lshl_add_u64 v[92:93], v[130:131], 0, v[190:191]
	v_add_co_u32_e32 v104, vcc, s12, v142
	global_store_dwordx4 v[92:93], v[84:87], off offset:16
	v_pk_fma_f32 v[78:79], v[122:123], s[14:15], v[78:79] op_sel_hi:[1,0,1]
	v_pk_fma_f32 v[76:77], v[120:121], s[14:15], v[76:77] op_sel_hi:[1,0,1]
	v_lshl_add_u64 v[84:85], v[130:131], 0, v[192:193]
	v_addc_co_u32_e32 v105, vcc, 0, v143, vcc
	s_mov_b32 s13, 0x160000
	v_pk_fma_f32 v[90:91], v[110:111], s[14:15], v[90:91] op_sel_hi:[1,0,1]
	v_pk_fma_f32 v[88:89], v[108:109], s[14:15], v[88:89] op_sel_hi:[1,0,1]
	v_pk_fma_f32 v[82:83], v[118:119], s[14:15], v[82:83] op_sel_hi:[1,0,1]
	v_pk_fma_f32 v[80:81], v[116:117], s[14:15], v[80:81] op_sel_hi:[1,0,1]
	global_store_dwordx4 v[84:85], v[76:79], off offset:16
	v_pk_fma_f32 v[74:75], v[126:127], s[14:15], v[74:75] op_sel_hi:[1,0,1]
	v_pk_fma_f32 v[72:73], v[124:125], s[14:15], v[72:73] op_sel_hi:[1,0,1]
	v_lshl_add_u64 v[76:77], v[130:131], 0, v[194:195]
	v_pk_fma_f32 v[70:71], v[150:151], s[14:15], v[70:71] op_sel_hi:[1,0,1]
	v_pk_fma_f32 v[68:69], v[148:149], s[14:15], v[68:69] op_sel_hi:[1,0,1]
	s_mov_b64 s[16:17], 0x100000
	s_mov_b64 s[18:19], 0x120000
	s_mov_b64 s[34:35], 0x140000
	s_mov_b64 s[36:37], 0x160000
	v_add_co_u32_e32 v106, vcc, s13, v142
	global_store_dwordx4 v[128:129], v[96:99], off offset:512
	global_store_dwordx4 v[92:93], v[88:91], off
	global_store_dwordx4 v[84:85], v[80:83], off
	global_store_dwordx4 v[76:77], v[72:75], off
	global_store_dwordx4 v[76:77], v[68:71], off offset:16
	v_lshl_add_u64 v[80:81], v[142:143], 0, s[18:19]
	v_lshl_add_u64 v[72:73], v[142:143], 0, s[16:17]
	v_lshl_add_u64 v[88:89], v[142:143], 0, s[34:35]
	v_lshl_add_u64 v[96:97], v[142:143], 0, s[36:37]
	v_addc_co_u32_e32 v107, vcc, 0, v143, vcc
	flat_load_dwordx4 v[68:71], v[100:101]
	s_nop 0
	flat_load_dwordx4 v[72:75], v[72:73] offset:16
	s_nop 0
	flat_load_dwordx4 v[76:79], v[102:103]
	s_nop 0
	flat_load_dwordx4 v[80:83], v[80:81] offset:16
	s_nop 0
	flat_load_dwordx4 v[84:87], v[104:105]
	s_nop 0
	flat_load_dwordx4 v[88:91], v[88:89] offset:16
	s_nop 0
	flat_load_dwordx4 v[92:95], v[106:107]
	s_nop 0
	flat_load_dwordx4 v[96:99], v[96:97] offset:16
	s_waitcnt vmcnt(0) lgkmcnt(0)
; #define PG8_WAIT_V(n) asm volatile("s_waitcnt vmcnt(" #n ")" ::: "memory")
; #define PG8_BAR __builtin_amdgcn_s_barrier()
; template <class Epi, class AddrA, class AddrB>
; __device__ __forceinline__ void gemm_phase(const Sched S, const int lda, const int ldb, const int K, const AddrA addrA,
;                                            const AddrB addrB, const Epi E) {
;     ...
;     if (!has_next) break;
;     ...
;   PG8_WAIT_V(0);
;   if (wr == 0) PG8_BAR;
;   PG8_BAR;
;   __device__ __forceinline__ void operator()(EPI_ARGS) const {
;     ...
;         for (int m = 0; m < 4; ++m) {
;           const size_t o = (row0 + ai * HALF + m * 16) * DM + col0 + bj * HALF;
;           *(f32x4*)(hbuf + o) = acc[ai][bj][m][0] + x0[m] * ALPHA;
;           *(f32x4*)(hbuf + o + 4) = acc[ai][bj][m][1] + x1[m] * ALPHA;
;         }
	v_pk_fma_f32 v[66:67], v[70:71], s[14:15], v[66:67] op_sel_hi:[1,0,1]
	v_add_co_u32_e32 v70, vcc, s3, v128
	v_pk_fma_f32 v[64:65], v[68:69], s[14:15], v[64:65] op_sel_hi:[1,0,1]
	v_lshl_add_u64 v[68:69], v[128:129], 0, s[16:17]
	v_addc_co_u32_e32 v71, vcc, 0, v129, vcc
	v_pk_fma_f32 v[62:63], v[74:75], s[14:15], v[62:63] op_sel_hi:[1,0,1]
	v_pk_fma_f32 v[60:61], v[72:73], s[14:15], v[60:61] op_sel_hi:[1,0,1]
	global_store_dwordx4 v[68:69], v[60:63], off offset:16
	v_add_co_u32_e32 v68, vcc, s5, v128
	s_nop 0
	v_lshl_add_u64 v[60:61], v[128:129], 0, s[18:19]
	v_addc_co_u32_e32 v69, vcc, 0, v129, vcc
	v_add_co_u32_e32 v72, vcc, s12, v128
	v_pk_fma_f32 v[54:55], v[82:83], s[14:15], v[54:55] op_sel_hi:[1,0,1]
	v_pk_fma_f32 v[52:53], v[80:81], s[14:15], v[52:53] op_sel_hi:[1,0,1]
	v_addc_co_u32_e32 v73, vcc, 0, v129, vcc
	global_store_dwordx4 v[60:61], v[52:55], off offset:16
	v_pk_fma_f32 v[46:47], v[90:91], s[14:15], v[46:47] op_sel_hi:[1,0,1]
	v_pk_fma_f32 v[44:45], v[88:89], s[14:15], v[44:45] op_sel_hi:[1,0,1]
	v_lshl_add_u64 v[52:53], v[128:129], 0, s[34:35]
	v_add_co_u32_e32 v74, vcc, s13, v128
	v_pk_fma_f32 v[58:59], v[78:79], s[14:15], v[58:59] op_sel_hi:[1,0,1]
	v_pk_fma_f32 v[56:57], v[76:77], s[14:15], v[56:57] op_sel_hi:[1,0,1]
	v_pk_fma_f32 v[50:51], v[86:87], s[14:15], v[50:51] op_sel_hi:[1,0,1]
	v_pk_fma_f32 v[48:49], v[84:85], s[14:15], v[48:49] op_sel_hi:[1,0,1]
	global_store_dwordx4 v[52:53], v[44:47], off offset:16
	v_pk_fma_f32 v[42:43], v[94:95], s[14:15], v[42:43] op_sel_hi:[1,0,1]
	v_pk_fma_f32 v[40:41], v[92:93], s[14:15], v[40:41] op_sel_hi:[1,0,1]
	v_lshl_add_u64 v[44:45], v[128:129], 0, s[36:37]
	v_addc_co_u32_e32 v75, vcc, 0, v129, vcc
	v_pk_fma_f32 v[38:39], v[98:99], s[14:15], v[38:39] op_sel_hi:[1,0,1]
	v_pk_fma_f32 v[36:37], v[96:97], s[14:15], v[36:37] op_sel_hi:[1,0,1]
	s_mov_b64 s[12:13], 0x100200
	s_mov_b64 s[16:17], 0x120200
	s_mov_b64 s[18:19], 0x140200
	s_mov_b64 s[34:35], 0x160200
	global_store_dwordx4 v[70:71], v[64:67], off
	global_store_dwordx4 v[68:69], v[56:59], off
	global_store_dwordx4 v[72:73], v[48:51], off
	global_store_dwordx4 v[74:75], v[40:43], off
	global_store_dwordx4 v[44:45], v[36:39], off offset:16
	v_lshl_add_u64 v[44:45], v[142:143], 0, s[12:13]
	v_lshl_add_u64 v[48:49], v[142:143], 0, s[16:17]
	v_lshl_add_u64 v[60:61], v[142:143], 0, s[18:19]
	v_lshl_add_u64 v[64:65], v[142:143], 0, s[34:35]
	flat_load_dwordx4 v[36:39], v[100:101] offset:512
	flat_load_dwordx4 v[40:43], v[102:103] offset:512
	s_nop 0
	flat_load_dwordx4 v[44:47], v[44:45] offset:16
	s_nop 0
	flat_load_dwordx4 v[48:51], v[48:49] offset:16
	s_nop 0
	flat_load_dwordx4 v[52:55], v[104:105] offset:512
	flat_load_dwordx4 v[56:59], v[106:107] offset:512
	s_nop 0
	flat_load_dwordx4 v[60:63], v[60:61] offset:16
	s_nop 0
	flat_load_dwordx4 v[64:67], v[64:65] offset:16
	s_waitcnt vmcnt(0) lgkmcnt(0)
	v_pk_fma_f32 v[32:33], v[36:37], s[14:15], v[32:33] op_sel_hi:[1,0,1]
	v_lshl_add_u64 v[36:37], v[128:129], 0, s[12:13]
	v_pk_fma_f32 v[30:31], v[46:47], s[14:15], v[30:31] op_sel_hi:[1,0,1]
	v_pk_fma_f32 v[28:29], v[44:45], s[14:15], v[28:29] op_sel_hi:[1,0,1]
	global_store_dwordx4 v[36:37], v[28:31], off offset:16
	v_pk_fma_f32 v[22:23], v[50:51], s[14:15], v[22:23] op_sel_hi:[1,0,1]
	v_pk_fma_f32 v[20:21], v[48:49], s[14:15], v[20:21] op_sel_hi:[1,0,1]
	v_lshl_add_u64 v[28:29], v[128:129], 0, s[16:17]
	global_store_dwordx4 v[28:29], v[20:23], off offset:16
	v_pk_fma_f32 v[14:15], v[62:63], s[14:15], v[14:15] op_sel_hi:[1,0,1]
	v_pk_fma_f32 v[12:13], v[60:61], s[14:15], v[12:13] op_sel_hi:[1,0,1]
	v_lshl_add_u64 v[20:21], v[128:129], 0, s[18:19]
	v_pk_fma_f32 v[34:35], v[38:39], s[14:15], v[34:35] op_sel_hi:[1,0,1]
	v_pk_fma_f32 v[26:27], v[42:43], s[14:15], v[26:27] op_sel_hi:[1,0,1]
	v_pk_fma_f32 v[24:25], v[40:41], s[14:15], v[24:25] op_sel_hi:[1,0,1]
	v_pk_fma_f32 v[18:19], v[54:55], s[14:15], v[18:19] op_sel_hi:[1,0,1]
	v_pk_fma_f32 v[16:17], v[52:53], s[14:15], v[16:17] op_sel_hi:[1,0,1]
	global_store_dwordx4 v[20:21], v[12:15], off offset:16
	v_pk_fma_f32 v[10:11], v[58:59], s[14:15], v[10:11] op_sel_hi:[1,0,1]
	v_pk_fma_f32 v[8:9], v[56:57], s[14:15], v[8:9] op_sel_hi:[1,0,1]
	v_lshl_add_u64 v[12:13], v[128:129], 0, s[34:35]
	v_pk_fma_f32 v[6:7], v[66:67], s[14:15], v[6:7] op_sel_hi:[1,0,1]
	v_pk_fma_f32 v[4:5], v[64:65], s[14:15], v[4:5] op_sel_hi:[1,0,1]
	s_and_b64 vcc, exec, s[6:7]
	s_mov_b32 s34, s4
	s_mov_b32 s12, s2
	s_mov_b64 s[14:15], s[10:11]
	s_mov_b64 s[16:17], s[8:9]
	global_store_dwordx4 v[70:71], v[32:35], off offset:512
	global_store_dwordx4 v[68:69], v[24:27], off offset:512
	global_store_dwordx4 v[72:73], v[16:19], off offset:512
	global_store_dwordx4 v[74:75], v[8:11], off offset:512
	global_store_dwordx4 v[12:13], v[4:7], off offset:16
	s_cbranch_vccz .LBB0_616
	s_waitcnt vmcnt(0)
	s_cmpk_gt_u32 s20, 0xff
	s_cbranch_scc1 .LBB0_623
	s_barrier

; __global__ void __launch_bounds__(512) fwd_megakernel(Params p) {
;   cg::grid_group grid = cg::this_grid();
	.amdhsa_kernel _Z14fwd_megakernel6Params
		.amdhsa_group_segment_fixed_size 0
		.amdhsa_private_segment_fixed_size 0
		.amdhsa_kernarg_size 416
		.amdhsa_user_sgpr_count 2
		.amdhsa_user_sgpr_dispatch_ptr 0
		.amdhsa_user_sgpr_queue_ptr 0
		.amdhsa_user_sgpr_kernarg_segment_ptr 1
		.amdhsa_user_sgpr_dispatch_id 0
		.amdhsa_user_sgpr_kernarg_preload_length 0
		.amdhsa_user_sgpr_kernarg_preload_offset 0
		.amdhsa_user_sgpr_private_segment_size 0
		.amdhsa_uses_dynamic_stack 0
		.amdhsa_enable_private_segment 0
		.amdhsa_system_sgpr_workgroup_id_x 1
		.amdhsa_system_sgpr_workgroup_id_y 0
		.amdhsa_system_sgpr_workgroup_id_z 0
		.amdhsa_system_sgpr_workgroup_info 0
		.amdhsa_system_vgpr_workitem_id 2
		.amdhsa_next_free_vgpr 246
		.amdhsa_next_free_sgpr 102
		.amdhsa_accum_offset 248
		.amdhsa_reserve_vcc 1
		.amdhsa_float_round_mode_32 0
		.amdhsa_float_round_mode_16_64 0
		.amdhsa_float_denorm_mode_32 3
		.amdhsa_float_denorm_mode_16_64 3
		.amdhsa_dx10_clamp 1
		.amdhsa_ieee_mode 1
		.amdhsa_fp16_overflow 0
		.amdhsa_tg_split 0
		.amdhsa_exception_fp_ieee_invalid_op 0
		.amdhsa_exception_fp_denorm_src 0
		.amdhsa_exception_fp_ieee_div_zero 0
		.amdhsa_exception_fp_ieee_overflow 0
		.amdhsa_exception_fp_ieee_underflow 0
		.amdhsa_exception_fp_ieee_inexact 0
		.amdhsa_exception_int_div_zero 0
	.end_amdhsa_kernel

; __global__ void __launch_bounds__(512) fwd_megakernel(Params p) {
;   cg::grid_group grid = cg::this_grid();
amdhsa.kernels:
  - .agpr_count:     0
    .args:
      - .offset:         0
        .size:           160
        .value_kind:     by_value
      - .offset:         160
        .size:           4
        .value_kind:     hidden_block_count_x
      - .offset:         164
        .size:           4
        .value_kind:     hidden_block_count_y
      - .offset:         168
        .size:           4
        .value_kind:     hidden_block_count_z
      - .offset:         172
        .size:           2
        .value_kind:     hidden_group_size_x
      - .offset:         174
        .size:           2
        .value_kind:     hidden_group_size_y
      - .offset:         176
        .size:           2
        .value_kind:     hidden_group_size_z
      - .offset:         178
        .size:           2
        .value_kind:     hidden_remainder_x
      - .offset:         180
        .size:           2
        .value_kind:     hidden_remainder_y
      - .offset:         182
        .size:           2
        .value_kind:     hidden_remainder_z
      - .offset:         200
        .size:           8
        .value_kind:     hidden_global_offset_x
      - .offset:         208
        .size:           8
        .value_kind:     hidden_global_offset_y
      - .offset:         216
        .size:           8
        .value_kind:     hidden_global_offset_z
      - .offset:         224
        .size:           2
        .value_kind:     hidden_grid_dims
      - .offset:         248
        .size:           8
        .value_kind:     hidden_multigrid_sync_arg
      - .offset:         280
        .size:           4
        .value_kind:     hidden_dynamic_lds_size
    .group_segment_fixed_size: 0
    .kernarg_segment_align: 8
    .kernarg_segment_size: 416
    .language:       OpenCL C
    .language_version:
      - 2
      - 0
    .max_flat_workgroup_size: 512
    .name:           _Z14fwd_megakernel6Params
    .private_segment_fixed_size: 0
    .sgpr_count:     108
    .sgpr_spill_count: 156
    .symbol:         _Z14fwd_megakernel6Params.kd
    .uniform_work_group_size: 1
    .uses_dynamic_stack: false
    .vgpr_count:     246
    .vgpr_spill_count: 0
    .wavefront_size: 64
